# gdn prep forward substitution: L-row ds_read_b128 issued up to 12 reads ahead into a 19-quad register ring with counted lgkmcnt (was 2 reads then wait); plus scan wait changes
# speedup vs baseline: 1.0091x; 1.0091x over previous
; #define LAS __attribute__((address_space(3)))
; DI void gdn_prep_item(LAS unsigned char* lds, const Ctx& c, int l, int item) {
;     ...
;     if (tid < 256) {
;         const int col = tid; const LAS float* src = col < 128 ? vf + col : kf + (col - 128); const LAS float* mul = col < 128 ? betaL : (LAS float*)(lds + GP_BEK);
;         const LAS float* Lb = Lm; asm volatile("" : "+v"(Lb)); asm volatile("" : "+v"(mul));
;         float xr[64];
; #pragma unroll
;         for (int i = 0; i < 64; ++i) xr[i] = src[i * 129] * mul[i];
; #pragma unroll
;         for (int j = 0; j < 63; ++j) {
;             const float xj = xr[j];
; #pragma unroll
;             for (int i4 = (j + 1) / 4; i4 < 16; ++i4) { const f32x4 Lv = *(const LAS f32x4*)(Lb + j * 64 + 4 * i4);
; #pragma unroll
;                 for (int q = 0; q < 4; ++q) xr[4 * i4 + q] -= Lv[q] * xj; }
.LBB0_313:
	s_andn2_saveexec_b64 s[4:5], s[4:5]
	s_cbranch_execz .LBB0_209
	v_lshlrev_b32_e32 v0, 2, v26
	v_readlane_b32 s6, v254, 4
	v_mov_b32_e32 v4, s42
	s_nop 0
	v_add_u32_e32 v2, s6, v0
	s_add_i32 s6, 0, 0x1cd00
	v_add_u32_e32 v0, 0, v0
	v_mov_b32_e32 v3, s6
	s_movk_i32 s6, 0x80
	v_add_u32_e32 v0, 0x8600, v0
	v_cmp_gt_i32_e32 vcc, s6, v26
	v_readlane_b32 s6, v254, 5
	s_nop 0
	v_cndmask_b32_e32 v27, v3, v4, vcc
	v_cndmask_b32_e32 v38, v0, v2, vcc
	v_mov_b32_e32 v0, s6
	ds_read2_b32 v[2:3], v38 offset1:129
	ds_read2_b32 v[4:5], v27 offset1:1
	v_add_u32_e32 v6, 0x7c00, v38
	ds_read2_b32 v[14:15], v6 offset0:62 offset1:191
	ds_read2_b32 v[16:17], v27 offset0:62 offset1:63
	ds_read_b128 v[6:9], v0 offset:240
	ds_read2_b32 v[22:23], v27 offset0:6 offset1:7
	ds_read2_b32 v[24:25], v27 offset0:4 offset1:5
	ds_read2_b32 v[28:29], v27 offset0:2 offset1:3
	ds_read2_b32 v[18:19], v27 offset0:60 offset1:61
	ds_read_b128 v[10:13], v0 offset:224
	s_waitcnt lgkmcnt(8)
	v_mul_f32_e32 v2, v2, v4
	s_waitcnt lgkmcnt(5)
	v_mul_f32_e32 v4, v2, v9
	v_fma_f32 v39, v15, v17, -v4
	v_add_u32_e32 v4, 0x7800, v38
	ds_read2_b32 v[20:21], v4 offset0:60 offset1:189
	v_mul_f32_e32 v4, v2, v8
	v_fma_f32 v40, v14, v16, -v4
	v_mul_f32_e32 v4, v2, v7
	ds_read2_b32 v[8:9], v27 offset0:58 offset1:59
	s_waitcnt lgkmcnt(1)
	v_fma_f32 v41, v21, v19, -v4
	v_mul_f32_e32 v4, v2, v6
	v_fma_f32 v42, v20, v18, -v4
	v_add_u32_e32 v4, 0x7400, v38
	ds_read2_b32 v[6:7], v4 offset0:58 offset1:187
	v_mul_f32_e32 v4, v2, v13
	v_add_u32_e32 v13, 0x7000, v38
	ds_read2_b32 v[14:15], v13 offset0:56 offset1:185
	ds_read2_b32 v[16:17], v27 offset0:56 offset1:57
	s_movk_i32 s6, 0x7f
	s_waitcnt lgkmcnt(2)
	v_fma_f32 v43, v7, v9, -v4
	v_mul_f32_e32 v4, v2, v12
	v_fma_f32 v44, v6, v8, -v4
	v_mul_f32_e32 v4, v2, v11
	s_waitcnt lgkmcnt(0)
	v_fma_f32 v45, v15, v17, -v4
	v_mul_f32_e32 v4, v2, v10
	v_add_u32_e32 v10, 0x6c00, v38
	ds_read_b128 v[6:9], v0 offset:208
	ds_read2_b32 v[18:19], v10 offset0:54 offset1:183
	ds_read2_b32 v[20:21], v27 offset0:54 offset1:55
	v_fma_f32 v46, v14, v16, -v4
	ds_read2_b32 v[14:15], v27 offset0:52 offset1:53
	s_waitcnt lgkmcnt(3)
	v_mul_f32_e32 v4, v2, v9
	ds_read_b128 v[10:13], v0 offset:192
	s_waitcnt lgkmcnt(2)
	v_fma_f32 v47, v19, v21, -v4
	v_add_u32_e32 v4, 0x6800, v38
	ds_read2_b32 v[16:17], v4 offset0:52 offset1:181
	v_mul_f32_e32 v4, v2, v8
	v_fma_f32 v48, v18, v20, -v4
	v_mul_f32_e32 v4, v2, v7
	ds_read2_b32 v[8:9], v27 offset0:50 offset1:51
	s_waitcnt lgkmcnt(1)
	v_fma_f32 v49, v17, v15, -v4
	v_mul_f32_e32 v4, v2, v6
	v_fma_f32 v50, v16, v14, -v4
	v_add_u32_e32 v4, 0x6400, v38
	ds_read2_b32 v[6:7], v4 offset0:50 offset1:179
	v_mul_f32_e32 v4, v2, v13
	v_add_u32_e32 v13, 0x6000, v38
	ds_read2_b32 v[14:15], v13 offset0:48 offset1:177
	ds_read2_b32 v[16:17], v27 offset0:48 offset1:49
	v_cmp_lt_i32_e32 vcc, s6, v26
	s_waitcnt lgkmcnt(2)
	v_fma_f32 v51, v7, v9, -v4
	v_mul_f32_e32 v4, v2, v12
	v_fma_f32 v52, v6, v8, -v4
	v_mul_f32_e32 v4, v2, v11
	s_waitcnt lgkmcnt(0)
	v_fma_f32 v53, v15, v17, -v4
	v_mul_f32_e32 v4, v2, v10
	v_add_u32_e32 v10, 0x5c00, v38
	ds_read_b128 v[6:9], v0 offset:176
	ds_read2_b32 v[18:19], v10 offset0:46 offset1:175
	ds_read2_b32 v[20:21], v27 offset0:46 offset1:47
	v_fma_f32 v54, v14, v16, -v4
	ds_read2_b32 v[14:15], v27 offset0:44 offset1:45
	s_waitcnt lgkmcnt(3)
	v_mul_f32_e32 v4, v2, v9
	ds_read_b128 v[10:13], v0 offset:160
	s_waitcnt lgkmcnt(2)
	v_fma_f32 v55, v19, v21, -v4
	v_add_u32_e32 v4, 0x5800, v38
	ds_read2_b32 v[16:17], v4 offset0:44 offset1:173
	v_mul_f32_e32 v4, v2, v8
	v_fma_f32 v56, v18, v20, -v4
	v_mul_f32_e32 v4, v2, v7
	ds_read2_b32 v[8:9], v27 offset0:42 offset1:43
	s_waitcnt lgkmcnt(1)
	v_fma_f32 v57, v17, v15, -v4
	v_mul_f32_e32 v4, v2, v6
	v_fma_f32 v58, v16, v14, -v4
	v_add_u32_e32 v4, 0x5400, v38
	ds_read2_b32 v[6:7], v4 offset0:42 offset1:171
	v_mul_f32_e32 v4, v2, v13
	v_add_u32_e32 v13, 0x5000, v38
	ds_read2_b32 v[14:15], v13 offset0:40 offset1:169
	ds_read2_b32 v[16:17], v27 offset0:40 offset1:41
	s_lshl_b64 s[6:7], s[40:41], 14
	s_waitcnt lgkmcnt(2)
	v_fma_f32 v59, v7, v9, -v4
	v_mul_f32_e32 v4, v2, v12
	v_fma_f32 v60, v6, v8, -v4
	v_mul_f32_e32 v4, v2, v11
	s_waitcnt lgkmcnt(0)
	v_fma_f32 v61, v15, v17, -v4
	v_mul_f32_e32 v4, v2, v10
	v_add_u32_e32 v10, 0x4c00, v38
	ds_read_b128 v[6:9], v0 offset:144
	ds_read2_b32 v[18:19], v10 offset0:38 offset1:167
	ds_read2_b32 v[20:21], v27 offset0:38 offset1:39
	v_fma_f32 v62, v14, v16, -v4
	ds_read2_b32 v[14:15], v27 offset0:36 offset1:37
	s_waitcnt lgkmcnt(3)
	v_mul_f32_e32 v4, v2, v9
	ds_read_b128 v[10:13], v0 offset:128
	s_waitcnt lgkmcnt(2)
	v_fma_f32 v63, v19, v21, -v4
	v_add_u32_e32 v4, 0x4800, v38
	ds_read2_b32 v[16:17], v4 offset0:36 offset1:165
	v_mul_f32_e32 v4, v2, v8
	v_fma_f32 v64, v18, v20, -v4
	v_mul_f32_e32 v4, v2, v7
	ds_read2_b32 v[8:9], v27 offset0:34 offset1:35
	s_waitcnt lgkmcnt(1)
	v_fma_f32 v65, v17, v15, -v4
	v_mul_f32_e32 v4, v2, v6
	v_fma_f32 v66, v16, v14, -v4
	v_add_u32_e32 v4, 0x4400, v38
	ds_read2_b32 v[6:7], v4 offset0:34 offset1:163
	v_mul_f32_e32 v4, v2, v13
	v_add_u32_e32 v13, 0x4000, v38
	ds_read2_b32 v[14:15], v13 offset0:32 offset1:161
	ds_read2_b32 v[16:17], v27 offset0:32 offset1:33
	s_waitcnt lgkmcnt(2)
	v_fma_f32 v67, v7, v9, -v4
	v_mul_f32_e32 v4, v2, v12
	v_fma_f32 v68, v6, v8, -v4
	v_mul_f32_e32 v4, v2, v11
	s_waitcnt lgkmcnt(0)
	v_fma_f32 v69, v15, v17, -v4
	v_mul_f32_e32 v4, v2, v10
	v_add_u32_e32 v10, 0x3c00, v38
	ds_read_b128 v[6:9], v0 offset:112
	ds_read2_b32 v[18:19], v10 offset0:30 offset1:159
	ds_read2_b32 v[20:21], v27 offset0:30 offset1:31
	v_fma_f32 v70, v14, v16, -v4
	ds_read2_b32 v[14:15], v27 offset0:28 offset1:29
	s_waitcnt lgkmcnt(3)
; #define LAS __attribute__((address_space(3)))
; #define PIN16(o) asm volatile("" : "+v"(xr[o]), "+v"(xr[o + 1]), "+v"(xr[o + 2]), "+v"(xr[o + 3]), "+v"(xr[o + 4]), "+v"(xr[o + 5]), "+v"(xr[o + 6]), "+v"(xr[o + 7]), "+v"(xr[o + 8]), "+v"(xr[o + 9]), "+v"(xr[o + 10]), "+v"(xr[o + 11]), "+v"(xr[o + 12]), "+v"(xr[o + 13]), "+v"(xr[o + 14]), "+v"(xr[o + 15]) :: "memory")
; DI void gdn_prep_item(LAS unsigned char* lds, const Ctx& c, int l, int item) {
;     ...
; #pragma unroll
;         for (int j = 0; j < 63; ++j) {
;             const float xj = xr[j];
; #pragma unroll
;             for (int i4 = (j + 1) / 4; i4 < 16; ++i4) { const f32x4 Lv = *(const LAS f32x4*)(Lb + j * 64 + 4 * i4);
; #pragma unroll
;                 for (int q = 0; q < 4; ++q) xr[4 * i4 + q] -= Lv[q] * xj; }
;     ...
;             PIN16(0); PIN16(16); PIN16(32); PIN16(48);
;         }
	v_mul_f32_e32 v4, v2, v9
	ds_read_b128 v[10:13], v0 offset:96
	s_waitcnt lgkmcnt(2)
	v_fma_f32 v71, v19, v21, -v4
	v_add_u32_e32 v4, 0x3800, v38
	ds_read2_b32 v[16:17], v4 offset0:28 offset1:157
	v_mul_f32_e32 v4, v2, v8
	v_fma_f32 v72, v18, v20, -v4
	v_mul_f32_e32 v4, v2, v7
	ds_read2_b32 v[8:9], v27 offset0:26 offset1:27
	s_waitcnt lgkmcnt(1)
	v_fma_f32 v73, v17, v15, -v4
	v_mul_f32_e32 v4, v2, v6
	v_fma_f32 v74, v16, v14, -v4
	v_add_u32_e32 v4, 0x3400, v38
	ds_read2_b32 v[6:7], v4 offset0:26 offset1:155
	v_mul_f32_e32 v4, v2, v13
	v_add_u32_e32 v13, 0x3000, v38
	ds_read2_b32 v[14:15], v13 offset0:24 offset1:153
	ds_read2_b32 v[16:17], v27 offset0:24 offset1:25
	s_waitcnt lgkmcnt(2)
	v_fma_f32 v75, v7, v9, -v4
	v_mul_f32_e32 v4, v2, v12
	v_fma_f32 v76, v6, v8, -v4
	v_mul_f32_e32 v4, v2, v11
	s_waitcnt lgkmcnt(0)
	v_fma_f32 v77, v15, v17, -v4
	v_mul_f32_e32 v4, v2, v10
	v_add_u32_e32 v10, 0x2c00, v38
	ds_read_b128 v[6:9], v0 offset:80
	ds_read2_b32 v[18:19], v10 offset0:22 offset1:151
	ds_read2_b32 v[20:21], v27 offset0:22 offset1:23
	v_fma_f32 v78, v14, v16, -v4
	ds_read2_b32 v[14:15], v27 offset0:20 offset1:21
	s_waitcnt lgkmcnt(3)
	v_mul_f32_e32 v4, v2, v9
	ds_read_b128 v[10:13], v0 offset:64
	s_waitcnt lgkmcnt(2)
	v_fma_f32 v79, v19, v21, -v4
	v_add_u32_e32 v4, 0x2800, v38
	ds_read2_b32 v[16:17], v4 offset0:20 offset1:149
	v_mul_f32_e32 v4, v2, v8
	v_fma_f32 v80, v18, v20, -v4
	v_mul_f32_e32 v4, v2, v7
	ds_read2_b32 v[8:9], v27 offset0:18 offset1:19
	s_waitcnt lgkmcnt(1)
	v_fma_f32 v81, v17, v15, -v4
	v_mul_f32_e32 v4, v2, v6
	v_fma_f32 v82, v16, v14, -v4
	v_add_u32_e32 v4, 0x2400, v38
	ds_read2_b32 v[6:7], v4 offset0:18 offset1:147
	v_mul_f32_e32 v4, v2, v13
	v_add_u32_e32 v13, 0x2000, v38
	ds_read2_b32 v[14:15], v13 offset0:16 offset1:145
	ds_read2_b32 v[16:17], v27 offset0:16 offset1:17
	s_waitcnt lgkmcnt(2)
	v_fma_f32 v83, v7, v9, -v4
	v_mul_f32_e32 v4, v2, v12
	v_fma_f32 v84, v6, v8, -v4
	v_mul_f32_e32 v4, v2, v11
	s_waitcnt lgkmcnt(0)
	v_fma_f32 v85, v15, v17, -v4
	v_mul_f32_e32 v4, v2, v10
	v_fma_f32 v86, v14, v16, -v4
	v_add_u32_e32 v4, 0x1c00, v38
	ds_read_b128 v[6:9], v0 offset:32
	ds_read_b128 v[10:13], v0 offset:48
	ds_read2_b32 v[30:31], v4 offset0:14 offset1:143
	ds_read2_b32 v[32:33], v27 offset0:14 offset1:15
	ds_read_b128 v[14:17], v0
	ds_read_b128 v[18:21], v0 offset:16
	s_waitcnt lgkmcnt(4)
	v_mul_f32_e32 v4, v2, v13
	ds_read2_b32 v[34:35], v27 offset0:12 offset1:13
	s_waitcnt lgkmcnt(3)
	v_fma_f32 v33, v31, v33, -v4
	v_add_u32_e32 v4, 0x1800, v38
	ds_read2_b32 v[36:37], v4 offset0:12 offset1:141
	v_mul_f32_e32 v4, v2, v12
	v_fma_f32 v32, v30, v32, -v4
	v_mul_f32_e32 v4, v2, v11
	ds_read2_b32 v[12:13], v27 offset0:10 offset1:11
	s_waitcnt lgkmcnt(1)
	v_fma_f32 v35, v37, v35, -v4
	v_add_u32_e32 v4, 0x1400, v38
	ds_read2_b32 v[30:31], v4 offset0:10 offset1:139
	v_mul_f32_e32 v4, v2, v10
	v_fma_f32 v34, v36, v34, -v4
	v_mul_f32_e32 v4, v2, v9
	ds_read2_b32 v[10:11], v27 offset0:8 offset1:9
	s_waitcnt lgkmcnt(1)
	v_fma_f32 v27, v31, v13, -v4
	v_mul_f32_e32 v4, v2, v8
	v_add_u32_e32 v8, 0x1000, v38
	ds_read2_b32 v[8:9], v8 offset0:8 offset1:137
	v_fma_f32 v30, v30, v12, -v4
	v_mul_f32_e32 v4, v2, v7
	v_add_u32_e32 v7, 0xc00, v38
	ds_read2_b32 v[12:13], v7 offset0:6 offset1:135
	s_waitcnt lgkmcnt(1)
	v_fma_f32 v31, v9, v11, -v4
	v_mul_f32_e32 v4, v2, v6
	v_add_u32_e32 v6, 0x800, v38
	ds_read2_b32 v[6:7], v6 offset0:4 offset1:133
	v_fma_f32 v36, v8, v10, -v4
	v_add_u32_e32 v8, 0x400, v38
	v_mul_f32_e32 v4, v2, v21
	ds_read2_b32 v[8:9], v8 offset0:2 offset1:131
	s_waitcnt lgkmcnt(2)
	v_fma_f32 v21, v13, v23, -v4
	v_mul_f32_e32 v4, v2, v20
	v_fma_f32 v20, v12, v22, -v4
	v_mul_f32_e32 v4, v2, v19
	s_waitcnt lgkmcnt(1)
	v_fma_f32 v22, v7, v25, -v4
	v_mul_f32_e32 v4, v2, v18
	v_fma_f32 v23, v6, v24, -v4
	v_mul_f32_e32 v4, v2, v17
	s_waitcnt lgkmcnt(0)
	v_fma_f32 v24, v9, v29, -v4
	v_mul_f32_e32 v4, v2, v16
	v_fma_f32 v25, v8, v28, -v4
	v_mul_f32_e32 v4, v2, v15
	v_fma_f32 v28, v3, v5, -v4
	v_fma_f32 v29, -v2, v14, v2
	ds_read_b128 v[90:93], v0 offset:496
	ds_read_b128 v[94:97], v0 offset:480
	ds_read_b128 v[98:101], v0 offset:464
	ds_read_b128 v[102:105], v0 offset:448
	ds_read_b128 v[106:109], v0 offset:432
	ds_read_b128 v[110:113], v0 offset:416
	ds_read_b128 v[114:117], v0 offset:400
	ds_read_b128 v[118:121], v0 offset:384
	ds_read_b128 v[122:125], v0 offset:368
	ds_read_b128 v[126:129], v0 offset:352
	ds_read_b128 v[156:159], v0 offset:336
	ds_read_b128 v[160:163], v0 offset:320
	ds_read_b128 v[164:167], v0 offset:288
	s_waitcnt lgkmcnt(12)
	v_fma_f32 v37, -v28, v93, v39
	v_fma_f32 v38, -v28, v92, v40
	v_fma_f32 v39, -v28, v91, v41
	v_fma_f32 v40, -v28, v90, v42
	ds_read_b128 v[168:171], v0 offset:304
	s_waitcnt lgkmcnt(12)
	v_fma_f32 v41, -v28, v97, v43
	v_fma_f32 v42, -v28, v96, v44
	v_fma_f32 v43, -v28, v95, v45
	v_fma_f32 v44, -v28, v94, v46
	ds_read_b128 v[172:175], v0 offset:256
	s_waitcnt lgkmcnt(12)
	v_fma_f32 v45, -v28, v101, v47
	v_fma_f32 v46, -v28, v100, v48
	v_fma_f32 v47, -v28, v99, v49
	v_fma_f32 v48, -v28, v98, v50
	ds_read_b128 v[176:179], v0 offset:272
	s_waitcnt lgkmcnt(12)
	v_fma_f32 v49, -v28, v105, v51
	v_fma_f32 v50, -v28, v104, v52
	v_fma_f32 v51, -v28, v103, v53
	v_fma_f32 v52, -v28, v102, v54
	ds_read_b128 v[180:183], v0 offset:752
	s_waitcnt lgkmcnt(12)
	v_fma_f32 v53, -v28, v109, v55
	v_fma_f32 v54, -v28, v108, v56
	v_fma_f32 v55, -v28, v107, v57
	v_fma_f32 v56, -v28, v106, v58
	ds_read_b128 v[184:187], v0 offset:736
	s_waitcnt lgkmcnt(12)
	v_fma_f32 v57, -v28, v113, v59
	v_fma_f32 v58, -v28, v112, v60
	v_fma_f32 v59, -v28, v111, v61
	v_fma_f32 v60, -v28, v110, v62
	ds_read_b128 v[188:191], v0 offset:720
	s_waitcnt lgkmcnt(12)
; #define LAS __attribute__((address_space(3)))
; #define PIN16(o) asm volatile("" : "+v"(xr[o]), "+v"(xr[o + 1]), "+v"(xr[o + 2]), "+v"(xr[o + 3]), "+v"(xr[o + 4]), "+v"(xr[o + 5]), "+v"(xr[o + 6]), "+v"(xr[o + 7]), "+v"(xr[o + 8]), "+v"(xr[o + 9]), "+v"(xr[o + 10]), "+v"(xr[o + 11]), "+v"(xr[o + 12]), "+v"(xr[o + 13]), "+v"(xr[o + 14]), "+v"(xr[o + 15]) :: "memory")
; DI void gdn_prep_item(LAS unsigned char* lds, const Ctx& c, int l, int item) {
;     ...
; #pragma unroll
;         for (int j = 0; j < 63; ++j) {
;             const float xj = xr[j];
; #pragma unroll
;             for (int i4 = (j + 1) / 4; i4 < 16; ++i4) { const f32x4 Lv = *(const LAS f32x4*)(Lb + j * 64 + 4 * i4);
; #pragma unroll
;                 for (int q = 0; q < 4; ++q) xr[4 * i4 + q] -= Lv[q] * xj; }
;     ...
;             PIN16(0); PIN16(16); PIN16(32); PIN16(48);
;         }
	v_fma_f32 v61, -v28, v117, v63
	v_fma_f32 v62, -v28, v116, v64
	v_fma_f32 v63, -v28, v115, v65
	v_fma_f32 v64, -v28, v114, v66
	ds_read_b128 v[90:93], v0 offset:704
	s_waitcnt lgkmcnt(12)
	v_fma_f32 v65, -v28, v121, v67
	v_fma_f32 v66, -v28, v120, v68
	v_fma_f32 v67, -v28, v119, v69
	v_fma_f32 v68, -v28, v118, v70
	ds_read_b128 v[94:97], v0 offset:688
	s_waitcnt lgkmcnt(12)
	v_fma_f32 v69, -v28, v125, v71
	v_fma_f32 v70, -v28, v124, v72
	v_fma_f32 v71, -v28, v123, v73
	v_fma_f32 v72, -v28, v122, v74
	ds_read_b128 v[98:101], v0 offset:672
	s_waitcnt lgkmcnt(12)
	v_fma_f32 v73, -v28, v129, v75
	v_fma_f32 v74, -v28, v128, v76
	v_fma_f32 v75, -v28, v127, v77
	v_fma_f32 v76, -v28, v126, v78
	ds_read_b128 v[102:105], v0 offset:656
	s_waitcnt lgkmcnt(12)
	v_fma_f32 v77, -v28, v159, v79
	v_fma_f32 v78, -v28, v158, v80
	v_fma_f32 v79, -v28, v157, v81
	v_fma_f32 v80, -v28, v156, v82
	ds_read_b128 v[106:109], v0 offset:640
	s_waitcnt lgkmcnt(12)
	v_fma_f32 v81, -v28, v163, v83
	v_fma_f32 v82, -v28, v162, v84
	v_fma_f32 v83, -v28, v161, v85
	v_fma_f32 v84, -v28, v160, v86
	ds_read_b128 v[110:113], v0 offset:624
	s_waitcnt lgkmcnt(12)
	v_fma_f32 v27, -v28, v167, v27
	ds_read_b128 v[114:117], v0 offset:608
	s_waitcnt lgkmcnt(12)
	v_fma_f32 v33, -v28, v171, v33
	v_fma_f32 v32, -v28, v170, v32
	v_fma_f32 v35, -v28, v169, v35
	v_fma_f32 v34, -v28, v168, v34
	v_fma_f32 v30, -v28, v166, v30
	v_fma_f32 v31, -v28, v165, v31
	v_fma_f32 v36, -v28, v164, v36
	ds_read_b128 v[118:121], v0 offset:592
	ds_read_b128 v[122:125], v0 offset:576
	s_waitcnt lgkmcnt(12)
	v_fma_f32 v21, -v28, v179, v21
	v_fma_f32 v20, -v28, v178, v20
	v_fma_f32 v22, -v28, v177, v22
	v_fma_f32 v23, -v28, v176, v23
	v_fma_f32 v24, -v28, v175, v24
	v_fma_f32 v25, -v28, v174, v25
	v_fma_f32 v85, -v28, v173, v28
	v_fma_f32 v28, -v28, v172, v29
	ds_read_b128 v[126:129], v0 offset:544
	s_waitcnt lgkmcnt(12)
	v_fma_f32 v29, -v25, v183, v37
	v_fma_f32 v37, -v25, v182, v38
	v_fma_f32 v38, -v25, v181, v39
	v_fma_f32 v39, -v25, v180, v40
	ds_read_b128 v[156:159], v0 offset:560
	s_waitcnt lgkmcnt(12)
	v_fma_f32 v40, -v25, v187, v41
	v_fma_f32 v41, -v25, v186, v42
	v_fma_f32 v42, -v25, v185, v43
	v_fma_f32 v43, -v25, v184, v44
	ds_read_b128 v[160:163], v0 offset:512
	s_waitcnt lgkmcnt(12)
	v_fma_f32 v44, -v25, v191, v45
	v_fma_f32 v45, -v25, v190, v46
	v_fma_f32 v46, -v25, v189, v47
	v_fma_f32 v47, -v25, v188, v48
	ds_read_b128 v[164:167], v0 offset:528
	s_waitcnt lgkmcnt(12)
	v_fma_f32 v48, -v25, v93, v49
	v_fma_f32 v49, -v25, v92, v50
	v_fma_f32 v50, -v25, v91, v51
	v_fma_f32 v51, -v25, v90, v52
	ds_read_b128 v[168:171], v0 offset:1008
	s_waitcnt lgkmcnt(12)
	v_fma_f32 v52, -v25, v97, v53
	v_fma_f32 v53, -v25, v96, v54
	v_fma_f32 v54, -v25, v95, v55
	v_fma_f32 v55, -v25, v94, v56
	ds_read_b128 v[172:175], v0 offset:992
	s_waitcnt lgkmcnt(12)
	v_fma_f32 v56, -v25, v101, v57
	v_fma_f32 v57, -v25, v100, v58
	v_fma_f32 v58, -v25, v99, v59
	v_fma_f32 v59, -v25, v98, v60
	ds_read_b128 v[176:179], v0 offset:976
	s_waitcnt lgkmcnt(12)
	v_fma_f32 v60, -v25, v105, v61
	v_fma_f32 v61, -v25, v104, v62
	v_fma_f32 v62, -v25, v103, v63
	v_fma_f32 v63, -v25, v102, v64
	ds_read_b128 v[180:183], v0 offset:960
	s_waitcnt lgkmcnt(12)
	v_fma_f32 v64, -v25, v109, v65
	v_fma_f32 v65, -v25, v108, v66
	v_fma_f32 v66, -v25, v107, v67
	v_fma_f32 v67, -v25, v106, v68
	ds_read_b128 v[184:187], v0 offset:944
	s_waitcnt lgkmcnt(12)
	v_fma_f32 v68, -v25, v113, v69
	v_fma_f32 v69, -v25, v112, v70
	v_fma_f32 v70, -v25, v111, v71
	v_fma_f32 v71, -v25, v110, v72
	ds_read_b128 v[188:191], v0 offset:928
	s_waitcnt lgkmcnt(12)
	v_fma_f32 v72, -v25, v117, v73
	v_fma_f32 v73, -v25, v116, v74
	v_fma_f32 v74, -v25, v115, v75
	v_fma_f32 v75, -v25, v114, v76
	ds_read_b128 v[90:93], v0 offset:912
	s_waitcnt lgkmcnt(12)
	v_fma_f32 v76, -v25, v121, v77
	v_fma_f32 v77, -v25, v120, v78
	v_fma_f32 v78, -v25, v119, v79
	v_fma_f32 v79, -v25, v118, v80
	ds_read_b128 v[94:97], v0 offset:896
	s_waitcnt lgkmcnt(12)
	v_fma_f32 v80, -v25, v125, v81
	v_fma_f32 v81, -v25, v124, v82
	v_fma_f32 v82, -v25, v123, v83
	v_fma_f32 v83, -v25, v122, v84
	ds_read_b128 v[98:101], v0 offset:880
	s_waitcnt lgkmcnt(12)
	v_fma_f32 v27, -v25, v129, v27
	ds_read_b128 v[102:105], v0 offset:864
	s_waitcnt lgkmcnt(12)
	v_fma_f32 v33, -v25, v159, v33
	v_fma_f32 v32, -v25, v158, v32
	v_fma_f32 v35, -v25, v157, v35
	v_fma_f32 v34, -v25, v156, v34
	v_fma_f32 v30, -v25, v128, v30
	v_fma_f32 v31, -v25, v127, v31
	v_fma_f32 v36, -v25, v126, v36
	ds_read_b128 v[106:109], v0 offset:848
	ds_read_b128 v[110:113], v0 offset:816
	s_waitcnt lgkmcnt(12)
	v_fma_f32 v84, -v25, v167, v21
	v_fma_f32 v86, -v25, v166, v20
	v_fma_f32 v87, -v25, v165, v22
	v_fma_f32 v88, -v25, v164, v23
	v_fma_f32 v2, -v25, v163, v24
	v_fma_f32 v3, -v25, v162, v25
	v_fma_f32 v4, -v25, v161, v85
	v_fma_f32 v5, -v25, v160, v28
	ds_read_b128 v[114:117], v0 offset:832
	s_waitcnt lgkmcnt(12)
	v_fma_f32 v24, -v2, v171, v29
	v_fma_f32 v25, -v2, v170, v37
	v_fma_f32 v28, -v2, v169, v38
	v_fma_f32 v29, -v2, v168, v39
	ds_read_b128 v[118:121], v0 offset:784
	s_waitcnt lgkmcnt(12)
	v_fma_f32 v37, -v2, v175, v40
	v_fma_f32 v38, -v2, v174, v41
	v_fma_f32 v39, -v2, v173, v42
	v_fma_f32 v40, -v2, v172, v43
	ds_read_b128 v[122:125], v0 offset:800
	s_waitcnt lgkmcnt(12)
	v_fma_f32 v41, -v2, v179, v44
	v_fma_f32 v42, -v2, v178, v45
	v_fma_f32 v43, -v2, v177, v46
	v_fma_f32 v44, -v2, v176, v47
	ds_read_b128 v[126:129], v0 offset:1264
	s_waitcnt lgkmcnt(12)
	v_fma_f32 v45, -v2, v183, v48
	v_fma_f32 v46, -v2, v182, v49
	v_fma_f32 v47, -v2, v181, v50
	v_fma_f32 v48, -v2, v180, v51
	ds_read_b128 v[156:159], v0 offset:1248
	s_waitcnt lgkmcnt(12)
; #define LAS __attribute__((address_space(3)))
; #define PIN16(o) asm volatile("" : "+v"(xr[o]), "+v"(xr[o + 1]), "+v"(xr[o + 2]), "+v"(xr[o + 3]), "+v"(xr[o + 4]), "+v"(xr[o + 5]), "+v"(xr[o + 6]), "+v"(xr[o + 7]), "+v"(xr[o + 8]), "+v"(xr[o + 9]), "+v"(xr[o + 10]), "+v"(xr[o + 11]), "+v"(xr[o + 12]), "+v"(xr[o + 13]), "+v"(xr[o + 14]), "+v"(xr[o + 15]) :: "memory")
; DI void gdn_prep_item(LAS unsigned char* lds, const Ctx& c, int l, int item) {
;     ...
; #pragma unroll
;         for (int j = 0; j < 63; ++j) {
;             const float xj = xr[j];
; #pragma unroll
;             for (int i4 = (j + 1) / 4; i4 < 16; ++i4) { const f32x4 Lv = *(const LAS f32x4*)(Lb + j * 64 + 4 * i4);
; #pragma unroll
;                 for (int q = 0; q < 4; ++q) xr[4 * i4 + q] -= Lv[q] * xj; }
;     ...
;             PIN16(0); PIN16(16); PIN16(32); PIN16(48);
;         }
	v_fma_f32 v49, -v2, v187, v52
	v_fma_f32 v50, -v2, v186, v53
	v_fma_f32 v51, -v2, v185, v54
	v_fma_f32 v52, -v2, v184, v55
	ds_read_b128 v[160:163], v0 offset:1232
	s_waitcnt lgkmcnt(12)
	v_fma_f32 v53, -v2, v191, v56
	v_fma_f32 v54, -v2, v190, v57
	v_fma_f32 v55, -v2, v189, v58
	v_fma_f32 v56, -v2, v188, v59
	ds_read_b128 v[164:167], v0 offset:1216
	s_waitcnt lgkmcnt(12)
	v_fma_f32 v57, -v2, v93, v60
	v_fma_f32 v58, -v2, v92, v61
	v_fma_f32 v59, -v2, v91, v62
	v_fma_f32 v60, -v2, v90, v63
	ds_read_b128 v[168:171], v0 offset:1200
	s_waitcnt lgkmcnt(12)
	v_fma_f32 v61, -v2, v97, v64
	v_fma_f32 v62, -v2, v96, v65
	v_fma_f32 v63, -v2, v95, v66
	v_fma_f32 v64, -v2, v94, v67
	ds_read_b128 v[172:175], v0 offset:1184
	s_waitcnt lgkmcnt(12)
	v_fma_f32 v65, -v2, v101, v68
	v_fma_f32 v66, -v2, v100, v69
	v_fma_f32 v67, -v2, v99, v70
	v_fma_f32 v68, -v2, v98, v71
	ds_read_b128 v[176:179], v0 offset:1168
	s_waitcnt lgkmcnt(12)
	v_fma_f32 v69, -v2, v105, v72
	v_fma_f32 v70, -v2, v104, v73
	v_fma_f32 v71, -v2, v103, v74
	v_fma_f32 v72, -v2, v102, v75
	ds_read_b128 v[180:183], v0 offset:1152
	s_waitcnt lgkmcnt(12)
	v_fma_f32 v73, -v2, v109, v76
	v_fma_f32 v74, -v2, v108, v77
	v_fma_f32 v75, -v2, v107, v78
	v_fma_f32 v76, -v2, v106, v79
	ds_read_b128 v[184:187], v0 offset:1136
	s_waitcnt lgkmcnt(12)
	v_fma_f32 v33, -v2, v113, v33
	ds_read_b128 v[188:191], v0 offset:1120
	s_waitcnt lgkmcnt(12)
	v_fma_f32 v77, -v2, v117, v80
	v_fma_f32 v78, -v2, v116, v81
	v_fma_f32 v79, -v2, v115, v82
	v_fma_f32 v80, -v2, v114, v83
	v_fma_f32 v32, -v2, v112, v32
	v_fma_f32 v35, -v2, v111, v35
	v_fma_f32 v34, -v2, v110, v34
	ds_read_b128 v[90:93], v0 offset:1104
	ds_read_b128 v[94:97], v0 offset:1072
	s_waitcnt lgkmcnt(12)
	v_fma_f32 v27, -v2, v125, v27
	v_fma_f32 v30, -v2, v124, v30
	v_fma_f32 v31, -v2, v123, v31
	v_fma_f32 v36, -v2, v122, v36
	v_fma_f32 v81, -v2, v121, v84
	v_fma_f32 v82, -v2, v120, v86
	v_fma_f32 v83, -v2, v119, v87
	v_fma_f32 v84, -v2, v118, v88
	ds_read_b128 v[98:101], v0 offset:1088
	s_waitcnt lgkmcnt(12)
	v_fma_f32 v24, -v84, v129, v24
	v_fma_f32 v25, -v84, v128, v25
	v_fma_f32 v28, -v84, v127, v28
	v_fma_f32 v29, -v84, v126, v29
	ds_read_b128 v[102:105], v0 offset:1040
	s_waitcnt lgkmcnt(12)
	v_fma_f32 v37, -v84, v159, v37
	v_fma_f32 v38, -v84, v158, v38
	v_fma_f32 v39, -v84, v157, v39
	v_fma_f32 v40, -v84, v156, v40
	ds_read_b128 v[106:109], v0 offset:1056
	s_waitcnt lgkmcnt(12)
	v_fma_f32 v41, -v84, v163, v41
	v_fma_f32 v42, -v84, v162, v42
	v_fma_f32 v43, -v84, v161, v43
	v_fma_f32 v44, -v84, v160, v44
	ds_read_b128 v[110:113], v0 offset:1520
	s_waitcnt lgkmcnt(12)
	v_fma_f32 v45, -v84, v167, v45
	v_fma_f32 v46, -v84, v166, v46
	v_fma_f32 v47, -v84, v165, v47
	v_fma_f32 v48, -v84, v164, v48
	ds_read_b128 v[114:117], v0 offset:1504
	s_waitcnt lgkmcnt(12)
	v_fma_f32 v49, -v84, v171, v49
	v_fma_f32 v50, -v84, v170, v50
	v_fma_f32 v51, -v84, v169, v51
	v_fma_f32 v52, -v84, v168, v52
	ds_read_b128 v[118:121], v0 offset:1488
	s_waitcnt lgkmcnt(12)
	v_fma_f32 v53, -v84, v175, v53
	v_fma_f32 v54, -v84, v174, v54
	v_fma_f32 v55, -v84, v173, v55
	v_fma_f32 v56, -v84, v172, v56
	ds_read_b128 v[122:125], v0 offset:1472
	s_waitcnt lgkmcnt(12)
	v_fma_f32 v57, -v84, v179, v57
	v_fma_f32 v58, -v84, v178, v58
	v_fma_f32 v59, -v84, v177, v59
	v_fma_f32 v60, -v84, v176, v60
	ds_read_b128 v[126:129], v0 offset:1456
	s_waitcnt lgkmcnt(12)
	v_fma_f32 v61, -v84, v183, v61
	v_fma_f32 v62, -v84, v182, v62
	v_fma_f32 v63, -v84, v181, v63
	v_fma_f32 v64, -v84, v180, v64
	ds_read_b128 v[156:159], v0 offset:1440
	s_waitcnt lgkmcnt(12)
	v_fma_f32 v65, -v84, v187, v65
	v_fma_f32 v66, -v84, v186, v66
	v_fma_f32 v67, -v84, v185, v67
	v_fma_f32 v68, -v84, v184, v68
	ds_read_b128 v[160:163], v0 offset:1424
	s_waitcnt lgkmcnt(12)
	v_fma_f32 v69, -v84, v191, v69
	v_fma_f32 v70, -v84, v190, v70
	v_fma_f32 v71, -v84, v189, v71
	v_fma_f32 v72, -v84, v188, v72
	ds_read_b128 v[164:167], v0 offset:1408
	s_waitcnt lgkmcnt(12)
	v_fma_f32 v73, -v84, v93, v73
	v_fma_f32 v74, -v84, v92, v74
	v_fma_f32 v75, -v84, v91, v75
	v_fma_f32 v76, -v84, v90, v76
	ds_read_b128 v[168:171], v0 offset:1392
	s_waitcnt lgkmcnt(12)
	v_fma_f32 v33, -v84, v97, v33
	ds_read_b128 v[172:175], v0 offset:1376
	s_waitcnt lgkmcnt(12)
	v_fma_f32 v77, -v84, v101, v77
	v_fma_f32 v78, -v84, v100, v78
	v_fma_f32 v79, -v84, v99, v79
	v_fma_f32 v80, -v84, v98, v80
	v_fma_f32 v32, -v84, v96, v32
	v_fma_f32 v35, -v84, v95, v35
	v_fma_f32 v34, -v84, v94, v34
	ds_read_b128 v[176:179], v0 offset:1360
	ds_read_b128 v[180:183], v0 offset:1328
	s_waitcnt lgkmcnt(12)
	v_fma_f32 v27, -v84, v109, v27
	v_fma_f32 v30, -v84, v108, v30
	v_fma_f32 v31, -v84, v107, v31
	v_fma_f32 v36, -v84, v106, v36
	v_fma_f32 v81, -v84, v105, v81
	v_fma_f32 v82, -v84, v104, v82
	v_fma_f32 v83, -v84, v103, v83
	v_fma_f32 v84, -v84, v102, v84
	ds_read_b128 v[184:187], v0 offset:1344
	s_waitcnt lgkmcnt(12)
	v_fma_f32 v24, -v83, v113, v24
	v_fma_f32 v25, -v83, v112, v25
	v_fma_f32 v28, -v83, v111, v28
	v_fma_f32 v29, -v83, v110, v29
	ds_read_b128 v[188:191], v0 offset:1296
	s_waitcnt lgkmcnt(12)
	v_fma_f32 v37, -v83, v117, v37
	v_fma_f32 v38, -v83, v116, v38
	v_fma_f32 v39, -v83, v115, v39
	v_fma_f32 v40, -v83, v114, v40
	ds_read_b128 v[90:93], v0 offset:1312
	s_waitcnt lgkmcnt(12)
	v_fma_f32 v41, -v83, v121, v41
	v_fma_f32 v42, -v83, v120, v42
	v_fma_f32 v43, -v83, v119, v43
	v_fma_f32 v44, -v83, v118, v44
	ds_read_b128 v[94:97], v0 offset:1776
	s_waitcnt lgkmcnt(12)
	v_fma_f32 v45, -v83, v125, v45
	v_fma_f32 v46, -v83, v124, v46
	v_fma_f32 v47, -v83, v123, v47
	v_fma_f32 v48, -v83, v122, v48
	ds_read_b128 v[98:101], v0 offset:1760
	s_waitcnt lgkmcnt(12)
; #define LAS __attribute__((address_space(3)))
; #define PIN16(o) asm volatile("" : "+v"(xr[o]), "+v"(xr[o + 1]), "+v"(xr[o + 2]), "+v"(xr[o + 3]), "+v"(xr[o + 4]), "+v"(xr[o + 5]), "+v"(xr[o + 6]), "+v"(xr[o + 7]), "+v"(xr[o + 8]), "+v"(xr[o + 9]), "+v"(xr[o + 10]), "+v"(xr[o + 11]), "+v"(xr[o + 12]), "+v"(xr[o + 13]), "+v"(xr[o + 14]), "+v"(xr[o + 15]) :: "memory")
; DI void gdn_prep_item(LAS unsigned char* lds, const Ctx& c, int l, int item) {
;     ...
; #pragma unroll
;         for (int j = 0; j < 63; ++j) {
;             const float xj = xr[j];
; #pragma unroll
;             for (int i4 = (j + 1) / 4; i4 < 16; ++i4) { const f32x4 Lv = *(const LAS f32x4*)(Lb + j * 64 + 4 * i4);
; #pragma unroll
;                 for (int q = 0; q < 4; ++q) xr[4 * i4 + q] -= Lv[q] * xj; }
;     ...
;             PIN16(0); PIN16(16); PIN16(32); PIN16(48);
;         }
	v_fma_f32 v49, -v83, v129, v49
	v_fma_f32 v50, -v83, v128, v50
	v_fma_f32 v51, -v83, v127, v51
	v_fma_f32 v52, -v83, v126, v52
	ds_read_b128 v[102:105], v0 offset:1744
	s_waitcnt lgkmcnt(12)
	v_fma_f32 v53, -v83, v159, v53
	v_fma_f32 v54, -v83, v158, v54
	v_fma_f32 v55, -v83, v157, v55
	v_fma_f32 v56, -v83, v156, v56
	ds_read_b128 v[106:109], v0 offset:1728
	s_waitcnt lgkmcnt(12)
	v_fma_f32 v57, -v83, v163, v57
	v_fma_f32 v58, -v83, v162, v58
	v_fma_f32 v59, -v83, v161, v59
	v_fma_f32 v60, -v83, v160, v60
	ds_read_b128 v[110:113], v0 offset:1712
	s_waitcnt lgkmcnt(12)
	v_fma_f32 v61, -v83, v167, v61
	v_fma_f32 v62, -v83, v166, v62
	v_fma_f32 v63, -v83, v165, v63
	v_fma_f32 v64, -v83, v164, v64
	ds_read_b128 v[114:117], v0 offset:1696
	s_waitcnt lgkmcnt(12)
	v_fma_f32 v65, -v83, v171, v65
	v_fma_f32 v66, -v83, v170, v66
	v_fma_f32 v67, -v83, v169, v67
	v_fma_f32 v68, -v83, v168, v68
	ds_read_b128 v[118:121], v0 offset:1680
	s_waitcnt lgkmcnt(12)
	v_fma_f32 v69, -v83, v175, v69
	v_fma_f32 v70, -v83, v174, v70
	v_fma_f32 v71, -v83, v173, v71
	v_fma_f32 v72, -v83, v172, v72
	ds_read_b128 v[122:125], v0 offset:1664
	s_waitcnt lgkmcnt(12)
	v_fma_f32 v73, -v83, v179, v73
	v_fma_f32 v74, -v83, v178, v74
	v_fma_f32 v75, -v83, v177, v75
	v_fma_f32 v76, -v83, v176, v76
	ds_read_b128 v[126:129], v0 offset:1648
	s_waitcnt lgkmcnt(12)
	v_fma_f32 v33, -v83, v183, v33
	ds_read_b128 v[156:159], v0 offset:1632
	s_waitcnt lgkmcnt(12)
	v_fma_f32 v77, -v83, v187, v77
	v_fma_f32 v78, -v83, v186, v78
	v_fma_f32 v79, -v83, v185, v79
	v_fma_f32 v80, -v83, v184, v80
	v_fma_f32 v32, -v83, v182, v32
	v_fma_f32 v35, -v83, v181, v35
	v_fma_f32 v34, -v83, v180, v34
	ds_read_b128 v[160:163], v0 offset:1616
	ds_read_b128 v[164:167], v0 offset:1584
	s_waitcnt lgkmcnt(12)
	v_fma_f32 v27, -v83, v93, v27
	v_fma_f32 v30, -v83, v92, v30
	v_fma_f32 v31, -v83, v91, v31
	v_fma_f32 v36, -v83, v90, v36
	v_fma_f32 v81, -v83, v191, v81
	v_fma_f32 v82, -v83, v190, v82
	v_fma_f32 v85, -v83, v189, v83
	v_fma_f32 v83, -v83, v188, v84
	ds_read_b128 v[168:171], v0 offset:1600
	s_waitcnt lgkmcnt(12)
	v_fma_f32 v24, -v82, v97, v24
	v_fma_f32 v25, -v82, v96, v25
	v_fma_f32 v28, -v82, v95, v28
	v_fma_f32 v29, -v82, v94, v29
	ds_read_b128 v[172:175], v0 offset:1552
	s_waitcnt lgkmcnt(12)
	v_fma_f32 v37, -v82, v101, v37
	v_fma_f32 v38, -v82, v100, v38
	v_fma_f32 v39, -v82, v99, v39
	v_fma_f32 v40, -v82, v98, v40
	ds_read_b128 v[176:179], v0 offset:1568
	s_waitcnt lgkmcnt(12)
	v_fma_f32 v41, -v82, v105, v41
	v_fma_f32 v42, -v82, v104, v42
	v_fma_f32 v43, -v82, v103, v43
	v_fma_f32 v44, -v82, v102, v44
	ds_read_b128 v[180:183], v0 offset:2032
	s_waitcnt lgkmcnt(12)
	v_fma_f32 v45, -v82, v109, v45
	v_fma_f32 v46, -v82, v108, v46
	v_fma_f32 v47, -v82, v107, v47
	v_fma_f32 v48, -v82, v106, v48
	ds_read_b128 v[184:187], v0 offset:2016
	s_waitcnt lgkmcnt(12)
	v_fma_f32 v49, -v82, v113, v49
	v_fma_f32 v50, -v82, v112, v50
	v_fma_f32 v51, -v82, v111, v51
	v_fma_f32 v52, -v82, v110, v52
	ds_read_b128 v[188:191], v0 offset:2000
	s_waitcnt lgkmcnt(12)
	v_fma_f32 v53, -v82, v117, v53
	v_fma_f32 v54, -v82, v116, v54
	v_fma_f32 v55, -v82, v115, v55
	v_fma_f32 v56, -v82, v114, v56
	ds_read_b128 v[90:93], v0 offset:1984
	s_waitcnt lgkmcnt(12)
	v_fma_f32 v57, -v82, v121, v57
	v_fma_f32 v58, -v82, v120, v58
	v_fma_f32 v59, -v82, v119, v59
	v_fma_f32 v60, -v82, v118, v60
	ds_read_b128 v[94:97], v0 offset:1968
	s_waitcnt lgkmcnt(12)
	v_fma_f32 v61, -v82, v125, v61
	v_fma_f32 v62, -v82, v124, v62
	v_fma_f32 v63, -v82, v123, v63
	v_fma_f32 v64, -v82, v122, v64
	ds_read_b128 v[98:101], v0 offset:1952
	s_waitcnt lgkmcnt(12)
	v_fma_f32 v65, -v82, v129, v65
	v_fma_f32 v66, -v82, v128, v66
	v_fma_f32 v67, -v82, v127, v67
	v_fma_f32 v68, -v82, v126, v68
	ds_read_b128 v[102:105], v0 offset:1936
	s_waitcnt lgkmcnt(12)
	v_fma_f32 v69, -v82, v159, v69
	v_fma_f32 v70, -v82, v158, v70
	v_fma_f32 v71, -v82, v157, v71
	v_fma_f32 v72, -v82, v156, v72
	ds_read_b128 v[106:109], v0 offset:1920
	s_waitcnt lgkmcnt(12)
	v_fma_f32 v73, -v82, v163, v73
	v_fma_f32 v74, -v82, v162, v74
	v_fma_f32 v75, -v82, v161, v75
	v_fma_f32 v76, -v82, v160, v76
	ds_read_b128 v[110:113], v0 offset:1904
	s_waitcnt lgkmcnt(12)
	v_fma_f32 v33, -v82, v167, v33
	v_fma_f32 v32, -v82, v166, v32
	v_fma_f32 v35, -v82, v165, v35
	v_fma_f32 v34, -v82, v164, v34
	ds_read_b128 v[114:117], v0 offset:1888
	ds_read_b128 v[118:121], v0 offset:1856
	ds_read_b128 v[122:125], v0 offset:1872
	s_waitcnt lgkmcnt(12)
	v_fma_f32 v27, -v82, v179, v27
	v_fma_f32 v84, -v82, v178, v30
	v_fma_f32 v86, -v82, v177, v31
	v_fma_f32 v36, -v82, v176, v36
	v_fma_f32 v6, -v82, v175, v81
	v_fma_f32 v7, -v82, v174, v82
	v_fma_f32 v8, -v82, v173, v85
	v_fma_f32 v9, -v82, v172, v83
	v_fma_f32 v77, -v82, v171, v77
	v_fma_f32 v78, -v82, v170, v78
	v_fma_f32 v79, -v82, v169, v79
	v_fma_f32 v80, -v82, v168, v80
	ds_read_b128 v[126:129], v0 offset:1824
	s_waitcnt lgkmcnt(12)
	v_fma_f32 v24, -v6, v183, v24
	v_fma_f32 v25, -v6, v182, v25
	v_fma_f32 v81, -v6, v181, v28
	v_fma_f32 v82, -v6, v180, v29
	ds_read_b128 v[156:159], v0 offset:1840
	s_waitcnt lgkmcnt(12)
	v_fma_f32 v37, -v6, v187, v37
	v_fma_f32 v38, -v6, v186, v38
	v_fma_f32 v39, -v6, v185, v39
	v_fma_f32 v40, -v6, v184, v40
	ds_read_b128 v[160:163], v0 offset:2288
	s_waitcnt lgkmcnt(12)
	v_fma_f32 v41, -v6, v191, v41
	v_fma_f32 v42, -v6, v190, v42
	v_fma_f32 v43, -v6, v189, v43
	v_fma_f32 v44, -v6, v188, v44
	ds_read_b128 v[164:167], v0 offset:2272
	s_waitcnt lgkmcnt(12)
	v_fma_f32 v45, -v6, v93, v45
	v_fma_f32 v46, -v6, v92, v46
	v_fma_f32 v47, -v6, v91, v47
	v_fma_f32 v48, -v6, v90, v48
	ds_read_b128 v[168:171], v0 offset:2256
	s_waitcnt lgkmcnt(12)
; #define LAS __attribute__((address_space(3)))
; #define PIN16(o) asm volatile("" : "+v"(xr[o]), "+v"(xr[o + 1]), "+v"(xr[o + 2]), "+v"(xr[o + 3]), "+v"(xr[o + 4]), "+v"(xr[o + 5]), "+v"(xr[o + 6]), "+v"(xr[o + 7]), "+v"(xr[o + 8]), "+v"(xr[o + 9]), "+v"(xr[o + 10]), "+v"(xr[o + 11]), "+v"(xr[o + 12]), "+v"(xr[o + 13]), "+v"(xr[o + 14]), "+v"(xr[o + 15]) :: "memory")
; DI void gdn_prep_item(LAS unsigned char* lds, const Ctx& c, int l, int item) {
;     ...
; #pragma unroll
;         for (int j = 0; j < 63; ++j) {
;             const float xj = xr[j];
; #pragma unroll
;             for (int i4 = (j + 1) / 4; i4 < 16; ++i4) { const f32x4 Lv = *(const LAS f32x4*)(Lb + j * 64 + 4 * i4);
; #pragma unroll
;                 for (int q = 0; q < 4; ++q) xr[4 * i4 + q] -= Lv[q] * xj; }
;     ...
;             PIN16(0); PIN16(16); PIN16(32); PIN16(48);
;         }
	v_fma_f32 v49, -v6, v97, v49
	v_fma_f32 v50, -v6, v96, v50
	v_fma_f32 v51, -v6, v95, v51
	v_fma_f32 v52, -v6, v94, v52
	ds_read_b128 v[172:175], v0 offset:2240
	s_waitcnt lgkmcnt(12)
	v_fma_f32 v53, -v6, v101, v53
	v_fma_f32 v54, -v6, v100, v54
	v_fma_f32 v55, -v6, v99, v55
	v_fma_f32 v56, -v6, v98, v56
	ds_read_b128 v[176:179], v0 offset:2224
	s_waitcnt lgkmcnt(12)
	v_fma_f32 v57, -v6, v105, v57
	v_fma_f32 v58, -v6, v104, v58
	v_fma_f32 v59, -v6, v103, v59
	v_fma_f32 v60, -v6, v102, v60
	ds_read_b128 v[180:183], v0 offset:2208
	s_waitcnt lgkmcnt(12)
	v_fma_f32 v61, -v6, v109, v61
	v_fma_f32 v62, -v6, v108, v62
	v_fma_f32 v63, -v6, v107, v63
	v_fma_f32 v64, -v6, v106, v64
	ds_read_b128 v[184:187], v0 offset:2192
	s_waitcnt lgkmcnt(12)
	v_fma_f32 v65, -v6, v113, v65
	v_fma_f32 v66, -v6, v112, v66
	v_fma_f32 v67, -v6, v111, v67
	v_fma_f32 v68, -v6, v110, v68
	ds_read_b128 v[188:191], v0 offset:2176
	s_waitcnt lgkmcnt(12)
	v_fma_f32 v69, -v6, v117, v69
	v_fma_f32 v70, -v6, v116, v70
	v_fma_f32 v71, -v6, v115, v71
	v_fma_f32 v72, -v6, v114, v72
	ds_read_b128 v[90:93], v0 offset:2160
	s_waitcnt lgkmcnt(12)
	v_fma_f32 v77, -v6, v121, v77
	ds_read_b128 v[94:97], v0 offset:2144
	ds_read_b128 v[98:101], v0 offset:2112
	s_waitcnt lgkmcnt(12)
	v_fma_f32 v27, -v6, v129, v27
	ds_read_b128 v[102:105], v0 offset:2128
	s_waitcnt lgkmcnt(12)
	v_fma_f32 v33, -v6, v159, v33
	v_fma_f32 v32, -v6, v158, v32
	v_fma_f32 v35, -v6, v157, v35
	v_fma_f32 v34, -v6, v156, v34
	v_fma_f32 v83, -v6, v128, v84
	v_fma_f32 v84, -v6, v127, v86
	v_fma_f32 v36, -v6, v126, v36
	v_fma_f32 v73, -v6, v125, v73
	v_fma_f32 v74, -v6, v124, v74
	v_fma_f32 v75, -v6, v123, v75
	v_fma_f32 v76, -v6, v122, v76
	v_fma_f32 v78, -v6, v120, v78
	v_fma_f32 v79, -v6, v119, v79
	v_fma_f32 v80, -v6, v118, v80
	ds_read_b128 v[106:109], v0 offset:2080
	s_waitcnt lgkmcnt(12)
	v_fma_f32 v24, -v36, v163, v24
	v_fma_f32 v25, -v36, v162, v25
	v_fma_f32 v81, -v36, v161, v81
	v_fma_f32 v82, -v36, v160, v82
	ds_read_b128 v[110:113], v0 offset:2096
	s_waitcnt lgkmcnt(12)
	v_fma_f32 v37, -v36, v167, v37
	v_fma_f32 v38, -v36, v166, v38
	v_fma_f32 v39, -v36, v165, v39
	v_fma_f32 v40, -v36, v164, v40
	ds_read_b128 v[114:117], v0 offset:2544
	s_waitcnt lgkmcnt(12)
	v_fma_f32 v41, -v36, v171, v41
	v_fma_f32 v42, -v36, v170, v42
	v_fma_f32 v43, -v36, v169, v43
	v_fma_f32 v44, -v36, v168, v44
	ds_read_b128 v[118:121], v0 offset:2528
	s_waitcnt lgkmcnt(12)
	v_fma_f32 v45, -v36, v175, v45
	v_fma_f32 v46, -v36, v174, v46
	v_fma_f32 v47, -v36, v173, v47
	v_fma_f32 v48, -v36, v172, v48
	ds_read_b128 v[122:125], v0 offset:2512
	s_waitcnt lgkmcnt(12)
	v_fma_f32 v49, -v36, v179, v49
	v_fma_f32 v50, -v36, v178, v50
	v_fma_f32 v51, -v36, v177, v51
	v_fma_f32 v52, -v36, v176, v52
	ds_read_b128 v[126:129], v0 offset:2496
	s_waitcnt lgkmcnt(12)
	v_fma_f32 v53, -v36, v183, v53
	v_fma_f32 v54, -v36, v182, v54
	v_fma_f32 v55, -v36, v181, v55
	v_fma_f32 v56, -v36, v180, v56
	ds_read_b128 v[156:159], v0 offset:2480
	s_waitcnt lgkmcnt(12)
	v_fma_f32 v57, -v36, v187, v57
	v_fma_f32 v58, -v36, v186, v58
	v_fma_f32 v59, -v36, v185, v59
	v_fma_f32 v60, -v36, v184, v60
	ds_read_b128 v[160:163], v0 offset:2464
	s_waitcnt lgkmcnt(12)
	v_fma_f32 v61, -v36, v191, v61
	v_fma_f32 v62, -v36, v190, v62
	v_fma_f32 v63, -v36, v189, v63
	v_fma_f32 v64, -v36, v188, v64
	ds_read_b128 v[164:167], v0 offset:2448
	s_waitcnt lgkmcnt(12)
	v_fma_f32 v65, -v36, v93, v65
	v_fma_f32 v66, -v36, v92, v66
	v_fma_f32 v67, -v36, v91, v67
	v_fma_f32 v68, -v36, v90, v68
	ds_read_b128 v[168:171], v0 offset:2432
	s_waitcnt lgkmcnt(12)
	v_fma_f32 v69, -v36, v97, v69
	v_fma_f32 v70, -v36, v96, v70
	v_fma_f32 v71, -v36, v95, v71
	v_fma_f32 v72, -v36, v94, v72
	ds_read_b128 v[172:175], v0 offset:2416
	s_waitcnt lgkmcnt(12)
	v_fma_f32 v77, -v36, v101, v77
	ds_read_b128 v[176:179], v0 offset:2400
	s_waitcnt lgkmcnt(12)
	v_fma_f32 v73, -v36, v105, v73
	v_fma_f32 v74, -v36, v104, v74
	v_fma_f32 v75, -v36, v103, v75
	v_fma_f32 v76, -v36, v102, v76
	v_fma_f32 v78, -v36, v100, v78
	v_fma_f32 v79, -v36, v99, v79
	v_fma_f32 v80, -v36, v98, v80
	ds_read_b128 v[180:183], v0 offset:2368
	ds_read_b128 v[184:187], v0 offset:2384
	s_waitcnt lgkmcnt(12)
	v_fma_f32 v33, -v36, v113, v33
	v_fma_f32 v32, -v36, v112, v32
	v_fma_f32 v35, -v36, v111, v35
	v_fma_f32 v34, -v36, v110, v34
	v_fma_f32 v27, -v36, v109, v27
	v_fma_f32 v83, -v36, v108, v83
	v_fma_f32 v84, -v36, v107, v84
	v_fma_f32 v36, -v36, v106, v36
	ds_read_b128 v[188:191], v0 offset:2336
	s_waitcnt lgkmcnt(12)
	v_fma_f32 v24, -v84, v117, v24
	v_fma_f32 v25, -v84, v116, v25
	v_fma_f32 v81, -v84, v115, v81
	v_fma_f32 v82, -v84, v114, v82
	ds_read_b128 v[90:93], v0 offset:2352
	s_waitcnt lgkmcnt(12)
	v_fma_f32 v37, -v84, v121, v37
	v_fma_f32 v38, -v84, v120, v38
	v_fma_f32 v39, -v84, v119, v39
	v_fma_f32 v40, -v84, v118, v40
	ds_read_b128 v[94:97], v0 offset:2800
	s_waitcnt lgkmcnt(12)
	v_fma_f32 v41, -v84, v125, v41
	v_fma_f32 v42, -v84, v124, v42
	v_fma_f32 v43, -v84, v123, v43
	v_fma_f32 v44, -v84, v122, v44
	ds_read_b128 v[98:101], v0 offset:2784
	s_waitcnt lgkmcnt(12)
	v_fma_f32 v45, -v84, v129, v45
	v_fma_f32 v46, -v84, v128, v46
	v_fma_f32 v47, -v84, v127, v47
	v_fma_f32 v48, -v84, v126, v48
	ds_read_b128 v[102:105], v0 offset:2768
	s_waitcnt lgkmcnt(12)
	v_fma_f32 v49, -v84, v159, v49
	v_fma_f32 v50, -v84, v158, v50
	v_fma_f32 v51, -v84, v157, v51
	v_fma_f32 v52, -v84, v156, v52
	ds_read_b128 v[106:109], v0 offset:2752
	s_waitcnt lgkmcnt(12)
	v_fma_f32 v53, -v84, v163, v53
	v_fma_f32 v54, -v84, v162, v54
	v_fma_f32 v55, -v84, v161, v55
	v_fma_f32 v56, -v84, v160, v56
	ds_read_b128 v[110:113], v0 offset:2736
	s_waitcnt lgkmcnt(12)
; #define LAS __attribute__((address_space(3)))
; #define PIN16(o) asm volatile("" : "+v"(xr[o]), "+v"(xr[o + 1]), "+v"(xr[o + 2]), "+v"(xr[o + 3]), "+v"(xr[o + 4]), "+v"(xr[o + 5]), "+v"(xr[o + 6]), "+v"(xr[o + 7]), "+v"(xr[o + 8]), "+v"(xr[o + 9]), "+v"(xr[o + 10]), "+v"(xr[o + 11]), "+v"(xr[o + 12]), "+v"(xr[o + 13]), "+v"(xr[o + 14]), "+v"(xr[o + 15]) :: "memory")
; DI void gdn_prep_item(LAS unsigned char* lds, const Ctx& c, int l, int item) {
;     ...
; #pragma unroll
;         for (int j = 0; j < 63; ++j) {
;             const float xj = xr[j];
; #pragma unroll
;             for (int i4 = (j + 1) / 4; i4 < 16; ++i4) { const f32x4 Lv = *(const LAS f32x4*)(Lb + j * 64 + 4 * i4);
; #pragma unroll
;                 for (int q = 0; q < 4; ++q) xr[4 * i4 + q] -= Lv[q] * xj; }
;     ...
;             PIN16(0); PIN16(16); PIN16(32); PIN16(48);
;         }
	v_fma_f32 v57, -v84, v167, v57
	v_fma_f32 v58, -v84, v166, v58
	v_fma_f32 v59, -v84, v165, v59
	v_fma_f32 v60, -v84, v164, v60
	ds_read_b128 v[114:117], v0 offset:2720
	s_waitcnt lgkmcnt(12)
	v_fma_f32 v61, -v84, v171, v61
	v_fma_f32 v62, -v84, v170, v62
	v_fma_f32 v63, -v84, v169, v63
	v_fma_f32 v64, -v84, v168, v64
	ds_read_b128 v[118:121], v0 offset:2704
	s_waitcnt lgkmcnt(12)
	v_fma_f32 v65, -v84, v175, v65
	v_fma_f32 v66, -v84, v174, v66
	v_fma_f32 v67, -v84, v173, v67
	v_fma_f32 v68, -v84, v172, v68
	ds_read_b128 v[122:125], v0 offset:2688
	s_waitcnt lgkmcnt(12)
	v_fma_f32 v69, -v84, v179, v69
	v_fma_f32 v70, -v84, v178, v70
	v_fma_f32 v71, -v84, v177, v71
	v_fma_f32 v72, -v84, v176, v72
	ds_read_b128 v[126:129], v0 offset:2672
	s_waitcnt lgkmcnt(12)
	v_fma_f32 v77, -v84, v183, v77
	ds_read_b128 v[156:159], v0 offset:2656
	ds_read_b128 v[160:163], v0 offset:2624
	s_waitcnt lgkmcnt(12)
	v_fma_f32 v27, -v84, v191, v27
	ds_read_b128 v[164:167], v0 offset:2640
	s_waitcnt lgkmcnt(12)
	v_fma_f32 v33, -v84, v93, v33
	v_fma_f32 v32, -v84, v92, v32
	v_fma_f32 v35, -v84, v91, v35
	v_fma_f32 v34, -v84, v90, v34
	v_fma_f32 v83, -v84, v190, v83
	v_fma_f32 v85, -v84, v189, v84
	v_fma_f32 v36, -v84, v188, v36
	v_fma_f32 v73, -v84, v187, v73
	v_fma_f32 v74, -v84, v186, v74
	v_fma_f32 v75, -v84, v185, v75
	v_fma_f32 v76, -v84, v184, v76
	v_fma_f32 v78, -v84, v182, v78
	v_fma_f32 v79, -v84, v181, v79
	v_fma_f32 v80, -v84, v180, v80
	ds_read_b128 v[168:171], v0 offset:2592
	s_waitcnt lgkmcnt(12)
	v_fma_f32 v24, -v83, v97, v24
	v_fma_f32 v25, -v83, v96, v25
	v_fma_f32 v81, -v83, v95, v81
	v_fma_f32 v82, -v83, v94, v82
	ds_read_b128 v[172:175], v0 offset:2608
	s_waitcnt lgkmcnt(12)
	v_fma_f32 v37, -v83, v101, v37
	v_fma_f32 v38, -v83, v100, v38
	v_fma_f32 v39, -v83, v99, v39
	v_fma_f32 v40, -v83, v98, v40
	ds_read_b128 v[176:179], v0 offset:3056
	s_waitcnt lgkmcnt(12)
	v_fma_f32 v41, -v83, v105, v41
	v_fma_f32 v42, -v83, v104, v42
	v_fma_f32 v43, -v83, v103, v43
	v_fma_f32 v44, -v83, v102, v44
	ds_read_b128 v[180:183], v0 offset:3040
	s_waitcnt lgkmcnt(12)
	v_fma_f32 v45, -v83, v109, v45
	v_fma_f32 v46, -v83, v108, v46
	v_fma_f32 v47, -v83, v107, v47
	v_fma_f32 v48, -v83, v106, v48
	ds_read_b128 v[184:187], v0 offset:3024
	s_waitcnt lgkmcnt(12)
	v_fma_f32 v49, -v83, v113, v49
	v_fma_f32 v50, -v83, v112, v50
	v_fma_f32 v51, -v83, v111, v51
	v_fma_f32 v52, -v83, v110, v52
	ds_read_b128 v[188:191], v0 offset:3008
	s_waitcnt lgkmcnt(12)
	v_fma_f32 v53, -v83, v117, v53
	v_fma_f32 v54, -v83, v116, v54
	v_fma_f32 v55, -v83, v115, v55
	v_fma_f32 v56, -v83, v114, v56
	ds_read_b128 v[90:93], v0 offset:2992
	s_waitcnt lgkmcnt(12)
	v_fma_f32 v57, -v83, v121, v57
	v_fma_f32 v58, -v83, v120, v58
	v_fma_f32 v59, -v83, v119, v59
	v_fma_f32 v60, -v83, v118, v60
	ds_read_b128 v[94:97], v0 offset:2976
	s_waitcnt lgkmcnt(12)
	v_fma_f32 v61, -v83, v125, v61
	v_fma_f32 v62, -v83, v124, v62
	v_fma_f32 v63, -v83, v123, v63
	v_fma_f32 v64, -v83, v122, v64
	ds_read_b128 v[98:101], v0 offset:2960
	s_waitcnt lgkmcnt(12)
	v_fma_f32 v65, -v83, v129, v65
	v_fma_f32 v66, -v83, v128, v66
	v_fma_f32 v67, -v83, v127, v67
	v_fma_f32 v68, -v83, v126, v68
	ds_read_b128 v[102:105], v0 offset:2944
	s_waitcnt lgkmcnt(12)
	v_fma_f32 v69, -v83, v159, v69
	v_fma_f32 v70, -v83, v158, v70
	v_fma_f32 v71, -v83, v157, v71
	v_fma_f32 v72, -v83, v156, v72
	ds_read_b128 v[106:109], v0 offset:2928
	s_waitcnt lgkmcnt(12)
	v_fma_f32 v77, -v83, v163, v77
	v_fma_f32 v78, -v83, v162, v78
	v_fma_f32 v79, -v83, v161, v79
	v_fma_f32 v80, -v83, v160, v80
	ds_read_b128 v[110:113], v0 offset:2896
	ds_read_b128 v[114:117], v0 offset:2912
	ds_read_b128 v[118:121], v0 offset:2864
	s_waitcnt lgkmcnt(12)
	v_fma_f32 v84, -v83, v175, v33
	v_fma_f32 v86, -v83, v174, v32
	v_fma_f32 v87, -v83, v173, v35
	v_fma_f32 v88, -v83, v172, v34
	v_fma_f32 v10, -v83, v171, v27
	v_fma_f32 v11, -v83, v170, v83
	v_fma_f32 v12, -v83, v169, v85
	v_fma_f32 v13, -v83, v168, v36
	v_fma_f32 v73, -v83, v167, v73
	v_fma_f32 v74, -v83, v166, v74
	v_fma_f32 v75, -v83, v165, v75
	v_fma_f32 v76, -v83, v164, v76
	ds_read_b128 v[122:125], v0 offset:2880
	s_waitcnt lgkmcnt(12)
	v_fma_f32 v24, -v10, v179, v24
	v_fma_f32 v25, -v10, v178, v25
	v_fma_f32 v27, -v10, v177, v81
	v_fma_f32 v36, -v10, v176, v82
	ds_read_b128 v[126:129], v0 offset:3312
	s_waitcnt lgkmcnt(12)
	v_fma_f32 v37, -v10, v183, v37
	v_fma_f32 v38, -v10, v182, v38
	v_fma_f32 v39, -v10, v181, v39
	v_fma_f32 v40, -v10, v180, v40
	ds_read_b128 v[156:159], v0 offset:3296
	s_waitcnt lgkmcnt(12)
	v_fma_f32 v41, -v10, v187, v41
	v_fma_f32 v42, -v10, v186, v42
	v_fma_f32 v43, -v10, v185, v43
	v_fma_f32 v44, -v10, v184, v44
	ds_read_b128 v[160:163], v0 offset:3280
	s_waitcnt lgkmcnt(12)
	v_fma_f32 v45, -v10, v191, v45
	v_fma_f32 v46, -v10, v190, v46
	v_fma_f32 v47, -v10, v189, v47
	v_fma_f32 v48, -v10, v188, v48
	ds_read_b128 v[164:167], v0 offset:3264
	s_waitcnt lgkmcnt(12)
	v_fma_f32 v49, -v10, v93, v49
	v_fma_f32 v50, -v10, v92, v50
	v_fma_f32 v51, -v10, v91, v51
	v_fma_f32 v52, -v10, v90, v52
	ds_read_b128 v[168:171], v0 offset:3248
	s_waitcnt lgkmcnt(12)
	v_fma_f32 v53, -v10, v97, v53
	v_fma_f32 v54, -v10, v96, v54
	v_fma_f32 v55, -v10, v95, v55
	v_fma_f32 v56, -v10, v94, v56
	ds_read_b128 v[172:175], v0 offset:3232
	s_waitcnt lgkmcnt(12)
	v_fma_f32 v57, -v10, v101, v57
	v_fma_f32 v58, -v10, v100, v58
	v_fma_f32 v59, -v10, v99, v59
	v_fma_f32 v60, -v10, v98, v60
	ds_read_b128 v[176:179], v0 offset:3216
	s_waitcnt lgkmcnt(12)
	v_fma_f32 v61, -v10, v105, v61
	v_fma_f32 v62, -v10, v104, v62
	v_fma_f32 v63, -v10, v103, v63
	v_fma_f32 v64, -v10, v102, v64
	ds_read_b128 v[180:183], v0 offset:3200
	s_waitcnt lgkmcnt(12)
; #define LAS __attribute__((address_space(3)))
; #define PIN16(o) asm volatile("" : "+v"(xr[o]), "+v"(xr[o + 1]), "+v"(xr[o + 2]), "+v"(xr[o + 3]), "+v"(xr[o + 4]), "+v"(xr[o + 5]), "+v"(xr[o + 6]), "+v"(xr[o + 7]), "+v"(xr[o + 8]), "+v"(xr[o + 9]), "+v"(xr[o + 10]), "+v"(xr[o + 11]), "+v"(xr[o + 12]), "+v"(xr[o + 13]), "+v"(xr[o + 14]), "+v"(xr[o + 15]) :: "memory")
; DI void gdn_prep_item(LAS unsigned char* lds, const Ctx& c, int l, int item) {
;     ...
; #pragma unroll
;         for (int j = 0; j < 63; ++j) {
;             const float xj = xr[j];
; #pragma unroll
;             for (int i4 = (j + 1) / 4; i4 < 16; ++i4) { const f32x4 Lv = *(const LAS f32x4*)(Lb + j * 64 + 4 * i4);
; #pragma unroll
;                 for (int q = 0; q < 4; ++q) xr[4 * i4 + q] -= Lv[q] * xj; }
;     ...
;             PIN16(0); PIN16(16); PIN16(32); PIN16(48);
;         }
	v_fma_f32 v65, -v10, v109, v65
	v_fma_f32 v66, -v10, v108, v66
	v_fma_f32 v67, -v10, v107, v67
	v_fma_f32 v68, -v10, v106, v68
	ds_read_b128 v[184:187], v0 offset:3184
	s_waitcnt lgkmcnt(12)
	v_fma_f32 v73, -v10, v113, v73
	ds_read_b128 v[188:191], v0 offset:3152
	ds_read_b128 v[90:93], v0 offset:3168
	s_waitcnt lgkmcnt(12)
	v_fma_f32 v81, -v10, v121, v84
	v_fma_f32 v82, -v10, v120, v86
	v_fma_f32 v83, -v10, v119, v87
	v_fma_f32 v84, -v10, v118, v88
	v_fma_f32 v69, -v10, v117, v69
	v_fma_f32 v70, -v10, v116, v70
	v_fma_f32 v71, -v10, v115, v71
	v_fma_f32 v72, -v10, v114, v72
	v_fma_f32 v74, -v10, v112, v74
	v_fma_f32 v75, -v10, v111, v75
	v_fma_f32 v76, -v10, v110, v76
	ds_read_b128 v[94:97], v0 offset:3120
	s_waitcnt lgkmcnt(12)
	v_fma_f32 v77, -v10, v125, v77
	v_fma_f32 v78, -v10, v124, v78
	v_fma_f32 v79, -v10, v123, v79
	v_fma_f32 v80, -v10, v122, v80
	ds_read_b128 v[98:101], v0 offset:3136
	s_waitcnt lgkmcnt(12)
	v_fma_f32 v24, -v84, v129, v24
	v_fma_f32 v25, -v84, v128, v25
	v_fma_f32 v27, -v84, v127, v27
	v_fma_f32 v36, -v84, v126, v36
	ds_read_b128 v[102:105], v0 offset:3568
	s_waitcnt lgkmcnt(12)
	v_fma_f32 v37, -v84, v159, v37
	v_fma_f32 v38, -v84, v158, v38
	v_fma_f32 v39, -v84, v157, v39
	v_fma_f32 v40, -v84, v156, v40
	ds_read_b128 v[106:109], v0 offset:3552
	s_waitcnt lgkmcnt(12)
	v_fma_f32 v41, -v84, v163, v41
	v_fma_f32 v42, -v84, v162, v42
	v_fma_f32 v43, -v84, v161, v43
	v_fma_f32 v44, -v84, v160, v44
	ds_read_b128 v[110:113], v0 offset:3536
	s_waitcnt lgkmcnt(12)
	v_fma_f32 v45, -v84, v167, v45
	v_fma_f32 v46, -v84, v166, v46
	v_fma_f32 v47, -v84, v165, v47
	v_fma_f32 v48, -v84, v164, v48
	ds_read_b128 v[114:117], v0 offset:3520
	s_waitcnt lgkmcnt(12)
	v_fma_f32 v49, -v84, v171, v49
	v_fma_f32 v50, -v84, v170, v50
	v_fma_f32 v51, -v84, v169, v51
	v_fma_f32 v52, -v84, v168, v52
	ds_read_b128 v[118:121], v0 offset:3504
	s_waitcnt lgkmcnt(12)
	v_fma_f32 v53, -v84, v175, v53
	v_fma_f32 v54, -v84, v174, v54
	v_fma_f32 v55, -v84, v173, v55
	v_fma_f32 v56, -v84, v172, v56
	ds_read_b128 v[122:125], v0 offset:3488
	s_waitcnt lgkmcnt(12)
	v_fma_f32 v57, -v84, v179, v57
	v_fma_f32 v58, -v84, v178, v58
	v_fma_f32 v59, -v84, v177, v59
	v_fma_f32 v60, -v84, v176, v60
	ds_read_b128 v[126:129], v0 offset:3472
	s_waitcnt lgkmcnt(12)
	v_fma_f32 v61, -v84, v183, v61
	v_fma_f32 v62, -v84, v182, v62
	v_fma_f32 v63, -v84, v181, v63
	v_fma_f32 v64, -v84, v180, v64
	ds_read_b128 v[156:159], v0 offset:3456
	s_waitcnt lgkmcnt(12)
	v_fma_f32 v65, -v84, v187, v65
	v_fma_f32 v66, -v84, v186, v66
	v_fma_f32 v67, -v84, v185, v67
	v_fma_f32 v68, -v84, v184, v68
	ds_read_b128 v[160:163], v0 offset:3440
	s_waitcnt lgkmcnt(12)
	v_fma_f32 v73, -v84, v191, v73
	ds_read_b128 v[164:167], v0 offset:3408
	s_waitcnt lgkmcnt(12)
	v_fma_f32 v69, -v84, v93, v69
	v_fma_f32 v70, -v84, v92, v70
	v_fma_f32 v71, -v84, v91, v71
	v_fma_f32 v72, -v84, v90, v72
	v_fma_f32 v74, -v84, v190, v74
	v_fma_f32 v75, -v84, v189, v75
	v_fma_f32 v76, -v84, v188, v76
	ds_read_b128 v[168:171], v0 offset:3424
	ds_read_b128 v[172:175], v0 offset:3376
	s_waitcnt lgkmcnt(12)
	v_fma_f32 v77, -v84, v101, v77
	v_fma_f32 v78, -v84, v100, v78
	v_fma_f32 v79, -v84, v99, v79
	v_fma_f32 v80, -v84, v98, v80
	v_fma_f32 v81, -v84, v97, v81
	v_fma_f32 v82, -v84, v96, v82
	v_fma_f32 v83, -v84, v95, v83
	v_fma_f32 v84, -v84, v94, v84
	ds_read_b128 v[176:179], v0 offset:3392
	s_waitcnt lgkmcnt(12)
	v_fma_f32 v24, -v83, v105, v24
	v_fma_f32 v25, -v83, v104, v25
	v_fma_f32 v27, -v83, v103, v27
	v_fma_f32 v36, -v83, v102, v36
	ds_read_b128 v[180:183], v0 offset:3824
	s_waitcnt lgkmcnt(12)
	v_fma_f32 v37, -v83, v109, v37
	v_fma_f32 v38, -v83, v108, v38
	v_fma_f32 v39, -v83, v107, v39
	v_fma_f32 v40, -v83, v106, v40
	ds_read_b128 v[184:187], v0 offset:3808
	s_waitcnt lgkmcnt(12)
	v_fma_f32 v41, -v83, v113, v41
	v_fma_f32 v42, -v83, v112, v42
	v_fma_f32 v43, -v83, v111, v43
	v_fma_f32 v44, -v83, v110, v44
	ds_read_b128 v[188:191], v0 offset:3792
	s_waitcnt lgkmcnt(12)
	v_fma_f32 v45, -v83, v117, v45
	v_fma_f32 v46, -v83, v116, v46
	v_fma_f32 v47, -v83, v115, v47
	v_fma_f32 v48, -v83, v114, v48
	ds_read_b128 v[90:93], v0 offset:3776
	s_waitcnt lgkmcnt(12)
	v_fma_f32 v49, -v83, v121, v49
	v_fma_f32 v50, -v83, v120, v50
	v_fma_f32 v51, -v83, v119, v51
	v_fma_f32 v52, -v83, v118, v52
	ds_read_b128 v[94:97], v0 offset:3760
	s_waitcnt lgkmcnt(12)
	v_fma_f32 v53, -v83, v125, v53
	v_fma_f32 v54, -v83, v124, v54
	v_fma_f32 v55, -v83, v123, v55
	v_fma_f32 v56, -v83, v122, v56
	ds_read_b128 v[98:101], v0 offset:3744
	s_waitcnt lgkmcnt(12)
	v_fma_f32 v57, -v83, v129, v57
	v_fma_f32 v58, -v83, v128, v58
	v_fma_f32 v59, -v83, v127, v59
	v_fma_f32 v60, -v83, v126, v60
	ds_read_b128 v[102:105], v0 offset:3728
	s_waitcnt lgkmcnt(12)
	v_fma_f32 v61, -v83, v159, v61
	v_fma_f32 v62, -v83, v158, v62
	v_fma_f32 v63, -v83, v157, v63
	v_fma_f32 v64, -v83, v156, v64
	ds_read_b128 v[106:109], v0 offset:3712
	s_waitcnt lgkmcnt(12)
	v_fma_f32 v65, -v83, v163, v65
	v_fma_f32 v66, -v83, v162, v66
	v_fma_f32 v67, -v83, v161, v67
	v_fma_f32 v68, -v83, v160, v68
	ds_read_b128 v[110:113], v0 offset:3696
	s_waitcnt lgkmcnt(12)
	v_fma_f32 v73, -v83, v167, v73
	ds_read_b128 v[114:117], v0 offset:3664
	s_waitcnt lgkmcnt(12)
	v_fma_f32 v69, -v83, v171, v69
	v_fma_f32 v70, -v83, v170, v70
	v_fma_f32 v71, -v83, v169, v71
	v_fma_f32 v72, -v83, v168, v72
	v_fma_f32 v74, -v83, v166, v74
	v_fma_f32 v75, -v83, v165, v75
	v_fma_f32 v76, -v83, v164, v76
	ds_read_b128 v[118:121], v0 offset:3680
	ds_read_b128 v[122:125], v0 offset:3632
	s_waitcnt lgkmcnt(12)
; #define LAS __attribute__((address_space(3)))
; #define PIN16(o) asm volatile("" : "+v"(xr[o]), "+v"(xr[o + 1]), "+v"(xr[o + 2]), "+v"(xr[o + 3]), "+v"(xr[o + 4]), "+v"(xr[o + 5]), "+v"(xr[o + 6]), "+v"(xr[o + 7]), "+v"(xr[o + 8]), "+v"(xr[o + 9]), "+v"(xr[o + 10]), "+v"(xr[o + 11]), "+v"(xr[o + 12]), "+v"(xr[o + 13]), "+v"(xr[o + 14]), "+v"(xr[o + 15]) :: "memory")
; DI void gdn_prep_item(LAS unsigned char* lds, const Ctx& c, int l, int item) {
;     ...
; #pragma unroll
;         for (int j = 0; j < 63; ++j) {
;             const float xj = xr[j];
; #pragma unroll
;             for (int i4 = (j + 1) / 4; i4 < 16; ++i4) { const f32x4 Lv = *(const LAS f32x4*)(Lb + j * 64 + 4 * i4);
; #pragma unroll
;                 for (int q = 0; q < 4; ++q) xr[4 * i4 + q] -= Lv[q] * xj; }
;     ...
;             PIN16(0); PIN16(16); PIN16(32); PIN16(48);
;         }
	v_fma_f32 v77, -v83, v179, v77
	v_fma_f32 v78, -v83, v178, v78
	v_fma_f32 v79, -v83, v177, v79
	v_fma_f32 v80, -v83, v176, v80
	v_fma_f32 v81, -v83, v175, v81
	v_fma_f32 v82, -v83, v174, v82
	v_fma_f32 v85, -v83, v173, v83
	v_fma_f32 v83, -v83, v172, v84
	ds_read_b128 v[126:129], v0 offset:3648
	s_waitcnt lgkmcnt(12)
	v_fma_f32 v84, -v82, v183, v24
	v_fma_f32 v86, -v82, v182, v25
	v_fma_f32 v27, -v82, v181, v27
	v_fma_f32 v36, -v82, v180, v36
	ds_read_b128 v[156:159], v0 offset:4080
	s_waitcnt lgkmcnt(12)
	v_fma_f32 v37, -v82, v187, v37
	v_fma_f32 v38, -v82, v186, v38
	v_fma_f32 v39, -v82, v185, v39
	v_fma_f32 v40, -v82, v184, v40
	ds_read_b128 v[160:163], v0 offset:4064
	s_waitcnt lgkmcnt(12)
	v_fma_f32 v41, -v82, v191, v41
	v_fma_f32 v42, -v82, v190, v42
	v_fma_f32 v43, -v82, v189, v43
	v_fma_f32 v44, -v82, v188, v44
	ds_read_b128 v[164:167], v0 offset:4048
	s_waitcnt lgkmcnt(12)
	v_fma_f32 v45, -v82, v93, v45
	v_fma_f32 v46, -v82, v92, v46
	v_fma_f32 v47, -v82, v91, v47
	v_fma_f32 v48, -v82, v90, v48
	ds_read_b128 v[168:171], v0 offset:4032
	s_waitcnt lgkmcnt(12)
	v_fma_f32 v49, -v82, v97, v49
	v_fma_f32 v50, -v82, v96, v50
	v_fma_f32 v51, -v82, v95, v51
	v_fma_f32 v52, -v82, v94, v52
	ds_read_b128 v[172:175], v0 offset:4016
	s_waitcnt lgkmcnt(12)
	v_fma_f32 v53, -v82, v101, v53
	v_fma_f32 v54, -v82, v100, v54
	v_fma_f32 v55, -v82, v99, v55
	v_fma_f32 v56, -v82, v98, v56
	ds_read_b128 v[176:179], v0 offset:4000
	s_waitcnt lgkmcnt(12)
	v_fma_f32 v57, -v82, v105, v57
	v_fma_f32 v58, -v82, v104, v58
	v_fma_f32 v59, -v82, v103, v59
	v_fma_f32 v60, -v82, v102, v60
	ds_read_b128 v[180:183], v0 offset:3984
	s_waitcnt lgkmcnt(12)
	v_fma_f32 v61, -v82, v109, v61
	v_fma_f32 v62, -v82, v108, v62
	v_fma_f32 v63, -v82, v107, v63
	v_fma_f32 v64, -v82, v106, v64
	ds_read_b128 v[184:187], v0 offset:3968
	s_waitcnt lgkmcnt(12)
	v_fma_f32 v65, -v82, v113, v65
	v_fma_f32 v66, -v82, v112, v66
	v_fma_f32 v67, -v82, v111, v67
	v_fma_f32 v68, -v82, v110, v68
	ds_read_b128 v[188:191], v0 offset:3936
	s_waitcnt lgkmcnt(12)
	v_fma_f32 v75, -v82, v115, v75
	v_fma_f32 v76, -v82, v114, v76
	ds_read_b128 v[90:93], v0 offset:3952
	ds_read_b128 v[94:97], v0 offset:3904
	s_waitcnt lgkmcnt(12)
	v_fma_f32 v14, -v82, v125, v81
	v_fma_f32 v15, -v82, v124, v82
	v_fma_f32 v16, -v82, v123, v85
	v_fma_f32 v17, -v82, v122, v83
	v_fma_f32 v69, -v82, v121, v69
	v_fma_f32 v70, -v82, v120, v70
	v_fma_f32 v71, -v82, v119, v71
	v_fma_f32 v72, -v82, v118, v72
	v_fma_f32 v73, -v82, v117, v73
	v_fma_f32 v74, -v82, v116, v74
	ds_read_b128 v[98:101], v0 offset:3920
	s_waitcnt lgkmcnt(12)
	v_fma_f32 v77, -v82, v129, v77
	v_fma_f32 v78, -v82, v128, v78
	v_fma_f32 v79, -v82, v127, v79
	v_fma_f32 v80, -v82, v126, v80
	ds_read_b128 v[102:105], v0 offset:4336
	s_waitcnt lgkmcnt(12)
	v_fma_f32 v81, -v14, v159, v84
	v_fma_f32 v82, -v14, v158, v86
	v_fma_f32 v27, -v14, v157, v27
	v_fma_f32 v36, -v14, v156, v36
	ds_read_b128 v[106:109], v0 offset:4320
	s_waitcnt lgkmcnt(12)
	v_fma_f32 v37, -v14, v163, v37
	v_fma_f32 v38, -v14, v162, v38
	v_fma_f32 v39, -v14, v161, v39
	v_fma_f32 v40, -v14, v160, v40
	ds_read_b128 v[110:113], v0 offset:4304
	s_waitcnt lgkmcnt(12)
	v_fma_f32 v41, -v14, v167, v41
	v_fma_f32 v42, -v14, v166, v42
	v_fma_f32 v43, -v14, v165, v43
	v_fma_f32 v44, -v14, v164, v44
	ds_read_b128 v[114:117], v0 offset:4288
	s_waitcnt lgkmcnt(12)
	v_fma_f32 v45, -v14, v171, v45
	v_fma_f32 v46, -v14, v170, v46
	v_fma_f32 v47, -v14, v169, v47
	v_fma_f32 v48, -v14, v168, v48
	ds_read_b128 v[118:121], v0 offset:4272
	s_waitcnt lgkmcnt(12)
	v_fma_f32 v49, -v14, v175, v49
	v_fma_f32 v50, -v14, v174, v50
	v_fma_f32 v51, -v14, v173, v51
	v_fma_f32 v52, -v14, v172, v52
	ds_read_b128 v[122:125], v0 offset:4256
	s_waitcnt lgkmcnt(12)
	v_fma_f32 v53, -v14, v179, v53
	v_fma_f32 v54, -v14, v178, v54
	v_fma_f32 v55, -v14, v177, v55
	v_fma_f32 v56, -v14, v176, v56
	ds_read_b128 v[126:129], v0 offset:4240
	s_waitcnt lgkmcnt(12)
	v_fma_f32 v57, -v14, v183, v57
	v_fma_f32 v58, -v14, v182, v58
	v_fma_f32 v59, -v14, v181, v59
	v_fma_f32 v60, -v14, v180, v60
	ds_read_b128 v[156:159], v0 offset:4224
	s_waitcnt lgkmcnt(12)
	v_fma_f32 v61, -v14, v187, v61
	v_fma_f32 v62, -v14, v186, v62
	v_fma_f32 v63, -v14, v185, v63
	v_fma_f32 v64, -v14, v184, v64
	ds_read_b128 v[160:163], v0 offset:4192
	s_waitcnt lgkmcnt(12)
	v_fma_f32 v69, -v14, v191, v69
	ds_read_b128 v[164:167], v0 offset:4208
	s_waitcnt lgkmcnt(12)
	v_fma_f32 v65, -v14, v93, v65
	v_fma_f32 v66, -v14, v92, v66
	v_fma_f32 v67, -v14, v91, v67
	v_fma_f32 v68, -v14, v90, v68
	v_fma_f32 v70, -v14, v190, v70
	v_fma_f32 v71, -v14, v189, v71
	v_fma_f32 v72, -v14, v188, v72
	ds_read_b128 v[168:171], v0 offset:4160
	ds_read_b128 v[172:175], v0 offset:4176
	s_waitcnt lgkmcnt(12)
	v_fma_f32 v73, -v14, v101, v73
	v_fma_f32 v74, -v14, v100, v74
	v_fma_f32 v75, -v14, v99, v75
	v_fma_f32 v76, -v14, v98, v76
	v_fma_f32 v77, -v14, v97, v77
	v_fma_f32 v78, -v14, v96, v78
	v_fma_f32 v79, -v14, v95, v79
	v_fma_f32 v80, -v14, v94, v80
	ds_read_b128 v[176:179], v0 offset:4592
	s_waitcnt lgkmcnt(12)
	v_fma_f32 v81, -v80, v105, v81
	v_fma_f32 v82, -v80, v104, v82
	v_fma_f32 v27, -v80, v103, v27
	v_fma_f32 v36, -v80, v102, v36
	ds_read_b128 v[180:183], v0 offset:4576
	s_waitcnt lgkmcnt(12)
	v_fma_f32 v37, -v80, v109, v37
	v_fma_f32 v38, -v80, v108, v38
	v_fma_f32 v39, -v80, v107, v39
	v_fma_f32 v40, -v80, v106, v40
	ds_read_b128 v[184:187], v0 offset:4560
	s_waitcnt lgkmcnt(12)
	v_fma_f32 v41, -v80, v113, v41
	v_fma_f32 v42, -v80, v112, v42
	v_fma_f32 v43, -v80, v111, v43
	v_fma_f32 v44, -v80, v110, v44
	ds_read_b128 v[188:191], v0 offset:4544
	s_waitcnt lgkmcnt(12)
; #define LAS __attribute__((address_space(3)))
; #define PIN16(o) asm volatile("" : "+v"(xr[o]), "+v"(xr[o + 1]), "+v"(xr[o + 2]), "+v"(xr[o + 3]), "+v"(xr[o + 4]), "+v"(xr[o + 5]), "+v"(xr[o + 6]), "+v"(xr[o + 7]), "+v"(xr[o + 8]), "+v"(xr[o + 9]), "+v"(xr[o + 10]), "+v"(xr[o + 11]), "+v"(xr[o + 12]), "+v"(xr[o + 13]), "+v"(xr[o + 14]), "+v"(xr[o + 15]) :: "memory")
; DI void gdn_prep_item(LAS unsigned char* lds, const Ctx& c, int l, int item) {
;     ...
; #pragma unroll
;         for (int j = 0; j < 63; ++j) {
;             const float xj = xr[j];
; #pragma unroll
;             for (int i4 = (j + 1) / 4; i4 < 16; ++i4) { const f32x4 Lv = *(const LAS f32x4*)(Lb + j * 64 + 4 * i4);
; #pragma unroll
;                 for (int q = 0; q < 4; ++q) xr[4 * i4 + q] -= Lv[q] * xj; }
;     ...
;             PIN16(0); PIN16(16); PIN16(32); PIN16(48);
;         }
	v_fma_f32 v45, -v80, v117, v45
	v_fma_f32 v46, -v80, v116, v46
	v_fma_f32 v47, -v80, v115, v47
	v_fma_f32 v48, -v80, v114, v48
	ds_read_b128 v[90:93], v0 offset:4528
	s_waitcnt lgkmcnt(12)
	v_fma_f32 v49, -v80, v121, v49
	v_fma_f32 v50, -v80, v120, v50
	v_fma_f32 v51, -v80, v119, v51
	v_fma_f32 v52, -v80, v118, v52
	ds_read_b128 v[94:97], v0 offset:4512
	s_waitcnt lgkmcnt(12)
	v_fma_f32 v53, -v80, v125, v53
	v_fma_f32 v54, -v80, v124, v54
	v_fma_f32 v55, -v80, v123, v55
	v_fma_f32 v56, -v80, v122, v56
	ds_read_b128 v[98:101], v0 offset:4496
	s_waitcnt lgkmcnt(12)
	v_fma_f32 v57, -v80, v129, v57
	v_fma_f32 v58, -v80, v128, v58
	v_fma_f32 v59, -v80, v127, v59
	v_fma_f32 v60, -v80, v126, v60
	ds_read_b128 v[102:105], v0 offset:4480
	s_waitcnt lgkmcnt(12)
	v_fma_f32 v61, -v80, v159, v61
	v_fma_f32 v62, -v80, v158, v62
	v_fma_f32 v63, -v80, v157, v63
	v_fma_f32 v64, -v80, v156, v64
	ds_read_b128 v[106:109], v0 offset:4448
	s_waitcnt lgkmcnt(12)
	v_fma_f32 v69, -v80, v163, v69
	ds_read_b128 v[110:113], v0 offset:4464
	s_waitcnt lgkmcnt(12)
	v_fma_f32 v65, -v80, v167, v65
	v_fma_f32 v66, -v80, v166, v66
	v_fma_f32 v67, -v80, v165, v67
	v_fma_f32 v68, -v80, v164, v68
	v_fma_f32 v70, -v80, v162, v70
	v_fma_f32 v71, -v80, v161, v71
	v_fma_f32 v72, -v80, v160, v72
	ds_read_b128 v[114:117], v0 offset:4416
	ds_read_b128 v[118:121], v0 offset:4432
	s_waitcnt lgkmcnt(12)
	v_fma_f32 v73, -v80, v175, v73
	v_fma_f32 v74, -v80, v174, v74
	v_fma_f32 v75, -v80, v173, v75
	v_fma_f32 v76, -v80, v172, v76
	v_fma_f32 v77, -v80, v171, v77
	v_fma_f32 v78, -v80, v170, v78
	v_fma_f32 v79, -v80, v169, v79
	v_fma_f32 v80, -v80, v168, v80
	ds_read_b128 v[122:125], v0 offset:4848
	s_waitcnt lgkmcnt(12)
	v_fma_f32 v81, -v79, v179, v81
	v_fma_f32 v82, -v79, v178, v82
	v_fma_f32 v27, -v79, v177, v27
	v_fma_f32 v36, -v79, v176, v36
	ds_read_b128 v[126:129], v0 offset:4832
	s_waitcnt lgkmcnt(12)
	v_fma_f32 v37, -v79, v183, v37
	v_fma_f32 v38, -v79, v182, v38
	v_fma_f32 v39, -v79, v181, v39
	v_fma_f32 v40, -v79, v180, v40
	ds_read_b128 v[156:159], v0 offset:4816
	s_waitcnt lgkmcnt(12)
	v_fma_f32 v41, -v79, v187, v41
	v_fma_f32 v42, -v79, v186, v42
	v_fma_f32 v43, -v79, v185, v43
	v_fma_f32 v44, -v79, v184, v44
	ds_read_b128 v[160:163], v0 offset:4800
	s_waitcnt lgkmcnt(12)
	v_fma_f32 v45, -v79, v191, v45
	v_fma_f32 v46, -v79, v190, v46
	v_fma_f32 v47, -v79, v189, v47
	v_fma_f32 v48, -v79, v188, v48
	ds_read_b128 v[164:167], v0 offset:4784
	s_waitcnt lgkmcnt(12)
	v_fma_f32 v49, -v79, v93, v49
	v_fma_f32 v50, -v79, v92, v50
	v_fma_f32 v51, -v79, v91, v51
	v_fma_f32 v52, -v79, v90, v52
	ds_read_b128 v[168:171], v0 offset:4768
	s_waitcnt lgkmcnt(12)
	v_fma_f32 v53, -v79, v97, v53
	v_fma_f32 v54, -v79, v96, v54
	v_fma_f32 v55, -v79, v95, v55
	v_fma_f32 v56, -v79, v94, v56
	ds_read_b128 v[172:175], v0 offset:4752
	s_waitcnt lgkmcnt(12)
	v_fma_f32 v57, -v79, v101, v57
	v_fma_f32 v58, -v79, v100, v58
	v_fma_f32 v59, -v79, v99, v59
	v_fma_f32 v60, -v79, v98, v60
	ds_read_b128 v[176:179], v0 offset:4736
	s_waitcnt lgkmcnt(12)
	v_fma_f32 v61, -v79, v105, v61
	v_fma_f32 v62, -v79, v104, v62
	v_fma_f32 v63, -v79, v103, v63
	v_fma_f32 v64, -v79, v102, v64
	ds_read_b128 v[180:183], v0 offset:4704
	s_waitcnt lgkmcnt(12)
	v_fma_f32 v69, -v79, v109, v69
	ds_read_b128 v[184:187], v0 offset:4720
	s_waitcnt lgkmcnt(12)
	v_fma_f32 v65, -v79, v113, v65
	v_fma_f32 v66, -v79, v112, v66
	v_fma_f32 v67, -v79, v111, v67
	v_fma_f32 v68, -v79, v110, v68
	v_fma_f32 v70, -v79, v108, v70
	v_fma_f32 v71, -v79, v107, v71
	v_fma_f32 v72, -v79, v106, v72
	ds_read_b128 v[188:191], v0 offset:4672
	ds_read_b128 v[90:93], v0 offset:4688
	s_waitcnt lgkmcnt(12)
	v_fma_f32 v73, -v79, v121, v73
	v_fma_f32 v74, -v79, v120, v74
	v_fma_f32 v75, -v79, v119, v75
	v_fma_f32 v76, -v79, v118, v76
	v_fma_f32 v77, -v79, v117, v77
	v_fma_f32 v78, -v79, v116, v78
	v_fma_f32 v83, -v79, v115, v79
	v_fma_f32 v79, -v79, v114, v80
	ds_read_b128 v[94:97], v0 offset:5104
	s_waitcnt lgkmcnt(12)
	v_fma_f32 v80, -v78, v125, v81
	v_fma_f32 v81, -v78, v124, v82
	v_fma_f32 v27, -v78, v123, v27
	v_fma_f32 v36, -v78, v122, v36
	ds_read_b128 v[98:101], v0 offset:5088
	s_waitcnt lgkmcnt(12)
	v_fma_f32 v37, -v78, v129, v37
	v_fma_f32 v38, -v78, v128, v38
	v_fma_f32 v39, -v78, v127, v39
	v_fma_f32 v40, -v78, v126, v40
	ds_read_b128 v[102:105], v0 offset:5072
	s_waitcnt lgkmcnt(12)
	v_fma_f32 v41, -v78, v159, v41
	v_fma_f32 v42, -v78, v158, v42
	v_fma_f32 v43, -v78, v157, v43
	v_fma_f32 v44, -v78, v156, v44
	ds_read_b128 v[106:109], v0 offset:5056
	s_waitcnt lgkmcnt(12)
	v_fma_f32 v45, -v78, v163, v45
	v_fma_f32 v46, -v78, v162, v46
	v_fma_f32 v47, -v78, v161, v47
	v_fma_f32 v48, -v78, v160, v48
	ds_read_b128 v[110:113], v0 offset:5040
	s_waitcnt lgkmcnt(12)
	v_fma_f32 v49, -v78, v167, v49
	v_fma_f32 v50, -v78, v166, v50
	v_fma_f32 v51, -v78, v165, v51
	v_fma_f32 v52, -v78, v164, v52
	ds_read_b128 v[114:117], v0 offset:5024
	s_waitcnt lgkmcnt(12)
	v_fma_f32 v53, -v78, v171, v53
	v_fma_f32 v54, -v78, v170, v54
	v_fma_f32 v55, -v78, v169, v55
	v_fma_f32 v56, -v78, v168, v56
	ds_read_b128 v[118:121], v0 offset:5008
	s_waitcnt lgkmcnt(12)
	v_fma_f32 v57, -v78, v175, v57
	v_fma_f32 v58, -v78, v174, v58
	v_fma_f32 v59, -v78, v173, v59
	v_fma_f32 v60, -v78, v172, v60
	ds_read_b128 v[122:125], v0 offset:4976
	s_waitcnt lgkmcnt(12)
	v_fma_f32 v61, -v78, v179, v61
	v_fma_f32 v62, -v78, v178, v62
	v_fma_f32 v63, -v78, v177, v63
	v_fma_f32 v64, -v78, v176, v64
	ds_read_b128 v[126:129], v0 offset:4992
	s_waitcnt lgkmcnt(12)
	v_fma_f32 v69, -v78, v183, v69
	ds_read_b128 v[156:159], v0 offset:4944
	s_waitcnt lgkmcnt(12)
; #define LAS __attribute__((address_space(3)))
; #define PIN16(o) asm volatile("" : "+v"(xr[o]), "+v"(xr[o + 1]), "+v"(xr[o + 2]), "+v"(xr[o + 3]), "+v"(xr[o + 4]), "+v"(xr[o + 5]), "+v"(xr[o + 6]), "+v"(xr[o + 7]), "+v"(xr[o + 8]), "+v"(xr[o + 9]), "+v"(xr[o + 10]), "+v"(xr[o + 11]), "+v"(xr[o + 12]), "+v"(xr[o + 13]), "+v"(xr[o + 14]), "+v"(xr[o + 15]) :: "memory")
; DI void gdn_prep_item(LAS unsigned char* lds, const Ctx& c, int l, int item) {
;     ...
; #pragma unroll
;         for (int j = 0; j < 63; ++j) {
;             const float xj = xr[j];
; #pragma unroll
;             for (int i4 = (j + 1) / 4; i4 < 16; ++i4) { const f32x4 Lv = *(const LAS f32x4*)(Lb + j * 64 + 4 * i4);
; #pragma unroll
;                 for (int q = 0; q < 4; ++q) xr[4 * i4 + q] -= Lv[q] * xj; }
;     ...
;             PIN16(0); PIN16(16); PIN16(32); PIN16(48);
;         }
	v_fma_f32 v65, -v78, v187, v65
	v_fma_f32 v66, -v78, v186, v66
	v_fma_f32 v67, -v78, v185, v67
	v_fma_f32 v68, -v78, v184, v68
	v_fma_f32 v70, -v78, v182, v70
	v_fma_f32 v71, -v78, v181, v71
	v_fma_f32 v72, -v78, v180, v72
	ds_read_b128 v[160:163], v0 offset:4960
	ds_read_b128 v[164:167], v0 offset:5360
	s_waitcnt lgkmcnt(12)
	v_fma_f32 v73, -v78, v93, v73
	v_fma_f32 v74, -v78, v92, v74
	v_fma_f32 v75, -v78, v91, v75
	v_fma_f32 v76, -v78, v90, v76
	v_fma_f32 v18, -v78, v191, v77
	v_fma_f32 v19, -v78, v190, v78
	v_fma_f32 v20, -v78, v189, v83
	v_fma_f32 v21, -v78, v188, v79
	ds_read_b128 v[168:171], v0 offset:5344
	s_waitcnt lgkmcnt(12)
	v_fma_f32 v77, -v18, v97, v80
	v_fma_f32 v78, -v18, v96, v81
	v_fma_f32 v27, -v18, v95, v27
	v_fma_f32 v79, -v18, v94, v36
	ds_read_b128 v[172:175], v0 offset:5328
	s_waitcnt lgkmcnt(12)
	v_fma_f32 v80, -v18, v101, v37
	v_fma_f32 v81, -v18, v100, v38
	v_fma_f32 v82, -v18, v99, v39
	v_fma_f32 v40, -v18, v98, v40
	ds_read_b128 v[176:179], v0 offset:5312
	s_waitcnt lgkmcnt(12)
	v_fma_f32 v41, -v18, v105, v41
	v_fma_f32 v42, -v18, v104, v42
	v_fma_f32 v43, -v18, v103, v43
	v_fma_f32 v44, -v18, v102, v44
	ds_read_b128 v[180:183], v0 offset:5296
	s_waitcnt lgkmcnt(12)
	v_fma_f32 v45, -v18, v109, v45
	v_fma_f32 v46, -v18, v108, v46
	v_fma_f32 v47, -v18, v107, v47
	v_fma_f32 v48, -v18, v106, v48
	ds_read_b128 v[184:187], v0 offset:5280
	s_waitcnt lgkmcnt(12)
	v_fma_f32 v49, -v18, v113, v49
	v_fma_f32 v50, -v18, v112, v50
	v_fma_f32 v51, -v18, v111, v51
	v_fma_f32 v52, -v18, v110, v52
	ds_read_b128 v[188:191], v0 offset:5264
	s_waitcnt lgkmcnt(12)
	v_fma_f32 v53, -v18, v117, v53
	v_fma_f32 v54, -v18, v116, v54
	v_fma_f32 v55, -v18, v115, v55
	v_fma_f32 v56, -v18, v114, v56
	ds_read_b128 v[90:93], v0 offset:5232
	s_waitcnt lgkmcnt(12)
	v_fma_f32 v57, -v18, v121, v57
	v_fma_f32 v58, -v18, v120, v58
	v_fma_f32 v59, -v18, v119, v59
	v_fma_f32 v60, -v18, v118, v60
	ds_read_b128 v[94:97], v0 offset:5248
	s_waitcnt lgkmcnt(12)
	v_fma_f32 v65, -v18, v125, v65
	v_fma_f32 v66, -v18, v124, v66
	v_fma_f32 v67, -v18, v123, v67
	v_fma_f32 v68, -v18, v122, v68
	ds_read_b128 v[98:101], v0 offset:5200
	ds_read_b128 v[102:105], v0 offset:5216
	ds_read_b128 v[106:109], v0 offset:5616
	s_waitcnt lgkmcnt(12)
	v_fma_f32 v69, -v18, v163, v69
	v_fma_f32 v70, -v18, v162, v70
	v_fma_f32 v71, -v18, v161, v71
	v_fma_f32 v72, -v18, v160, v72
	v_fma_f32 v73, -v18, v159, v73
	v_fma_f32 v74, -v18, v158, v74
	v_fma_f32 v75, -v18, v157, v75
	v_fma_f32 v76, -v18, v156, v76
	v_fma_f32 v61, -v18, v129, v61
	v_fma_f32 v62, -v18, v128, v62
	v_fma_f32 v63, -v18, v127, v63
	v_fma_f32 v64, -v18, v126, v64
	ds_read_b128 v[110:113], v0 offset:5600
	s_waitcnt lgkmcnt(12)
	v_fma_f32 v77, -v76, v167, v77
	v_fma_f32 v78, -v76, v166, v78
	v_fma_f32 v27, -v76, v165, v27
	v_fma_f32 v79, -v76, v164, v79
	ds_read_b128 v[114:117], v0 offset:5584
	s_waitcnt lgkmcnt(12)
	v_fma_f32 v80, -v76, v171, v80
	v_fma_f32 v81, -v76, v170, v81
	v_fma_f32 v82, -v76, v169, v82
	v_fma_f32 v40, -v76, v168, v40
	ds_read_b128 v[118:121], v0 offset:5568
	s_waitcnt lgkmcnt(12)
	v_fma_f32 v41, -v76, v175, v41
	v_fma_f32 v42, -v76, v174, v42
	v_fma_f32 v43, -v76, v173, v43
	v_fma_f32 v44, -v76, v172, v44
	ds_read_b128 v[122:125], v0 offset:5552
	s_waitcnt lgkmcnt(12)
	v_fma_f32 v45, -v76, v179, v45
	v_fma_f32 v46, -v76, v178, v46
	v_fma_f32 v47, -v76, v177, v47
	v_fma_f32 v48, -v76, v176, v48
	ds_read_b128 v[126:129], v0 offset:5536
	s_waitcnt lgkmcnt(12)
	v_fma_f32 v49, -v76, v183, v49
	v_fma_f32 v50, -v76, v182, v50
	v_fma_f32 v51, -v76, v181, v51
	v_fma_f32 v52, -v76, v180, v52
	ds_read_b128 v[156:159], v0 offset:5520
	s_waitcnt lgkmcnt(12)
	v_fma_f32 v53, -v76, v187, v53
	v_fma_f32 v54, -v76, v186, v54
	v_fma_f32 v55, -v76, v185, v55
	v_fma_f32 v56, -v76, v184, v56
	ds_read_b128 v[160:163], v0 offset:5488
	s_waitcnt lgkmcnt(12)
	v_fma_f32 v57, -v76, v191, v57
	v_fma_f32 v58, -v76, v190, v58
	v_fma_f32 v59, -v76, v189, v59
	v_fma_f32 v60, -v76, v188, v60
	ds_read_b128 v[164:167], v0 offset:5504
	s_waitcnt lgkmcnt(12)
	v_fma_f32 v65, -v76, v93, v65
	ds_read_b128 v[168:171], v0 offset:5456
	s_waitcnt lgkmcnt(12)
	v_fma_f32 v61, -v76, v97, v61
	v_fma_f32 v62, -v76, v96, v62
	v_fma_f32 v63, -v76, v95, v63
	v_fma_f32 v64, -v76, v94, v64
	v_fma_f32 v66, -v76, v92, v66
	v_fma_f32 v67, -v76, v91, v67
	v_fma_f32 v68, -v76, v90, v68
	ds_read_b128 v[172:175], v0 offset:5472
	ds_read_b128 v[176:179], v0 offset:5872
	s_waitcnt lgkmcnt(12)
	v_fma_f32 v69, -v76, v105, v69
	v_fma_f32 v70, -v76, v104, v70
	v_fma_f32 v71, -v76, v103, v71
	v_fma_f32 v72, -v76, v102, v72
	v_fma_f32 v73, -v76, v101, v73
	v_fma_f32 v74, -v76, v100, v74
	v_fma_f32 v75, -v76, v99, v75
	v_fma_f32 v76, -v76, v98, v76
	ds_read_b128 v[180:183], v0 offset:5856
	s_waitcnt lgkmcnt(12)
	v_fma_f32 v77, -v75, v109, v77
	v_fma_f32 v78, -v75, v108, v78
	v_fma_f32 v27, -v75, v107, v27
	v_fma_f32 v79, -v75, v106, v79
	ds_read_b128 v[184:187], v0 offset:5840
	s_waitcnt lgkmcnt(12)
	v_fma_f32 v80, -v75, v113, v80
	v_fma_f32 v81, -v75, v112, v81
	v_fma_f32 v82, -v75, v111, v82
	v_fma_f32 v40, -v75, v110, v40
	ds_read_b128 v[188:191], v0 offset:5824
	s_waitcnt lgkmcnt(12)
	v_fma_f32 v41, -v75, v117, v41
	v_fma_f32 v42, -v75, v116, v42
	v_fma_f32 v43, -v75, v115, v43
	v_fma_f32 v44, -v75, v114, v44
	ds_read_b128 v[90:93], v0 offset:5808
	s_waitcnt lgkmcnt(12)
	v_fma_f32 v45, -v75, v121, v45
	v_fma_f32 v46, -v75, v120, v46
	v_fma_f32 v47, -v75, v119, v47
	v_fma_f32 v48, -v75, v118, v48
	ds_read_b128 v[94:97], v0 offset:5792
	s_waitcnt lgkmcnt(12)
	v_fma_f32 v49, -v75, v125, v49
	v_fma_f32 v50, -v75, v124, v50
	v_fma_f32 v51, -v75, v123, v51
	v_fma_f32 v52, -v75, v122, v52
	ds_read_b128 v[98:101], v0 offset:5776
	s_waitcnt lgkmcnt(12)
; #define LAS __attribute__((address_space(3)))
; #define PIN16(o) asm volatile("" : "+v"(xr[o]), "+v"(xr[o + 1]), "+v"(xr[o + 2]), "+v"(xr[o + 3]), "+v"(xr[o + 4]), "+v"(xr[o + 5]), "+v"(xr[o + 6]), "+v"(xr[o + 7]), "+v"(xr[o + 8]), "+v"(xr[o + 9]), "+v"(xr[o + 10]), "+v"(xr[o + 11]), "+v"(xr[o + 12]), "+v"(xr[o + 13]), "+v"(xr[o + 14]), "+v"(xr[o + 15]) :: "memory")
; DI void gdn_prep_item(LAS unsigned char* lds, const Ctx& c, int l, int item) {
;     ...
; #pragma unroll
;         for (int j = 0; j < 63; ++j) {
;             const float xj = xr[j];
; #pragma unroll
;             for (int i4 = (j + 1) / 4; i4 < 16; ++i4) { const f32x4 Lv = *(const LAS f32x4*)(Lb + j * 64 + 4 * i4);
; #pragma unroll
;                 for (int q = 0; q < 4; ++q) xr[4 * i4 + q] -= Lv[q] * xj; }
;     ...
;             PIN16(0); PIN16(16); PIN16(32); PIN16(48);
;         }
	v_fma_f32 v53, -v75, v129, v53
	v_fma_f32 v54, -v75, v128, v54
	v_fma_f32 v55, -v75, v127, v55
	v_fma_f32 v56, -v75, v126, v56
	ds_read_b128 v[102:105], v0 offset:5744
	s_waitcnt lgkmcnt(12)
	v_fma_f32 v57, -v75, v159, v57
	v_fma_f32 v58, -v75, v158, v58
	v_fma_f32 v59, -v75, v157, v59
	v_fma_f32 v60, -v75, v156, v60
	ds_read_b128 v[106:109], v0 offset:5760
	s_waitcnt lgkmcnt(12)
	v_fma_f32 v65, -v75, v163, v65
	ds_read_b128 v[110:113], v0 offset:5712
	s_waitcnt lgkmcnt(12)
	v_fma_f32 v61, -v75, v167, v61
	v_fma_f32 v62, -v75, v166, v62
	v_fma_f32 v63, -v75, v165, v63
	v_fma_f32 v64, -v75, v164, v64
	v_fma_f32 v66, -v75, v162, v66
	v_fma_f32 v67, -v75, v161, v67
	v_fma_f32 v68, -v75, v160, v68
	ds_read_b128 v[114:117], v0 offset:5728
	ds_read_b128 v[118:121], v0 offset:6128
	s_waitcnt lgkmcnt(12)
	v_fma_f32 v69, -v75, v175, v69
	v_fma_f32 v70, -v75, v174, v70
	v_fma_f32 v71, -v75, v173, v71
	v_fma_f32 v72, -v75, v172, v72
	v_fma_f32 v73, -v75, v171, v73
	v_fma_f32 v74, -v75, v170, v74
	v_fma_f32 v83, -v75, v169, v75
	v_fma_f32 v75, -v75, v168, v76
	ds_read_b128 v[122:125], v0 offset:6112
	s_waitcnt lgkmcnt(12)
	v_fma_f32 v76, -v74, v179, v77
	v_fma_f32 v77, -v74, v178, v78
	v_fma_f32 v27, -v74, v177, v27
	v_fma_f32 v78, -v74, v176, v79
	ds_read_b128 v[126:129], v0 offset:6096
	s_waitcnt lgkmcnt(12)
	v_fma_f32 v79, -v74, v183, v80
	v_fma_f32 v80, -v74, v182, v81
	v_fma_f32 v81, -v74, v181, v82
	v_fma_f32 v40, -v74, v180, v40
	ds_read_b128 v[156:159], v0 offset:6080
	s_waitcnt lgkmcnt(12)
	v_fma_f32 v41, -v74, v187, v41
	v_fma_f32 v42, -v74, v186, v42
	v_fma_f32 v43, -v74, v185, v43
	v_fma_f32 v44, -v74, v184, v44
	ds_read_b128 v[160:163], v0 offset:6064
	s_waitcnt lgkmcnt(12)
	v_fma_f32 v45, -v74, v191, v45
	v_fma_f32 v46, -v74, v190, v46
	v_fma_f32 v47, -v74, v189, v47
	v_fma_f32 v48, -v74, v188, v48
	ds_read_b128 v[164:167], v0 offset:6048
	s_waitcnt lgkmcnt(12)
	v_fma_f32 v49, -v74, v93, v49
	v_fma_f32 v50, -v74, v92, v50
	v_fma_f32 v51, -v74, v91, v51
	v_fma_f32 v52, -v74, v90, v52
	ds_read_b128 v[168:171], v0 offset:6016
	s_waitcnt lgkmcnt(12)
	v_fma_f32 v53, -v74, v97, v53
	v_fma_f32 v54, -v74, v96, v54
	v_fma_f32 v55, -v74, v95, v55
	v_fma_f32 v56, -v74, v94, v56
	ds_read_b128 v[172:175], v0 offset:6032
	s_waitcnt lgkmcnt(12)
	v_fma_f32 v57, -v74, v101, v57
	v_fma_f32 v58, -v74, v100, v58
	v_fma_f32 v59, -v74, v99, v59
	v_fma_f32 v60, -v74, v98, v60
	ds_read_b128 v[176:179], v0 offset:5984
	s_waitcnt lgkmcnt(12)
	v_fma_f32 v65, -v74, v105, v65
	v_fma_f32 v66, -v74, v104, v66
	v_fma_f32 v67, -v74, v103, v67
	v_fma_f32 v68, -v74, v102, v68
	ds_read_b128 v[180:183], v0 offset:6000
	ds_read_b128 v[184:187], v0 offset:6384
	ds_read_b128 v[188:191], v0 offset:6368
	s_waitcnt lgkmcnt(12)
	v_fma_f32 v69, -v74, v117, v69
	v_fma_f32 v70, -v74, v116, v70
	v_fma_f32 v71, -v74, v115, v71
	v_fma_f32 v72, -v74, v114, v72
	v_fma_f32 v22, -v74, v113, v73
	v_fma_f32 v23, -v74, v112, v74
	v_fma_f32 v24, -v74, v111, v83
	v_fma_f32 v25, -v74, v110, v75
	v_fma_f32 v61, -v74, v109, v61
	v_fma_f32 v62, -v74, v108, v62
	v_fma_f32 v63, -v74, v107, v63
	v_fma_f32 v64, -v74, v106, v64
	ds_read_b128 v[90:93], v0 offset:6352
	s_waitcnt lgkmcnt(12)
	v_fma_f32 v73, -v22, v121, v76
	v_fma_f32 v74, -v22, v120, v77
	v_fma_f32 v27, -v22, v119, v27
	v_fma_f32 v75, -v22, v118, v78
	ds_read_b128 v[94:97], v0 offset:6336
	s_waitcnt lgkmcnt(12)
	v_fma_f32 v76, -v22, v125, v79
	v_fma_f32 v77, -v22, v124, v80
	v_fma_f32 v78, -v22, v123, v81
	v_fma_f32 v79, -v22, v122, v40
	ds_read_b128 v[98:101], v0 offset:6320
	s_waitcnt lgkmcnt(12)
	v_fma_f32 v80, -v22, v129, v41
	v_fma_f32 v81, -v22, v128, v42
	v_fma_f32 v82, -v22, v127, v43
	v_fma_f32 v83, -v22, v126, v44
	ds_read_b128 v[102:105], v0 offset:6304
	s_waitcnt lgkmcnt(12)
	v_fma_f32 v84, -v22, v159, v45
	v_fma_f32 v46, -v22, v158, v46
	v_fma_f32 v47, -v22, v157, v47
	v_fma_f32 v48, -v22, v156, v48
	ds_read_b128 v[106:109], v0 offset:6272
	s_waitcnt lgkmcnt(12)
	v_fma_f32 v49, -v22, v163, v49
	v_fma_f32 v50, -v22, v162, v50
	v_fma_f32 v51, -v22, v161, v51
	v_fma_f32 v52, -v22, v160, v52
	ds_read_b128 v[110:113], v0 offset:6288
	s_waitcnt lgkmcnt(12)
	v_fma_f32 v53, -v22, v167, v53
	v_fma_f32 v54, -v22, v166, v54
	v_fma_f32 v55, -v22, v165, v55
	v_fma_f32 v56, -v22, v164, v56
	ds_read_b128 v[114:117], v0 offset:6240
	ds_read_b128 v[118:121], v0 offset:6256
	ds_read_b128 v[122:125], v0 offset:6640
	s_waitcnt lgkmcnt(12)
	v_fma_f32 v69, -v22, v179, v69
	ds_read_b128 v[126:129], v0 offset:6624
	s_waitcnt lgkmcnt(12)
	v_fma_f32 v65, -v22, v183, v65
	v_fma_f32 v66, -v22, v182, v66
	v_fma_f32 v67, -v22, v181, v67
	v_fma_f32 v68, -v22, v180, v68
	v_fma_f32 v70, -v22, v178, v70
	v_fma_f32 v71, -v22, v177, v71
	v_fma_f32 v72, -v22, v176, v72
	v_fma_f32 v57, -v22, v175, v57
	v_fma_f32 v58, -v22, v174, v58
	v_fma_f32 v59, -v22, v173, v59
	v_fma_f32 v60, -v22, v172, v60
	v_fma_f32 v61, -v22, v171, v61
	v_fma_f32 v62, -v22, v170, v62
	v_fma_f32 v63, -v22, v169, v63
	v_fma_f32 v64, -v22, v168, v64
	ds_read_b128 v[156:159], v0 offset:6608
	s_waitcnt lgkmcnt(12)
	v_fma_f32 v73, -v72, v187, v73
	v_fma_f32 v74, -v72, v186, v74
	v_fma_f32 v27, -v72, v185, v27
	v_fma_f32 v75, -v72, v184, v75
	ds_read_b128 v[160:163], v0 offset:6592
	s_waitcnt lgkmcnt(12)
	v_fma_f32 v76, -v72, v191, v76
	v_fma_f32 v77, -v72, v190, v77
	v_fma_f32 v78, -v72, v189, v78
	v_fma_f32 v79, -v72, v188, v79
	ds_read_b128 v[164:167], v0 offset:6576
	s_waitcnt lgkmcnt(12)
	v_fma_f32 v80, -v72, v93, v80
	v_fma_f32 v81, -v72, v92, v81
	v_fma_f32 v82, -v72, v91, v82
	v_fma_f32 v83, -v72, v90, v83
	ds_read_b128 v[168:171], v0 offset:6560
	s_waitcnt lgkmcnt(12)
; #define LAS __attribute__((address_space(3)))
; #define PIN16(o) asm volatile("" : "+v"(xr[o]), "+v"(xr[o + 1]), "+v"(xr[o + 2]), "+v"(xr[o + 3]), "+v"(xr[o + 4]), "+v"(xr[o + 5]), "+v"(xr[o + 6]), "+v"(xr[o + 7]), "+v"(xr[o + 8]), "+v"(xr[o + 9]), "+v"(xr[o + 10]), "+v"(xr[o + 11]), "+v"(xr[o + 12]), "+v"(xr[o + 13]), "+v"(xr[o + 14]), "+v"(xr[o + 15]) :: "memory")
; DI void gdn_prep_item(LAS unsigned char* lds, const Ctx& c, int l, int item) {
;     ...
; #pragma unroll
;         for (int j = 0; j < 63; ++j) {
;             const float xj = xr[j];
; #pragma unroll
;             for (int i4 = (j + 1) / 4; i4 < 16; ++i4) { const f32x4 Lv = *(const LAS f32x4*)(Lb + j * 64 + 4 * i4);
; #pragma unroll
;                 for (int q = 0; q < 4; ++q) xr[4 * i4 + q] -= Lv[q] * xj; }
;     ...
;             PIN16(0); PIN16(16); PIN16(32); PIN16(48);
;         }
	v_fma_f32 v84, -v72, v97, v84
	v_fma_f32 v46, -v72, v96, v46
	v_fma_f32 v47, -v72, v95, v47
	v_fma_f32 v48, -v72, v94, v48
	ds_read_b128 v[172:175], v0 offset:6528
	s_waitcnt lgkmcnt(12)
	v_fma_f32 v49, -v72, v101, v49
	v_fma_f32 v50, -v72, v100, v50
	v_fma_f32 v51, -v72, v99, v51
	v_fma_f32 v52, -v72, v98, v52
	ds_read_b128 v[176:179], v0 offset:6544
	s_waitcnt lgkmcnt(12)
	v_fma_f32 v53, -v72, v105, v53
	v_fma_f32 v54, -v72, v104, v54
	v_fma_f32 v55, -v72, v103, v55
	v_fma_f32 v56, -v72, v102, v56
	ds_read_b128 v[180:183], v0 offset:6496
	s_waitcnt lgkmcnt(12)
	v_fma_f32 v61, -v72, v109, v61
	ds_read_b128 v[184:187], v0 offset:6512
	s_waitcnt lgkmcnt(12)
	v_fma_f32 v57, -v72, v113, v57
	v_fma_f32 v58, -v72, v112, v58
	v_fma_f32 v59, -v72, v111, v59
	v_fma_f32 v60, -v72, v110, v60
	v_fma_f32 v62, -v72, v108, v62
	v_fma_f32 v63, -v72, v107, v63
	v_fma_f32 v64, -v72, v106, v64
	ds_read_b128 v[188:191], v0 offset:6896
	ds_read_b128 v[90:93], v0 offset:6880
	s_waitcnt lgkmcnt(12)
	v_fma_f32 v65, -v72, v121, v65
	v_fma_f32 v66, -v72, v120, v66
	v_fma_f32 v67, -v72, v119, v67
	v_fma_f32 v68, -v72, v118, v68
	v_fma_f32 v69, -v72, v117, v69
	v_fma_f32 v70, -v72, v116, v70
	v_fma_f32 v71, -v72, v115, v71
	v_fma_f32 v72, -v72, v114, v72
	ds_read_b128 v[94:97], v0 offset:6864
	s_waitcnt lgkmcnt(12)
	v_fma_f32 v73, -v71, v125, v73
	v_fma_f32 v74, -v71, v124, v74
	v_fma_f32 v27, -v71, v123, v27
	v_fma_f32 v75, -v71, v122, v75
	ds_read_b128 v[98:101], v0 offset:6848
	s_waitcnt lgkmcnt(12)
	v_fma_f32 v76, -v71, v129, v76
	v_fma_f32 v77, -v71, v128, v77
	v_fma_f32 v78, -v71, v127, v78
	v_fma_f32 v79, -v71, v126, v79
	ds_read_b128 v[102:105], v0 offset:6832
	s_waitcnt lgkmcnt(12)
	v_fma_f32 v80, -v71, v159, v80
	v_fma_f32 v81, -v71, v158, v81
	v_fma_f32 v82, -v71, v157, v82
	v_fma_f32 v83, -v71, v156, v83
	ds_read_b128 v[106:109], v0 offset:6816
	s_waitcnt lgkmcnt(12)
	v_fma_f32 v84, -v71, v163, v84
	v_fma_f32 v46, -v71, v162, v46
	v_fma_f32 v47, -v71, v161, v47
	v_fma_f32 v48, -v71, v160, v48
	ds_read_b128 v[110:113], v0 offset:6784
	s_waitcnt lgkmcnt(12)
	v_fma_f32 v49, -v71, v167, v49
	v_fma_f32 v50, -v71, v166, v50
	v_fma_f32 v51, -v71, v165, v51
	v_fma_f32 v52, -v71, v164, v52
	ds_read_b128 v[114:117], v0 offset:6800
	s_waitcnt lgkmcnt(12)
	v_fma_f32 v53, -v71, v171, v53
	v_fma_f32 v54, -v71, v170, v54
	v_fma_f32 v55, -v71, v169, v55
	v_fma_f32 v56, -v71, v168, v56
	ds_read_b128 v[118:121], v0 offset:6752
	s_waitcnt lgkmcnt(12)
	v_fma_f32 v61, -v71, v175, v61
	ds_read_b128 v[122:125], v0 offset:6768
	s_waitcnt lgkmcnt(12)
	v_fma_f32 v57, -v71, v179, v57
	v_fma_f32 v58, -v71, v178, v58
	v_fma_f32 v59, -v71, v177, v59
	v_fma_f32 v60, -v71, v176, v60
	v_fma_f32 v62, -v71, v174, v62
	v_fma_f32 v63, -v71, v173, v63
	v_fma_f32 v64, -v71, v172, v64
	ds_read_b128 v[126:129], v0 offset:7152
	ds_read_b128 v[156:159], v0 offset:7136
	s_waitcnt lgkmcnt(12)
	v_fma_f32 v65, -v71, v187, v65
	v_fma_f32 v66, -v71, v186, v66
	v_fma_f32 v67, -v71, v185, v67
	v_fma_f32 v68, -v71, v184, v68
	v_fma_f32 v69, -v71, v183, v69
	v_fma_f32 v70, -v71, v182, v70
	v_fma_f32 v85, -v71, v181, v71
	v_fma_f32 v71, -v71, v180, v72
	ds_read_b128 v[160:163], v0 offset:7120
	s_waitcnt lgkmcnt(12)
	v_fma_f32 v72, -v70, v191, v73
	v_fma_f32 v73, -v70, v190, v74
	v_fma_f32 v27, -v70, v189, v27
	v_fma_f32 v74, -v70, v188, v75
	ds_read_b128 v[164:167], v0 offset:7104
	s_waitcnt lgkmcnt(12)
	v_fma_f32 v75, -v70, v93, v76
	v_fma_f32 v76, -v70, v92, v77
	v_fma_f32 v77, -v70, v91, v78
	v_fma_f32 v78, -v70, v90, v79
	ds_read_b128 v[168:171], v0 offset:7088
	s_waitcnt lgkmcnt(12)
	v_fma_f32 v79, -v70, v97, v80
	v_fma_f32 v80, -v70, v96, v81
	v_fma_f32 v81, -v70, v95, v82
	v_fma_f32 v82, -v70, v94, v83
	ds_read_b128 v[172:175], v0 offset:7056
	s_waitcnt lgkmcnt(12)
	v_fma_f32 v83, -v70, v101, v84
	v_fma_f32 v46, -v70, v100, v46
	v_fma_f32 v47, -v70, v99, v47
	v_fma_f32 v48, -v70, v98, v48
	ds_read_b128 v[176:179], v0 offset:7072
	s_waitcnt lgkmcnt(12)
	v_fma_f32 v49, -v70, v105, v49
	v_fma_f32 v50, -v70, v104, v50
	v_fma_f32 v51, -v70, v103, v51
	v_fma_f32 v52, -v70, v102, v52
	ds_read_b128 v[180:183], v0 offset:7024
	s_waitcnt lgkmcnt(12)
	v_fma_f32 v53, -v70, v109, v53
	v_fma_f32 v54, -v70, v108, v54
	v_fma_f32 v55, -v70, v107, v55
	ds_read_b128 v[184:187], v0 offset:7040
	s_waitcnt lgkmcnt(12)
	v_fma_f32 v61, -v70, v113, v61
	v_fma_f32 v62, -v70, v112, v62
	v_fma_f32 v63, -v70, v111, v63
	v_fma_f32 v64, -v70, v110, v64
	ds_read_b128 v[188:191], v0 offset:7408
	ds_read_b128 v[90:93], v0 offset:7392
	ds_read_b128 v[94:97], v0 offset:7376
	s_waitcnt lgkmcnt(12)
	v_fma_f32 v65, -v70, v125, v65
	v_fma_f32 v66, -v70, v124, v66
	v_fma_f32 v67, -v70, v123, v67
	v_fma_f32 v68, -v70, v122, v68
	v_fma_f32 v28, -v70, v121, v69
	v_fma_f32 v29, -v70, v120, v70
	v_fma_f32 v30, -v70, v119, v85
	v_fma_f32 v31, -v70, v118, v71
	v_fma_f32 v56, -v70, v106, v56
	v_fma_f32 v57, -v70, v117, v57
	v_fma_f32 v58, -v70, v116, v58
	v_fma_f32 v59, -v70, v115, v59
	v_fma_f32 v60, -v70, v114, v60
	ds_read_b128 v[98:101], v0 offset:7360
	s_waitcnt lgkmcnt(12)
	v_fma_f32 v69, -v28, v129, v72
	v_fma_f32 v70, -v28, v128, v73
	v_fma_f32 v27, -v28, v127, v27
	v_fma_f32 v71, -v28, v126, v74
	ds_read_b128 v[102:105], v0 offset:7344
	s_waitcnt lgkmcnt(12)
	v_fma_f32 v72, -v28, v159, v75
	v_fma_f32 v73, -v28, v158, v76
	v_fma_f32 v74, -v28, v157, v77
	v_fma_f32 v75, -v28, v156, v78
	ds_read_b128 v[106:109], v0 offset:7312
	s_waitcnt lgkmcnt(12)
	v_fma_f32 v76, -v28, v163, v79
	v_fma_f32 v77, -v28, v162, v80
	v_fma_f32 v78, -v28, v161, v81
	v_fma_f32 v79, -v28, v160, v82
	ds_read_b128 v[110:113], v0 offset:7328
	s_waitcnt lgkmcnt(12)
; #define LAS __attribute__((address_space(3)))
; #define PIN16(o) asm volatile("" : "+v"(xr[o]), "+v"(xr[o + 1]), "+v"(xr[o + 2]), "+v"(xr[o + 3]), "+v"(xr[o + 4]), "+v"(xr[o + 5]), "+v"(xr[o + 6]), "+v"(xr[o + 7]), "+v"(xr[o + 8]), "+v"(xr[o + 9]), "+v"(xr[o + 10]), "+v"(xr[o + 11]), "+v"(xr[o + 12]), "+v"(xr[o + 13]), "+v"(xr[o + 14]), "+v"(xr[o + 15]) :: "memory")
; DI void gdn_prep_item(LAS unsigned char* lds, const Ctx& c, int l, int item) {
;     ...
; #pragma unroll
;         for (int j = 0; j < 63; ++j) {
;             const float xj = xr[j];
; #pragma unroll
;             for (int i4 = (j + 1) / 4; i4 < 16; ++i4) { const f32x4 Lv = *(const LAS f32x4*)(Lb + j * 64 + 4 * i4);
; #pragma unroll
;                 for (int q = 0; q < 4; ++q) xr[4 * i4 + q] -= Lv[q] * xj; }
;     ...
;             PIN16(0); PIN16(16); PIN16(32); PIN16(48);
;         }
	v_fma_f32 v80, -v28, v167, v83
	v_fma_f32 v81, -v28, v166, v46
	v_fma_f32 v82, -v28, v165, v47
	v_fma_f32 v83, -v28, v164, v48
	ds_read_b128 v[114:117], v0 offset:7280
	s_waitcnt lgkmcnt(12)
	v_fma_f32 v84, -v28, v171, v49
	v_fma_f32 v50, -v28, v170, v50
	v_fma_f32 v51, -v28, v169, v51
	v_fma_f32 v52, -v28, v168, v52
	ds_read_b128 v[118:121], v0 offset:7296
	ds_read_b128 v[122:125], v0 offset:7664
	ds_read_b128 v[126:129], v0 offset:7648
	s_waitcnt lgkmcnt(12)
	v_fma_f32 v65, -v28, v183, v65
	v_fma_f32 v66, -v28, v182, v66
	v_fma_f32 v67, -v28, v181, v67
	v_fma_f32 v68, -v28, v180, v68
	v_fma_f32 v53, -v28, v179, v53
	v_fma_f32 v54, -v28, v178, v54
	v_fma_f32 v55, -v28, v177, v55
	v_fma_f32 v56, -v28, v176, v56
	v_fma_f32 v57, -v28, v175, v57
	v_fma_f32 v58, -v28, v174, v58
	v_fma_f32 v59, -v28, v173, v59
	v_fma_f32 v60, -v28, v172, v60
	ds_read_b128 v[156:159], v0 offset:7632
	s_waitcnt lgkmcnt(12)
	v_fma_f32 v61, -v28, v187, v61
	v_fma_f32 v62, -v28, v186, v62
	v_fma_f32 v63, -v28, v185, v63
	v_fma_f32 v64, -v28, v184, v64
	ds_read_b128 v[160:163], v0 offset:7616
	s_waitcnt lgkmcnt(12)
	v_fma_f32 v69, -v68, v191, v69
	v_fma_f32 v70, -v68, v190, v70
	v_fma_f32 v27, -v68, v189, v27
	v_fma_f32 v71, -v68, v188, v71
	ds_read_b128 v[164:167], v0 offset:7600
	s_waitcnt lgkmcnt(12)
	v_fma_f32 v72, -v68, v93, v72
	v_fma_f32 v73, -v68, v92, v73
	v_fma_f32 v74, -v68, v91, v74
	v_fma_f32 v75, -v68, v90, v75
	ds_read_b128 v[168:171], v0 offset:7568
	s_waitcnt lgkmcnt(12)
	v_fma_f32 v76, -v68, v97, v76
	v_fma_f32 v77, -v68, v96, v77
	v_fma_f32 v78, -v68, v95, v78
	v_fma_f32 v79, -v68, v94, v79
	ds_read_b128 v[172:175], v0 offset:7584
	s_waitcnt lgkmcnt(12)
	v_fma_f32 v80, -v68, v101, v80
	v_fma_f32 v81, -v68, v100, v81
	v_fma_f32 v82, -v68, v99, v82
	v_fma_f32 v83, -v68, v98, v83
	ds_read_b128 v[176:179], v0 offset:7536
	s_waitcnt lgkmcnt(12)
	v_fma_f32 v84, -v68, v105, v84
	v_fma_f32 v50, -v68, v104, v50
	v_fma_f32 v51, -v68, v103, v51
	v_fma_f32 v52, -v68, v102, v52
	ds_read_b128 v[180:183], v0 offset:7552
	s_waitcnt lgkmcnt(12)
	v_fma_f32 v57, -v68, v109, v57
	ds_read_b128 v[184:187], v0 offset:7920
	s_waitcnt lgkmcnt(12)
	v_fma_f32 v53, -v68, v113, v53
	v_fma_f32 v54, -v68, v112, v54
	v_fma_f32 v55, -v68, v111, v55
	v_fma_f32 v56, -v68, v110, v56
	v_fma_f32 v58, -v68, v108, v58
	v_fma_f32 v59, -v68, v107, v59
	v_fma_f32 v60, -v68, v106, v60
	ds_read_b128 v[188:191], v0 offset:7904
	ds_read_b128 v[90:93], v0 offset:7888
	s_waitcnt lgkmcnt(12)
	v_fma_f32 v61, -v68, v121, v61
	v_fma_f32 v62, -v68, v120, v62
	v_fma_f32 v63, -v68, v119, v63
	v_fma_f32 v64, -v68, v118, v64
	v_fma_f32 v65, -v68, v117, v65
	v_fma_f32 v66, -v68, v116, v66
	v_fma_f32 v67, -v68, v115, v67
	v_fma_f32 v68, -v68, v114, v68
	ds_read_b128 v[94:97], v0 offset:7872
	s_waitcnt lgkmcnt(12)
	v_fma_f32 v69, -v67, v125, v69
	v_fma_f32 v70, -v67, v124, v70
	v_fma_f32 v27, -v67, v123, v27
	v_fma_f32 v71, -v67, v122, v71
	ds_read_b128 v[98:101], v0 offset:7856
	s_waitcnt lgkmcnt(12)
	v_fma_f32 v72, -v67, v129, v72
	v_fma_f32 v73, -v67, v128, v73
	v_fma_f32 v74, -v67, v127, v74
	v_fma_f32 v75, -v67, v126, v75
	ds_read_b128 v[102:105], v0 offset:7824
	s_waitcnt lgkmcnt(12)
	v_fma_f32 v76, -v67, v159, v76
	v_fma_f32 v77, -v67, v158, v77
	v_fma_f32 v78, -v67, v157, v78
	v_fma_f32 v79, -v67, v156, v79
	ds_read_b128 v[106:109], v0 offset:7840
	s_waitcnt lgkmcnt(12)
	v_fma_f32 v80, -v67, v163, v80
	v_fma_f32 v81, -v67, v162, v81
	v_fma_f32 v82, -v67, v161, v82
	v_fma_f32 v83, -v67, v160, v83
	ds_read_b128 v[110:113], v0 offset:7792
	s_waitcnt lgkmcnt(12)
	v_fma_f32 v84, -v67, v167, v84
	v_fma_f32 v50, -v67, v166, v50
	v_fma_f32 v51, -v67, v165, v51
	v_fma_f32 v52, -v67, v164, v52
	ds_read_b128 v[114:117], v0 offset:7808
	s_waitcnt lgkmcnt(12)
	v_fma_f32 v57, -v67, v171, v57
	ds_read_b128 v[118:121], v0 offset:8176
	s_waitcnt lgkmcnt(12)
	v_fma_f32 v53, -v67, v175, v53
	v_fma_f32 v54, -v67, v174, v54
	v_fma_f32 v55, -v67, v173, v55
	v_fma_f32 v56, -v67, v172, v56
	v_fma_f32 v58, -v67, v170, v58
	v_fma_f32 v59, -v67, v169, v59
	v_fma_f32 v60, -v67, v168, v60
	ds_read_b128 v[122:125], v0 offset:8160
	ds_read_b128 v[126:129], v0 offset:8144
	s_waitcnt lgkmcnt(12)
	v_fma_f32 v61, -v67, v183, v61
	v_fma_f32 v62, -v67, v182, v62
	v_fma_f32 v63, -v67, v181, v63
	v_fma_f32 v64, -v67, v180, v64
	v_fma_f32 v65, -v67, v179, v65
	v_fma_f32 v66, -v67, v178, v66
	v_fma_f32 v85, -v67, v177, v67
	v_fma_f32 v67, -v67, v176, v68
	ds_read_b128 v[156:159], v0 offset:8128
	s_waitcnt lgkmcnt(12)
	v_fma_f32 v68, -v66, v187, v69
	v_fma_f32 v69, -v66, v186, v70
	v_fma_f32 v27, -v66, v185, v27
	v_fma_f32 v70, -v66, v184, v71
	ds_read_b128 v[160:163], v0 offset:8096
	s_waitcnt lgkmcnt(12)
	v_fma_f32 v71, -v66, v191, v72
	v_fma_f32 v72, -v66, v190, v73
	v_fma_f32 v73, -v66, v189, v74
	v_fma_f32 v74, -v66, v188, v75
	ds_read_b128 v[164:167], v0 offset:8112
	s_waitcnt lgkmcnt(12)
	v_fma_f32 v75, -v66, v93, v76
	v_fma_f32 v76, -v66, v92, v77
	v_fma_f32 v77, -v66, v91, v78
	v_fma_f32 v78, -v66, v90, v79
	ds_read_b128 v[168:171], v0 offset:8064
	s_waitcnt lgkmcnt(12)
	v_fma_f32 v79, -v66, v97, v80
	v_fma_f32 v80, -v66, v96, v81
	v_fma_f32 v81, -v66, v95, v82
	v_fma_f32 v82, -v66, v94, v83
	ds_read_b128 v[172:175], v0 offset:8080
	s_waitcnt lgkmcnt(12)
	v_fma_f32 v83, -v66, v101, v84
	v_fma_f32 v84, -v66, v100, v50
	v_fma_f32 v86, -v66, v99, v51
	v_fma_f32 v87, -v66, v98, v52
	ds_read_b128 v[176:179], v0 offset:8432
	s_waitcnt lgkmcnt(12)
	v_fma_f32 v59, -v66, v103, v59
	v_fma_f32 v60, -v66, v102, v60
	ds_read_b128 v[180:183], v0 offset:8416
	ds_read_b128 v[184:187], v0 offset:8400
	s_waitcnt lgkmcnt(12)
; #define LAS __attribute__((address_space(3)))
; #define PIN16(o) asm volatile("" : "+v"(xr[o]), "+v"(xr[o + 1]), "+v"(xr[o + 2]), "+v"(xr[o + 3]), "+v"(xr[o + 4]), "+v"(xr[o + 5]), "+v"(xr[o + 6]), "+v"(xr[o + 7]), "+v"(xr[o + 8]), "+v"(xr[o + 9]), "+v"(xr[o + 10]), "+v"(xr[o + 11]), "+v"(xr[o + 12]), "+v"(xr[o + 13]), "+v"(xr[o + 14]), "+v"(xr[o + 15]) :: "memory")
; DI void gdn_prep_item(LAS unsigned char* lds, const Ctx& c, int l, int item) {
;     ...
; #pragma unroll
;         for (int j = 0; j < 63; ++j) {
;             const float xj = xr[j];
; #pragma unroll
;             for (int i4 = (j + 1) / 4; i4 < 16; ++i4) { const f32x4 Lv = *(const LAS f32x4*)(Lb + j * 64 + 4 * i4);
; #pragma unroll
;                 for (int q = 0; q < 4; ++q) xr[4 * i4 + q] -= Lv[q] * xj; }
;     ...
;             PIN16(0); PIN16(16); PIN16(32); PIN16(48);
;         }
	v_fma_f32 v32, -v66, v113, v65
	v_fma_f32 v33, -v66, v112, v66
	v_fma_f32 v34, -v66, v111, v85
	v_fma_f32 v35, -v66, v110, v67
	v_fma_f32 v88, -v66, v109, v53
	v_fma_f32 v54, -v66, v108, v54
	v_fma_f32 v55, -v66, v107, v55
	v_fma_f32 v56, -v66, v106, v56
	v_fma_f32 v57, -v66, v105, v57
	v_fma_f32 v58, -v66, v104, v58
	ds_read_b128 v[188:191], v0 offset:8384
	s_waitcnt lgkmcnt(12)
	v_fma_f32 v61, -v66, v117, v61
	v_fma_f32 v62, -v66, v116, v62
	v_fma_f32 v63, -v66, v115, v63
	v_fma_f32 v64, -v66, v114, v64
	ds_read_b128 v[90:93], v0 offset:8352
	s_waitcnt lgkmcnt(12)
	v_fma_f32 v65, -v32, v121, v68
	v_fma_f32 v66, -v32, v120, v69
	v_fma_f32 v27, -v32, v119, v27
	v_fma_f32 v67, -v32, v118, v70
	ds_read_b128 v[94:97], v0 offset:8368
	s_waitcnt lgkmcnt(12)
	v_fma_f32 v68, -v32, v125, v71
	v_fma_f32 v69, -v32, v124, v72
	v_fma_f32 v70, -v32, v123, v73
	v_fma_f32 v71, -v32, v122, v74
	ds_read_b128 v[98:101], v0 offset:8320
	s_waitcnt lgkmcnt(12)
	v_fma_f32 v72, -v32, v129, v75
	v_fma_f32 v73, -v32, v128, v76
	v_fma_f32 v74, -v32, v127, v77
	v_fma_f32 v75, -v32, v126, v78
	ds_read_b128 v[102:105], v0 offset:8336
	s_waitcnt lgkmcnt(12)
	v_fma_f32 v76, -v32, v159, v79
	v_fma_f32 v77, -v32, v158, v80
	v_fma_f32 v78, -v32, v157, v81
	v_fma_f32 v79, -v32, v156, v82
	ds_read_b128 v[106:109], v0 offset:8688
	ds_read_b128 v[110:113], v0 offset:8672
	s_waitcnt lgkmcnt(12)
	v_fma_f32 v80, -v32, v167, v83
	v_fma_f32 v81, -v32, v166, v84
	v_fma_f32 v82, -v32, v165, v86
	v_fma_f32 v83, -v32, v164, v87
	v_fma_f32 v84, -v32, v163, v88
	v_fma_f32 v54, -v32, v162, v54
	v_fma_f32 v55, -v32, v161, v55
	v_fma_f32 v56, -v32, v160, v56
	ds_read_b128 v[114:117], v0 offset:8656
	ds_read_b128 v[118:121], v0 offset:8640
	s_waitcnt lgkmcnt(12)
	v_fma_f32 v57, -v32, v175, v57
	v_fma_f32 v58, -v32, v174, v58
	v_fma_f32 v59, -v32, v173, v59
	v_fma_f32 v60, -v32, v172, v60
	v_fma_f32 v61, -v32, v171, v61
	v_fma_f32 v62, -v32, v170, v62
	v_fma_f32 v63, -v32, v169, v63
	v_fma_f32 v64, -v32, v168, v64
	ds_read_b128 v[122:125], v0 offset:8608
	s_waitcnt lgkmcnt(12)
	v_fma_f32 v65, -v64, v179, v65
	v_fma_f32 v66, -v64, v178, v66
	v_fma_f32 v27, -v64, v177, v27
	v_fma_f32 v67, -v64, v176, v67
	ds_read_b128 v[126:129], v0 offset:8624
	s_waitcnt lgkmcnt(12)
	v_fma_f32 v68, -v64, v183, v68
	v_fma_f32 v69, -v64, v182, v69
	v_fma_f32 v70, -v64, v181, v70
	v_fma_f32 v71, -v64, v180, v71
	ds_read_b128 v[156:159], v0 offset:8576
	s_waitcnt lgkmcnt(12)
	v_fma_f32 v72, -v64, v187, v72
	v_fma_f32 v73, -v64, v186, v73
	v_fma_f32 v74, -v64, v185, v74
	v_fma_f32 v75, -v64, v184, v75
	ds_read_b128 v[160:163], v0 offset:8592
	s_waitcnt lgkmcnt(12)
	v_fma_f32 v76, -v64, v191, v76
	v_fma_f32 v77, -v64, v190, v77
	v_fma_f32 v78, -v64, v189, v78
	v_fma_f32 v79, -v64, v188, v79
	ds_read_b128 v[164:167], v0 offset:8944
	ds_read_b128 v[168:171], v0 offset:8928
	s_waitcnt lgkmcnt(12)
	v_fma_f32 v80, -v64, v97, v80
	v_fma_f32 v81, -v64, v96, v81
	v_fma_f32 v82, -v64, v95, v82
	v_fma_f32 v83, -v64, v94, v83
	v_fma_f32 v84, -v64, v93, v84
	v_fma_f32 v54, -v64, v92, v54
	v_fma_f32 v55, -v64, v91, v55
	v_fma_f32 v56, -v64, v90, v56
	ds_read_b128 v[172:175], v0 offset:8912
	ds_read_b128 v[176:179], v0 offset:8896
	s_waitcnt lgkmcnt(12)
	v_fma_f32 v57, -v64, v105, v57
	v_fma_f32 v58, -v64, v104, v58
	v_fma_f32 v59, -v64, v103, v59
	v_fma_f32 v60, -v64, v102, v60
	v_fma_f32 v61, -v64, v101, v61
	v_fma_f32 v62, -v64, v100, v62
	v_fma_f32 v63, -v64, v99, v63
	v_fma_f32 v64, -v64, v98, v64
	ds_read_b128 v[180:183], v0 offset:8864
	s_waitcnt lgkmcnt(12)
	v_fma_f32 v65, -v63, v109, v65
	v_fma_f32 v66, -v63, v108, v66
	v_fma_f32 v27, -v63, v107, v27
	v_fma_f32 v67, -v63, v106, v67
	ds_read_b128 v[184:187], v0 offset:8880
	s_waitcnt lgkmcnt(12)
	v_fma_f32 v68, -v63, v113, v68
	v_fma_f32 v69, -v63, v112, v69
	v_fma_f32 v70, -v63, v111, v70
	v_fma_f32 v71, -v63, v110, v71
	ds_read_b128 v[188:191], v0 offset:8832
	s_waitcnt lgkmcnt(12)
	v_fma_f32 v72, -v63, v117, v72
	v_fma_f32 v73, -v63, v116, v73
	v_fma_f32 v74, -v63, v115, v74
	v_fma_f32 v75, -v63, v114, v75
	ds_read_b128 v[90:93], v0 offset:8848
	s_waitcnt lgkmcnt(12)
	v_fma_f32 v76, -v63, v121, v76
	v_fma_f32 v77, -v63, v120, v77
	v_fma_f32 v78, -v63, v119, v78
	v_fma_f32 v79, -v63, v118, v79
	ds_read_b128 v[94:97], v0 offset:9200
	ds_read_b128 v[98:101], v0 offset:9184
	s_waitcnt lgkmcnt(12)
	v_fma_f32 v80, -v63, v129, v80
	v_fma_f32 v81, -v63, v128, v81
	v_fma_f32 v82, -v63, v127, v82
	v_fma_f32 v83, -v63, v126, v83
	v_fma_f32 v84, -v63, v125, v84
	v_fma_f32 v54, -v63, v124, v54
	v_fma_f32 v55, -v63, v123, v55
	v_fma_f32 v56, -v63, v122, v56
	ds_read_b128 v[102:105], v0 offset:9168
	ds_read_b128 v[106:109], v0 offset:9136
	s_waitcnt lgkmcnt(12)
	v_fma_f32 v57, -v63, v163, v57
	v_fma_f32 v58, -v63, v162, v58
	v_fma_f32 v59, -v63, v161, v59
	v_fma_f32 v60, -v63, v160, v60
	v_fma_f32 v61, -v63, v159, v61
	v_fma_f32 v62, -v63, v158, v62
	v_fma_f32 v85, -v63, v157, v63
	v_fma_f32 v63, -v63, v156, v64
	ds_read_b128 v[110:113], v0 offset:9152
	s_waitcnt lgkmcnt(12)
	v_fma_f32 v64, -v62, v167, v65
	v_fma_f32 v65, -v62, v166, v66
	v_fma_f32 v27, -v62, v165, v27
	v_fma_f32 v66, -v62, v164, v67
	ds_read_b128 v[114:117], v0 offset:9104
	s_waitcnt lgkmcnt(12)
	v_fma_f32 v67, -v62, v171, v68
	v_fma_f32 v68, -v62, v170, v69
	v_fma_f32 v69, -v62, v169, v70
	v_fma_f32 v70, -v62, v168, v71
	ds_read_b128 v[118:121], v0 offset:9120
	s_waitcnt lgkmcnt(12)
	v_fma_f32 v71, -v62, v175, v72
	v_fma_f32 v72, -v62, v174, v73
	v_fma_f32 v73, -v62, v173, v74
	v_fma_f32 v74, -v62, v172, v75
	ds_read_b128 v[122:125], v0 offset:9456
	s_waitcnt lgkmcnt(12)
; #define LAS __attribute__((address_space(3)))
; #define PIN16(o) asm volatile("" : "+v"(xr[o]), "+v"(xr[o + 1]), "+v"(xr[o + 2]), "+v"(xr[o + 3]), "+v"(xr[o + 4]), "+v"(xr[o + 5]), "+v"(xr[o + 6]), "+v"(xr[o + 7]), "+v"(xr[o + 8]), "+v"(xr[o + 9]), "+v"(xr[o + 10]), "+v"(xr[o + 11]), "+v"(xr[o + 12]), "+v"(xr[o + 13]), "+v"(xr[o + 14]), "+v"(xr[o + 15]) :: "memory")
; DI void gdn_prep_item(LAS unsigned char* lds, const Ctx& c, int l, int item) {
;     ...
; #pragma unroll
;         for (int j = 0; j < 63; ++j) {
;             const float xj = xr[j];
; #pragma unroll
;             for (int i4 = (j + 1) / 4; i4 < 16; ++i4) { const f32x4 Lv = *(const LAS f32x4*)(Lb + j * 64 + 4 * i4);
; #pragma unroll
;                 for (int q = 0; q < 4; ++q) xr[4 * i4 + q] -= Lv[q] * xj; }
;     ...
;             PIN16(0); PIN16(16); PIN16(32); PIN16(48);
;         }
	v_fma_f32 v75, -v62, v179, v76
	v_fma_f32 v76, -v62, v178, v77
	v_fma_f32 v77, -v62, v177, v78
	v_fma_f32 v78, -v62, v176, v79
	ds_read_b128 v[126:129], v0 offset:9440
	ds_read_b128 v[156:159], v0 offset:9424
	s_waitcnt lgkmcnt(12)
	v_fma_f32 v79, -v62, v187, v80
	v_fma_f32 v80, -v62, v186, v81
	v_fma_f32 v81, -v62, v185, v82
	v_fma_f32 v82, -v62, v184, v83
	v_fma_f32 v83, -v62, v183, v84
	v_fma_f32 v84, -v62, v182, v54
	v_fma_f32 v86, -v62, v181, v55
	v_fma_f32 v87, -v62, v180, v56
	ds_read_b128 v[160:163], v0 offset:9392
	ds_read_b128 v[164:167], v0 offset:9408
	s_waitcnt lgkmcnt(12)
	v_fma_f32 v88, -v62, v93, v57
	v_fma_f32 v58, -v62, v92, v58
	v_fma_f32 v59, -v62, v91, v59
	v_fma_f32 v60, -v62, v90, v60
	v_fma_f32 v36, -v62, v191, v61
	v_fma_f32 v37, -v62, v190, v62
	v_fma_f32 v38, -v62, v189, v85
	v_fma_f32 v39, -v62, v188, v63
	ds_read_b128 v[168:171], v0 offset:9360
	s_waitcnt lgkmcnt(12)
	v_fma_f32 v61, -v36, v97, v64
	v_fma_f32 v62, -v36, v96, v65
	v_fma_f32 v27, -v36, v95, v27
	v_fma_f32 v63, -v36, v94, v66
	ds_read_b128 v[172:175], v0 offset:9376
	s_waitcnt lgkmcnt(12)
	v_fma_f32 v64, -v36, v101, v67
	v_fma_f32 v65, -v36, v100, v68
	v_fma_f32 v66, -v36, v99, v69
	v_fma_f32 v67, -v36, v98, v70
	ds_read_b128 v[176:179], v0 offset:9712
	s_waitcnt lgkmcnt(12)
	v_fma_f32 v68, -v36, v105, v71
	v_fma_f32 v69, -v36, v104, v72
	v_fma_f32 v70, -v36, v103, v73
	v_fma_f32 v71, -v36, v102, v74
	ds_read_b128 v[180:183], v0 offset:9696
	ds_read_b128 v[184:187], v0 offset:9680
	s_waitcnt lgkmcnt(12)
	v_fma_f32 v72, -v36, v113, v75
	v_fma_f32 v73, -v36, v112, v76
	v_fma_f32 v74, -v36, v111, v77
	v_fma_f32 v75, -v36, v110, v78
	v_fma_f32 v76, -v36, v109, v79
	v_fma_f32 v77, -v36, v108, v80
	v_fma_f32 v78, -v36, v107, v81
	v_fma_f32 v79, -v36, v106, v82
	ds_read_b128 v[188:191], v0 offset:9648
	ds_read_b128 v[90:93], v0 offset:9664
	s_waitcnt lgkmcnt(12)
	v_fma_f32 v80, -v36, v121, v83
	v_fma_f32 v81, -v36, v120, v84
	v_fma_f32 v82, -v36, v119, v86
	v_fma_f32 v83, -v36, v118, v87
	v_fma_f32 v84, -v36, v117, v88
	v_fma_f32 v58, -v36, v116, v58
	v_fma_f32 v59, -v36, v115, v59
	v_fma_f32 v60, -v36, v114, v60
	ds_read_b128 v[94:97], v0 offset:9616
	s_waitcnt lgkmcnt(12)
	v_fma_f32 v61, -v60, v125, v61
	v_fma_f32 v62, -v60, v124, v62
	v_fma_f32 v27, -v60, v123, v27
	v_fma_f32 v63, -v60, v122, v63
	ds_read_b128 v[98:101], v0 offset:9632
	s_waitcnt lgkmcnt(12)
	v_fma_f32 v64, -v60, v129, v64
	v_fma_f32 v65, -v60, v128, v65
	v_fma_f32 v66, -v60, v127, v66
	v_fma_f32 v67, -v60, v126, v67
	ds_read_b128 v[102:105], v0 offset:9968
	s_waitcnt lgkmcnt(12)
	v_fma_f32 v68, -v60, v159, v68
	v_fma_f32 v69, -v60, v158, v69
	v_fma_f32 v70, -v60, v157, v70
	v_fma_f32 v71, -v60, v156, v71
	ds_read_b128 v[106:109], v0 offset:9952
	ds_read_b128 v[110:113], v0 offset:9936
	s_waitcnt lgkmcnt(12)
	v_fma_f32 v72, -v60, v167, v72
	v_fma_f32 v73, -v60, v166, v73
	v_fma_f32 v74, -v60, v165, v74
	v_fma_f32 v75, -v60, v164, v75
	v_fma_f32 v76, -v60, v163, v76
	v_fma_f32 v77, -v60, v162, v77
	v_fma_f32 v78, -v60, v161, v78
	v_fma_f32 v79, -v60, v160, v79
	ds_read_b128 v[114:117], v0 offset:9904
	ds_read_b128 v[118:121], v0 offset:9920
	s_waitcnt lgkmcnt(12)
	v_fma_f32 v80, -v60, v175, v80
	v_fma_f32 v81, -v60, v174, v81
	v_fma_f32 v82, -v60, v173, v82
	v_fma_f32 v83, -v60, v172, v83
	v_fma_f32 v84, -v60, v171, v84
	v_fma_f32 v58, -v60, v170, v58
	v_fma_f32 v59, -v60, v169, v59
	v_fma_f32 v60, -v60, v168, v60
	ds_read_b128 v[122:125], v0 offset:9872
	s_waitcnt lgkmcnt(12)
	v_fma_f32 v61, -v59, v179, v61
	v_fma_f32 v62, -v59, v178, v62
	v_fma_f32 v27, -v59, v177, v27
	v_fma_f32 v63, -v59, v176, v63
	ds_read_b128 v[126:129], v0 offset:9888
	s_waitcnt lgkmcnt(12)
	v_fma_f32 v64, -v59, v183, v64
	v_fma_f32 v65, -v59, v182, v65
	v_fma_f32 v66, -v59, v181, v66
	v_fma_f32 v67, -v59, v180, v67
	ds_read_b128 v[156:159], v0 offset:10224
	s_waitcnt lgkmcnt(12)
	v_fma_f32 v68, -v59, v187, v68
	v_fma_f32 v69, -v59, v186, v69
	v_fma_f32 v70, -v59, v185, v70
	v_fma_f32 v71, -v59, v184, v71
	ds_read_b128 v[160:163], v0 offset:10208
	ds_read_b128 v[164:167], v0 offset:10176
	s_waitcnt lgkmcnt(12)
	v_fma_f32 v72, -v59, v93, v72
	v_fma_f32 v73, -v59, v92, v73
	v_fma_f32 v74, -v59, v91, v74
	v_fma_f32 v75, -v59, v90, v75
	v_fma_f32 v76, -v59, v191, v76
	v_fma_f32 v77, -v59, v190, v77
	v_fma_f32 v78, -v59, v189, v78
	v_fma_f32 v79, -v59, v188, v79
	ds_read_b128 v[168:171], v0 offset:10192
	ds_read_b128 v[172:175], v0 offset:10144
	s_waitcnt lgkmcnt(12)
	v_fma_f32 v80, -v59, v101, v80
	v_fma_f32 v81, -v59, v100, v81
	v_fma_f32 v82, -v59, v99, v82
	v_fma_f32 v83, -v59, v98, v83
	v_fma_f32 v84, -v59, v97, v84
	v_fma_f32 v58, -v59, v96, v58
	v_fma_f32 v85, -v59, v95, v59
	v_fma_f32 v59, -v59, v94, v60
	ds_read_b128 v[176:179], v0 offset:10160
	s_waitcnt lgkmcnt(12)
	v_fma_f32 v60, -v58, v105, v61
	v_fma_f32 v61, -v58, v104, v62
	v_fma_f32 v27, -v58, v103, v27
	v_fma_f32 v62, -v58, v102, v63
	ds_read_b128 v[180:183], v0 offset:10480
	s_waitcnt lgkmcnt(12)
	v_fma_f32 v63, -v58, v109, v64
	v_fma_f32 v64, -v58, v108, v65
	v_fma_f32 v65, -v58, v107, v66
	v_fma_f32 v66, -v58, v106, v67
	ds_read_b128 v[184:187], v0 offset:10464
	s_waitcnt lgkmcnt(12)
	v_fma_f32 v67, -v58, v113, v68
	v_fma_f32 v68, -v58, v112, v69
	v_fma_f32 v69, -v58, v111, v70
	v_fma_f32 v70, -v58, v110, v71
	ds_read_b128 v[188:191], v0 offset:10432
	ds_read_b128 v[90:93], v0 offset:10448
	s_waitcnt lgkmcnt(12)
	v_fma_f32 v71, -v58, v121, v72
	v_fma_f32 v72, -v58, v120, v73
	v_fma_f32 v73, -v58, v119, v74
	v_fma_f32 v74, -v58, v118, v75
	v_fma_f32 v75, -v58, v117, v76
	v_fma_f32 v76, -v58, v116, v77
	v_fma_f32 v77, -v58, v115, v78
	v_fma_f32 v78, -v58, v114, v79
	ds_read_b128 v[94:97], v0 offset:10400
	ds_read_b128 v[98:101], v0 offset:10416
	s_waitcnt lgkmcnt(12)
; #define LAS __attribute__((address_space(3)))
; #define PIN16(o) asm volatile("" : "+v"(xr[o]), "+v"(xr[o + 1]), "+v"(xr[o + 2]), "+v"(xr[o + 3]), "+v"(xr[o + 4]), "+v"(xr[o + 5]), "+v"(xr[o + 6]), "+v"(xr[o + 7]), "+v"(xr[o + 8]), "+v"(xr[o + 9]), "+v"(xr[o + 10]), "+v"(xr[o + 11]), "+v"(xr[o + 12]), "+v"(xr[o + 13]), "+v"(xr[o + 14]), "+v"(xr[o + 15]) :: "memory")
; DI void gdn_prep_item(LAS unsigned char* lds, const Ctx& c, int l, int item) {
;     ...
; #pragma unroll
;         for (int j = 0; j < 63; ++j) {
;             const float xj = xr[j];
; #pragma unroll
;             for (int i4 = (j + 1) / 4; i4 < 16; ++i4) { const f32x4 Lv = *(const LAS f32x4*)(Lb + j * 64 + 4 * i4);
; #pragma unroll
;                 for (int q = 0; q < 4; ++q) xr[4 * i4 + q] -= Lv[q] * xj; }
;     ...
;             PIN16(0); PIN16(16); PIN16(32); PIN16(48);
;         }
	v_fma_f32 v79, -v58, v129, v80
	v_fma_f32 v80, -v58, v128, v81
	v_fma_f32 v81, -v58, v127, v82
	v_fma_f32 v82, -v58, v126, v83
	v_fma_f32 v40, -v58, v125, v84
	v_fma_f32 v41, -v58, v124, v58
	v_fma_f32 v42, -v58, v123, v85
	v_fma_f32 v43, -v58, v122, v59
	ds_read_b128 v[102:105], v0 offset:10736
	s_waitcnt lgkmcnt(12)
	v_fma_f32 v83, -v40, v159, v60
	v_fma_f32 v84, -v40, v158, v61
	v_fma_f32 v27, -v40, v157, v27
	v_fma_f32 v62, -v40, v156, v62
	ds_read_b128 v[106:109], v0 offset:10720
	s_waitcnt lgkmcnt(12)
	v_fma_f32 v63, -v40, v163, v63
	v_fma_f32 v64, -v40, v162, v64
	v_fma_f32 v65, -v40, v161, v65
	ds_read_b128 v[110:113], v0 offset:10688
	ds_read_b128 v[114:117], v0 offset:10704
	ds_read_b128 v[118:121], v0 offset:10656
	s_waitcnt lgkmcnt(12)
	v_fma_f32 v79, -v40, v175, v79
	ds_read_b128 v[122:125], v0 offset:10672
	s_waitcnt lgkmcnt(12)
	v_fma_f32 v75, -v40, v179, v75
	v_fma_f32 v76, -v40, v178, v76
	v_fma_f32 v77, -v40, v177, v77
	v_fma_f32 v78, -v40, v176, v78
	v_fma_f32 v80, -v40, v174, v80
	v_fma_f32 v81, -v40, v173, v81
	v_fma_f32 v82, -v40, v172, v82
	v_fma_f32 v66, -v40, v160, v66
	v_fma_f32 v67, -v40, v171, v67
	v_fma_f32 v68, -v40, v170, v68
	v_fma_f32 v69, -v40, v169, v69
	v_fma_f32 v70, -v40, v168, v70
	v_fma_f32 v71, -v40, v167, v71
	v_fma_f32 v72, -v40, v166, v72
	v_fma_f32 v73, -v40, v165, v73
	v_fma_f32 v74, -v40, v164, v74
	ds_read_b128 v[126:129], v0 offset:10992
	s_waitcnt lgkmcnt(12)
	v_fma_f32 v83, -v82, v183, v83
	v_fma_f32 v84, -v82, v182, v84
	v_fma_f32 v27, -v82, v181, v27
	v_fma_f32 v62, -v82, v180, v62
	ds_read_b128 v[156:159], v0 offset:10976
	s_waitcnt lgkmcnt(12)
	v_fma_f32 v63, -v82, v187, v63
	v_fma_f32 v64, -v82, v186, v64
	v_fma_f32 v65, -v82, v185, v65
	v_fma_f32 v66, -v82, v184, v66
	ds_read_b128 v[160:163], v0 offset:10944
	ds_read_b128 v[164:167], v0 offset:10960
	s_waitcnt lgkmcnt(12)
	v_fma_f32 v67, -v82, v93, v67
	v_fma_f32 v68, -v82, v92, v68
	v_fma_f32 v69, -v82, v91, v69
	v_fma_f32 v70, -v82, v90, v70
	v_fma_f32 v71, -v82, v191, v71
	v_fma_f32 v72, -v82, v190, v72
	v_fma_f32 v73, -v82, v189, v73
	v_fma_f32 v74, -v82, v188, v74
	ds_read_b128 v[168:171], v0 offset:10912
	ds_read_b128 v[172:175], v0 offset:10928
	s_waitcnt lgkmcnt(12)
	v_fma_f32 v75, -v82, v101, v75
	v_fma_f32 v76, -v82, v100, v76
	v_fma_f32 v77, -v82, v99, v77
	v_fma_f32 v78, -v82, v98, v78
	v_fma_f32 v79, -v82, v97, v79
	v_fma_f32 v80, -v82, v96, v80
	v_fma_f32 v81, -v82, v95, v81
	v_fma_f32 v82, -v82, v94, v82
	ds_read_b128 v[176:179], v0 offset:11248
	s_waitcnt lgkmcnt(12)
	v_fma_f32 v83, -v81, v105, v83
	v_fma_f32 v84, -v81, v104, v84
	v_fma_f32 v27, -v81, v103, v27
	v_fma_f32 v62, -v81, v102, v62
	ds_read_b128 v[180:183], v0 offset:11216
	s_waitcnt lgkmcnt(12)
	v_fma_f32 v63, -v81, v109, v63
	v_fma_f32 v64, -v81, v108, v64
	v_fma_f32 v65, -v81, v107, v65
	v_fma_f32 v66, -v81, v106, v66
	ds_read_b128 v[184:187], v0 offset:11232
	ds_read_b128 v[188:191], v0 offset:11184
	s_waitcnt lgkmcnt(12)
	v_fma_f32 v67, -v81, v117, v67
	v_fma_f32 v68, -v81, v116, v68
	v_fma_f32 v69, -v81, v115, v69
	v_fma_f32 v70, -v81, v114, v70
	v_fma_f32 v71, -v81, v113, v71
	v_fma_f32 v72, -v81, v112, v72
	v_fma_f32 v73, -v81, v111, v73
	v_fma_f32 v74, -v81, v110, v74
	ds_read_b128 v[90:93], v0 offset:11200
	ds_read_b128 v[94:97], v0 offset:11504
	s_waitcnt lgkmcnt(12)
	v_fma_f32 v75, -v81, v125, v75
	v_fma_f32 v76, -v81, v124, v76
	v_fma_f32 v77, -v81, v123, v77
	v_fma_f32 v78, -v81, v122, v78
	v_fma_f32 v79, -v81, v121, v79
	v_fma_f32 v80, -v81, v120, v80
	v_fma_f32 v85, -v81, v119, v81
	v_fma_f32 v81, -v81, v118, v82
	ds_read_b128 v[98:101], v0 offset:11472
	s_waitcnt lgkmcnt(12)
	v_fma_f32 v82, -v80, v129, v83
	v_fma_f32 v83, -v80, v128, v84
	v_fma_f32 v27, -v80, v127, v27
	v_fma_f32 v62, -v80, v126, v62
	ds_read_b128 v[102:105], v0 offset:11488
	s_waitcnt lgkmcnt(12)
	v_fma_f32 v84, -v80, v159, v63
	v_fma_f32 v86, -v80, v158, v64
	ds_read_b128 v[106:109], v0 offset:11440
	s_waitcnt lgkmcnt(12)
	v_fma_f32 v71, -v80, v163, v71
	v_fma_f32 v72, -v80, v162, v72
	v_fma_f32 v73, -v80, v161, v73
	v_fma_f32 v74, -v80, v160, v74
	ds_read_b128 v[110:113], v0 offset:11456
	ds_read_b128 v[114:117], v0 offset:11760
	ds_read_b128 v[118:121], v0 offset:11728
	s_waitcnt lgkmcnt(12)
	v_fma_f32 v75, -v80, v175, v75
	v_fma_f32 v76, -v80, v174, v76
	v_fma_f32 v77, -v80, v173, v77
	v_fma_f32 v78, -v80, v172, v78
	v_fma_f32 v44, -v80, v171, v79
	v_fma_f32 v45, -v80, v170, v80
	v_fma_f32 v46, -v80, v169, v85
	v_fma_f32 v47, -v80, v168, v81
	v_fma_f32 v87, -v80, v157, v65
	v_fma_f32 v66, -v80, v156, v66
	v_fma_f32 v67, -v80, v167, v67
	v_fma_f32 v68, -v80, v166, v68
	v_fma_f32 v69, -v80, v165, v69
	v_fma_f32 v70, -v80, v164, v70
	ds_read_b128 v[122:125], v0 offset:11744
	s_waitcnt lgkmcnt(12)
	v_fma_f32 v79, -v44, v179, v82
	v_fma_f32 v80, -v44, v178, v83
	v_fma_f32 v81, -v44, v176, v62
	v_fma_f32 v27, -v44, v177, v27
	ds_read_b128 v[126:129], v0 offset:11696
	ds_read_b128 v[156:159], v0 offset:11712
	ds_read_b128 v[160:163], v0 offset:12016
	s_waitcnt lgkmcnt(12)
	v_fma_f32 v75, -v44, v191, v75
	v_fma_f32 v76, -v44, v190, v76
	v_fma_f32 v77, -v44, v189, v77
	v_fma_f32 v78, -v44, v188, v78
	v_fma_f32 v82, -v44, v187, v84
	v_fma_f32 v83, -v44, v186, v86
	v_fma_f32 v84, -v44, v185, v87
	v_fma_f32 v66, -v44, v184, v66
	v_fma_f32 v67, -v44, v183, v67
	v_fma_f32 v68, -v44, v182, v68
	v_fma_f32 v69, -v44, v181, v69
	v_fma_f32 v70, -v44, v180, v70
	ds_read_b128 v[164:167], v0 offset:11984
	s_waitcnt lgkmcnt(12)
	v_fma_f32 v71, -v44, v93, v71
	v_fma_f32 v72, -v44, v92, v72
	v_fma_f32 v73, -v44, v91, v73
	v_fma_f32 v74, -v44, v90, v74
	ds_read_b128 v[168:171], v0 offset:12000
	s_waitcnt lgkmcnt(12)
; #define LAS __attribute__((address_space(3)))
; #define PIN16(o) asm volatile("" : "+v"(xr[o]), "+v"(xr[o + 1]), "+v"(xr[o + 2]), "+v"(xr[o + 3]), "+v"(xr[o + 4]), "+v"(xr[o + 5]), "+v"(xr[o + 6]), "+v"(xr[o + 7]), "+v"(xr[o + 8]), "+v"(xr[o + 9]), "+v"(xr[o + 10]), "+v"(xr[o + 11]), "+v"(xr[o + 12]), "+v"(xr[o + 13]), "+v"(xr[o + 14]), "+v"(xr[o + 15]) :: "memory")
; DI void gdn_prep_item(LAS unsigned char* lds, const Ctx& c, int l, int item) {
;     ...
; #pragma unroll
;         for (int j = 0; j < 63; ++j) {
;             const float xj = xr[j];
; #pragma unroll
;             for (int i4 = (j + 1) / 4; i4 < 16; ++i4) { const f32x4 Lv = *(const LAS f32x4*)(Lb + j * 64 + 4 * i4);
; #pragma unroll
;                 for (int q = 0; q < 4; ++q) xr[4 * i4 + q] -= Lv[q] * xj; }
;     ...
;             PIN16(0); PIN16(16); PIN16(32); PIN16(48);
;         }
	v_fma_f32 v79, -v78, v97, v79
	v_fma_f32 v80, -v78, v96, v80
	v_fma_f32 v27, -v78, v95, v27
	v_fma_f32 v81, -v78, v94, v81
	ds_read_b128 v[172:175], v0 offset:11952
	ds_read_b128 v[176:179], v0 offset:11968
	s_waitcnt lgkmcnt(12)
	v_fma_f32 v82, -v78, v105, v82
	v_fma_f32 v83, -v78, v104, v83
	v_fma_f32 v84, -v78, v103, v84
	v_fma_f32 v66, -v78, v102, v66
	v_fma_f32 v67, -v78, v101, v67
	v_fma_f32 v68, -v78, v100, v68
	v_fma_f32 v69, -v78, v99, v69
	v_fma_f32 v70, -v78, v98, v70
	ds_read_b128 v[180:183], v0 offset:12272
	ds_read_b128 v[184:187], v0 offset:12256
	s_waitcnt lgkmcnt(12)
	v_fma_f32 v71, -v78, v113, v71
	v_fma_f32 v72, -v78, v112, v72
	v_fma_f32 v73, -v78, v111, v73
	v_fma_f32 v74, -v78, v110, v74
	v_fma_f32 v75, -v78, v109, v75
	v_fma_f32 v76, -v78, v108, v76
	v_fma_f32 v77, -v78, v107, v77
	v_fma_f32 v78, -v78, v106, v78
	ds_read_b128 v[188:191], v0 offset:12224
	s_waitcnt lgkmcnt(12)
	v_fma_f32 v79, -v77, v117, v79
	v_fma_f32 v80, -v77, v116, v80
	v_fma_f32 v27, -v77, v115, v27
	v_fma_f32 v81, -v77, v114, v81
	ds_read_b128 v[90:93], v0 offset:12240
	ds_read_b128 v[94:97], v0 offset:12528
	s_waitcnt lgkmcnt(12)
	v_fma_f32 v82, -v77, v125, v82
	v_fma_f32 v83, -v77, v124, v83
	v_fma_f32 v84, -v77, v123, v84
	v_fma_f32 v66, -v77, v122, v66
	v_fma_f32 v67, -v77, v121, v67
	v_fma_f32 v68, -v77, v120, v68
	v_fma_f32 v69, -v77, v119, v69
	v_fma_f32 v70, -v77, v118, v70
	ds_read_b128 v[98:101], v0 offset:12512
	ds_read_b128 v[102:105], v0 offset:12480
	s_waitcnt lgkmcnt(12)
	v_fma_f32 v71, -v77, v159, v71
	v_fma_f32 v72, -v77, v158, v72
	v_fma_f32 v73, -v77, v157, v73
	v_fma_f32 v74, -v77, v156, v74
	v_fma_f32 v75, -v77, v129, v75
	v_fma_f32 v76, -v77, v128, v76
	v_fma_f32 v85, -v77, v127, v77
	v_fma_f32 v77, -v77, v126, v78
	ds_read_b128 v[106:109], v0 offset:12496
	s_waitcnt lgkmcnt(12)
	v_fma_f32 v78, -v76, v163, v79
	v_fma_f32 v79, -v76, v162, v80
	v_fma_f32 v27, -v76, v161, v27
	v_fma_f32 v80, -v76, v160, v81
	ds_read_b128 v[110:113], v0 offset:12784
	s_waitcnt lgkmcnt(12)
	v_fma_f32 v69, -v76, v165, v69
	v_fma_f32 v70, -v76, v164, v70
	ds_read_b128 v[114:117], v0 offset:12768
	ds_read_b128 v[118:121], v0 offset:12736
	s_waitcnt lgkmcnt(12)
	v_fma_f32 v48, -v76, v175, v75
	v_fma_f32 v49, -v76, v174, v76
	v_fma_f32 v50, -v76, v173, v85
	v_fma_f32 v51, -v76, v172, v77
	v_fma_f32 v81, -v76, v171, v82
	v_fma_f32 v82, -v76, v170, v83
	v_fma_f32 v83, -v76, v169, v84
	v_fma_f32 v84, -v76, v168, v66
	v_fma_f32 v86, -v76, v167, v67
	v_fma_f32 v68, -v76, v166, v68
	ds_read_b128 v[122:125], v0 offset:12752
	s_waitcnt lgkmcnt(12)
	v_fma_f32 v71, -v76, v179, v71
	v_fma_f32 v72, -v76, v178, v72
	v_fma_f32 v73, -v76, v177, v73
	v_fma_f32 v74, -v76, v176, v74
	ds_read_b128 v[126:129], v0 offset:13040
	s_waitcnt lgkmcnt(12)
	v_fma_f32 v75, -v48, v183, v78
	v_fma_f32 v76, -v48, v182, v79
	v_fma_f32 v27, -v48, v181, v27
	v_fma_f32 v77, -v48, v180, v80
	ds_read_b128 v[156:159], v0 offset:13024
	s_waitcnt lgkmcnt(12)
	v_fma_f32 v78, -v48, v187, v81
	v_fma_f32 v79, -v48, v186, v82
	v_fma_f32 v80, -v48, v185, v83
	v_fma_f32 v81, -v48, v184, v84
	ds_read_b128 v[160:163], v0 offset:12992
	ds_read_b128 v[164:167], v0 offset:13008
	s_waitcnt lgkmcnt(12)
	v_fma_f32 v82, -v48, v93, v86
	v_fma_f32 v68, -v48, v92, v68
	v_fma_f32 v69, -v48, v91, v69
	v_fma_f32 v70, -v48, v90, v70
	v_fma_f32 v71, -v48, v191, v71
	v_fma_f32 v72, -v48, v190, v72
	v_fma_f32 v73, -v48, v189, v73
	v_fma_f32 v74, -v48, v188, v74
	ds_read_b128 v[168:171], v0 offset:13296
	s_waitcnt lgkmcnt(12)
	v_fma_f32 v75, -v74, v97, v75
	v_fma_f32 v76, -v74, v96, v76
	v_fma_f32 v27, -v74, v95, v27
	v_fma_f32 v77, -v74, v94, v77
	ds_read_b128 v[172:175], v0 offset:13264
	s_waitcnt lgkmcnt(12)
	v_fma_f32 v78, -v74, v101, v78
	v_fma_f32 v79, -v74, v100, v79
	v_fma_f32 v80, -v74, v99, v80
	v_fma_f32 v81, -v74, v98, v81
	ds_read_b128 v[176:179], v0 offset:13280
	ds_read_b128 v[180:183], v0 offset:13552
	s_waitcnt lgkmcnt(12)
	v_fma_f32 v82, -v74, v109, v82
	v_fma_f32 v68, -v74, v108, v68
	v_fma_f32 v69, -v74, v107, v69
	v_fma_f32 v70, -v74, v106, v70
	v_fma_f32 v71, -v74, v105, v71
	v_fma_f32 v72, -v74, v104, v72
	v_fma_f32 v73, -v74, v103, v73
	v_fma_f32 v74, -v74, v102, v74
	ds_read_b128 v[184:187], v0 offset:13520
	s_waitcnt lgkmcnt(12)
	v_fma_f32 v75, -v73, v113, v75
	v_fma_f32 v76, -v73, v112, v76
	v_fma_f32 v27, -v73, v111, v27
	v_fma_f32 v77, -v73, v110, v77
	ds_read_b128 v[188:191], v0 offset:13536
	s_waitcnt lgkmcnt(12)
	v_fma_f32 v78, -v73, v117, v78
	v_fma_f32 v79, -v73, v116, v79
	v_fma_f32 v80, -v73, v115, v80
	v_fma_f32 v81, -v73, v114, v81
	ds_read_b128 v[90:93], v0 offset:13808
	ds_read_b128 v[94:97], v0 offset:13776
	s_waitcnt lgkmcnt(12)
	v_fma_f32 v82, -v73, v125, v82
	v_fma_f32 v68, -v73, v124, v68
	v_fma_f32 v69, -v73, v123, v69
	v_fma_f32 v70, -v73, v122, v70
	v_fma_f32 v71, -v73, v121, v71
	v_fma_f32 v72, -v73, v120, v72
	v_fma_f32 v83, -v73, v119, v73
	v_fma_f32 v73, -v73, v118, v74
	ds_read_b128 v[98:101], v0 offset:13792
	s_waitcnt lgkmcnt(12)
	v_fma_f32 v74, -v72, v129, v75
	v_fma_f32 v75, -v72, v128, v76
	v_fma_f32 v27, -v72, v127, v27
	v_fma_f32 v76, -v72, v126, v77
	ds_read_b128 v[102:105], v0 offset:14064
	s_waitcnt lgkmcnt(12)
	v_fma_f32 v77, -v72, v159, v78
	v_fma_f32 v78, -v72, v158, v79
	v_fma_f32 v79, -v72, v157, v80
	v_fma_f32 v80, -v72, v156, v81
	ds_read_b128 v[106:109], v0 offset:14032
	ds_read_b128 v[110:113], v0 offset:14048
	s_waitcnt lgkmcnt(12)
	v_fma_f32 v81, -v72, v167, v82
	v_fma_f32 v68, -v72, v166, v68
	v_fma_f32 v69, -v72, v165, v69
	v_fma_f32 v70, -v72, v164, v70
	v_fma_f32 v52, -v72, v163, v71
	v_fma_f32 v53, -v72, v162, v72
	v_fma_f32 v54, -v72, v161, v83
	v_fma_f32 v55, -v72, v160, v73
	ds_read_b128 v[114:117], v0 offset:14320
	s_waitcnt lgkmcnt(12)
; #define LAS __attribute__((address_space(3)))
; #define PIN16(o) asm volatile("" : "+v"(xr[o]), "+v"(xr[o + 1]), "+v"(xr[o + 2]), "+v"(xr[o + 3]), "+v"(xr[o + 4]), "+v"(xr[o + 5]), "+v"(xr[o + 6]), "+v"(xr[o + 7]), "+v"(xr[o + 8]), "+v"(xr[o + 9]), "+v"(xr[o + 10]), "+v"(xr[o + 11]), "+v"(xr[o + 12]), "+v"(xr[o + 13]), "+v"(xr[o + 14]), "+v"(xr[o + 15]) :: "memory")
; DI void gdn_prep_item(LAS unsigned char* lds, const Ctx& c, int l, int item) {
;     ...
; #pragma unroll
;         for (int j = 0; j < 63; ++j) {
;             const float xj = xr[j];
; #pragma unroll
;             for (int i4 = (j + 1) / 4; i4 < 16; ++i4) { const f32x4 Lv = *(const LAS f32x4*)(Lb + j * 64 + 4 * i4);
; #pragma unroll
;                 for (int q = 0; q < 4; ++q) xr[4 * i4 + q] -= Lv[q] * xj; }
;     ...
;             PIN16(0); PIN16(16); PIN16(32); PIN16(48);
;         }
	v_fma_f32 v71, -v52, v171, v74
	v_fma_f32 v72, -v52, v170, v75
	v_fma_f32 v27, -v52, v169, v27
	v_fma_f32 v73, -v52, v168, v76
	ds_read_b128 v[118:121], v0 offset:14304
	ds_read_b128 v[122:125], v0 offset:14576
	s_waitcnt lgkmcnt(12)
	v_fma_f32 v74, -v52, v179, v77
	v_fma_f32 v75, -v52, v178, v78
	v_fma_f32 v76, -v52, v177, v79
	v_fma_f32 v77, -v52, v176, v80
	v_fma_f32 v78, -v52, v175, v81
	v_fma_f32 v68, -v52, v174, v68
	v_fma_f32 v69, -v52, v173, v69
	v_fma_f32 v70, -v52, v172, v70
	ds_read_b128 v[126:129], v0 offset:14560
	s_waitcnt lgkmcnt(12)
	v_fma_f32 v71, -v70, v183, v71
	v_fma_f32 v72, -v70, v182, v72
	v_fma_f32 v27, -v70, v181, v27
	v_fma_f32 v73, -v70, v180, v73
	ds_read_b128 v[156:159], v0 offset:14832
	ds_read_b128 v[160:163], v0 offset:14816
	s_waitcnt lgkmcnt(12)
	v_fma_f32 v74, -v70, v191, v74
	v_fma_f32 v75, -v70, v190, v75
	v_fma_f32 v76, -v70, v189, v76
	v_fma_f32 v77, -v70, v188, v77
	v_fma_f32 v78, -v70, v187, v78
	v_fma_f32 v68, -v70, v186, v68
	v_fma_f32 v69, -v70, v185, v69
	v_fma_f32 v70, -v70, v184, v70
	ds_read_b128 v[164:167], v0 offset:15088
	s_waitcnt lgkmcnt(12)
	v_fma_f32 v71, -v69, v93, v71
	v_fma_f32 v72, -v69, v92, v72
	v_fma_f32 v27, -v69, v91, v27
	v_fma_f32 v73, -v69, v90, v73
	ds_read_b128 v[168:171], v0 offset:15072
	ds_read_b128 v[172:175], v0 offset:15344
	s_waitcnt lgkmcnt(12)
	v_fma_f32 v74, -v69, v101, v74
	v_fma_f32 v75, -v69, v100, v75
	v_fma_f32 v76, -v69, v99, v76
	v_fma_f32 v77, -v69, v98, v77
	v_fma_f32 v78, -v69, v97, v78
	v_fma_f32 v68, -v69, v96, v68
	v_fma_f32 v79, -v69, v95, v69
	v_fma_f32 v69, -v69, v94, v70
	ds_read_b128 v[176:179], v0 offset:15600
	s_waitcnt lgkmcnt(12)
	v_fma_f32 v70, -v68, v105, v71
	v_fma_f32 v71, -v68, v104, v72
	v_fma_f32 v27, -v68, v103, v27
	v_fma_f32 v72, -v68, v102, v73
	ds_read_b128 v[180:183], v0 offset:15856
	ds_read_b128 v[184:187], v0 offset:16112
	s_waitcnt lgkmcnt(12)
	v_fma_f32 v73, -v68, v113, v74
	v_fma_f32 v74, -v68, v112, v75
	v_fma_f32 v75, -v68, v111, v76
	v_fma_f32 v76, -v68, v110, v77
	v_fma_f32 v56, -v68, v109, v78
	v_fma_f32 v57, -v68, v108, v68
	v_fma_f32 v58, -v68, v107, v79
	v_fma_f32 v59, -v68, v106, v69
	s_waitcnt lgkmcnt(11)
	v_fma_f32 v68, -v56, v117, v70
	v_fma_f32 v69, -v56, v116, v71
	v_fma_f32 v27, -v56, v115, v27
	v_fma_f32 v70, -v56, v114, v72
	s_waitcnt lgkmcnt(10)
	v_fma_f32 v71, -v56, v121, v73
	v_fma_f32 v72, -v56, v120, v74
	v_fma_f32 v73, -v56, v119, v75
	v_fma_f32 v74, -v56, v118, v76
	s_waitcnt lgkmcnt(9)
	v_fma_f32 v68, -v74, v125, v68
	v_fma_f32 v69, -v74, v124, v69
	v_fma_f32 v27, -v74, v123, v27
	v_fma_f32 v70, -v74, v122, v70
	s_waitcnt lgkmcnt(8)
	v_fma_f32 v71, -v74, v129, v71
	v_fma_f32 v72, -v74, v128, v72
	v_fma_f32 v73, -v74, v127, v73
	v_fma_f32 v74, -v74, v126, v74
	s_waitcnt lgkmcnt(7)
	v_fma_f32 v68, -v73, v159, v68
	v_fma_f32 v69, -v73, v158, v69
	v_fma_f32 v27, -v73, v157, v27
	v_fma_f32 v70, -v73, v156, v70
	s_waitcnt lgkmcnt(6)
	v_fma_f32 v71, -v73, v163, v71
	v_fma_f32 v72, -v73, v162, v72
	v_fma_f32 v75, -v73, v161, v73
	v_fma_f32 v73, -v73, v160, v74
	s_waitcnt lgkmcnt(5)
	v_fma_f32 v68, -v72, v167, v68
	v_fma_f32 v69, -v72, v166, v69
	v_fma_f32 v27, -v72, v165, v27
	v_fma_f32 v70, -v72, v164, v70
	s_waitcnt lgkmcnt(4)
	v_fma_f32 v60, -v72, v171, v71
	v_fma_f32 v61, -v72, v170, v72
	v_fma_f32 v62, -v72, v169, v75
	v_fma_f32 v63, -v72, v168, v73
	s_waitcnt lgkmcnt(3)
	v_fma_f32 v68, -v60, v175, v68
	v_fma_f32 v69, -v60, v174, v69
	v_fma_f32 v27, -v60, v173, v27
	v_fma_f32 v70, -v60, v172, v70
	s_waitcnt lgkmcnt(2)
	v_fma_f32 v68, -v70, v179, v68
	v_fma_f32 v69, -v70, v178, v69
	v_fma_f32 v27, -v70, v177, v27
	v_fma_f32 v70, -v70, v176, v70
	s_waitcnt lgkmcnt(1)
	v_fma_f32 v71, -v27, v183, v68
	v_fma_f32 v72, -v27, v182, v69
	v_fma_f32 v65, -v27, v181, v27
	v_fma_f32 v27, -v27, v180, v70
	s_waitcnt lgkmcnt(0)
	v_fma_f32 v0, -v72, v187, v71
	v_fma_f32 v64, -v72, v186, v72
	v_fma_f32 v65, -v72, v185, v65
	v_fma_f32 v66, -v72, v184, v27
	s_waitcnt lgkmcnt(0)
	s_and_saveexec_b64 s[8:9], vcc
	s_xor_b64 s[8:9], exec, s[8:9]
	s_cbranch_execz .LBB0_316
; DI unsigned pk2(float lo, float hi) { f32x2 v = {lo, hi}; bf16x2_t b = __builtin_convertvector(v, bf16x2_t); return __builtin_bit_cast(unsigned, b); }
; DI void gdn_prep_item(LAS unsigned char* lds, const Ctx& c, int l, int item) {
;     ...
;             bf16_t* Wg = (bf16_t*)(ws + WS_WC) + cidx * 8192 + (col - 128);
; #pragma unroll
;             for (int i = 0; i < 64; ++i) Wg[i * 128] = (bf16_t)(pk2(xr[i], 0.f) & 0xffffu);
	s_add_u32 s10, s0, s6
	s_addc_u32 s11, s1, s7
	v_mov_b32_e32 v27, v1
	v_lshl_add_u64 v[26:27], v[26:27], 1, s[10:11]
	v_add_co_u32_e32 v68, vcc, 0xe5ff000, v26
	v_cvt_pk_bf16_f32 v5, v5, s0
	s_nop 0
	v_addc_co_u32_e32 v69, vcc, 0, v27, vcc
	v_cvt_pk_bf16_f32 v67, v4, s0
	v_add_co_u32_e32 v4, vcc, 0xe600000, v26
	global_store_short v[68:69], v5, off offset:3840
	s_nop 0
	v_addc_co_u32_e32 v5, vcc, 0, v27, vcc
	v_cvt_pk_bf16_f32 v2, v2, s0
	global_store_short v[4:5], v2, off offset:512
	v_cvt_pk_bf16_f32 v2, v9, s0
	global_store_short v[4:5], v2, off offset:768
	v_cvt_pk_bf16_f32 v2, v8, s0
	global_store_short v[4:5], v2, off offset:1024
	v_cvt_pk_bf16_f32 v2, v7, s0
	global_store_short v[4:5], v2, off offset:1280
	v_cvt_pk_bf16_f32 v2, v6, s0
	global_store_short v[4:5], v2, off offset:1536
	v_cvt_pk_bf16_f32 v2, v13, s0
	global_store_short v[4:5], v2, off offset:1792
	v_cvt_pk_bf16_f32 v2, v12, s0
	global_store_short v[4:5], v2, off offset:2048
	v_cvt_pk_bf16_f32 v2, v11, s0
	global_store_short v[4:5], v2, off offset:2304
	v_cvt_pk_bf16_f32 v2, v10, s0
	global_store_short v[4:5], v2, off offset:2560
	v_cvt_pk_bf16_f32 v2, v17, s0
	global_store_short v[4:5], v2, off offset:2816
	v_cvt_pk_bf16_f32 v2, v16, s0
	global_store_short v[4:5], v2, off offset:3072
	v_cvt_pk_bf16_f32 v2, v15, s0
	global_store_short v[4:5], v2, off offset:3328
	v_cvt_pk_bf16_f32 v2, v14, s0
	global_store_short v[4:5], v2, off offset:3584
	v_cvt_pk_bf16_f32 v2, v21, s0
	s_mov_b32 s10, 0xe601000
	v_cvt_pk_bf16_f32 v3, v3, s0
	global_store_short v[4:5], v2, off offset:3840
	v_add_co_u32_e32 v2, vcc, s10, v26
	global_store_short v[4:5], v3, off offset:256
	s_nop 0
	v_addc_co_u32_e32 v3, vcc, 0, v27, vcc
	s_mov_b32 s10, 0xe602000
	global_store_short v[4:5], v67, off
	v_add_co_u32_e32 v4, vcc, s10, v26
	v_cvt_pk_bf16_f32 v6, v20, s0
	s_nop 0
	v_addc_co_u32_e32 v5, vcc, 0, v27, vcc
	global_store_short v[4:5], v6, off offset:-4096
	v_cvt_pk_bf16_f32 v6, v19, s0
	global_store_short v[2:3], v6, off offset:256
	v_cvt_pk_bf16_f32 v6, v18, s0
	global_store_short v[2:3], v6, off offset:512
	v_cvt_pk_bf16_f32 v6, v25, s0
	global_store_short v[2:3], v6, off offset:768
	v_cvt_pk_bf16_f32 v6, v24, s0
	global_store_short v[2:3], v6, off offset:1024
	v_cvt_pk_bf16_f32 v6, v23, s0
	global_store_short v[2:3], v6, off offset:1280
	v_cvt_pk_bf16_f32 v6, v22, s0
	global_store_short v[2:3], v6, off offset:1536
	v_cvt_pk_bf16_f32 v6, v31, s0
	global_store_short v[2:3], v6, off offset:1792
	v_cvt_pk_bf16_f32 v6, v30, s0
	global_store_short v[2:3], v6, off offset:2048
	v_cvt_pk_bf16_f32 v6, v29, s0
	global_store_short v[2:3], v6, off offset:2304
	v_cvt_pk_bf16_f32 v6, v28, s0
	global_store_short v[2:3], v6, off offset:2560
	v_cvt_pk_bf16_f32 v6, v35, s0
	global_store_short v[2:3], v6, off offset:2816
	v_cvt_pk_bf16_f32 v6, v34, s0
	global_store_short v[2:3], v6, off offset:3072
	v_cvt_pk_bf16_f32 v6, v33, s0
	global_store_short v[2:3], v6, off offset:3328
	v_cvt_pk_bf16_f32 v6, v32, s0
	global_store_short v[2:3], v6, off offset:3584
	v_cvt_pk_bf16_f32 v6, v39, s0
	global_store_short v[2:3], v6, off offset:3840
	v_cvt_pk_bf16_f32 v2, v38, s0
	global_store_short v[4:5], v2, off
	v_cvt_pk_bf16_f32 v2, v37, s0
	global_store_short v[4:5], v2, off offset:256
	v_cvt_pk_bf16_f32 v2, v36, s0
	global_store_short v[4:5], v2, off offset:512
	v_cvt_pk_bf16_f32 v2, v43, s0
	global_store_short v[4:5], v2, off offset:768
	v_cvt_pk_bf16_f32 v2, v42, s0
	global_store_short v[4:5], v2, off offset:1024
	v_cvt_pk_bf16_f32 v2, v41, s0
	global_store_short v[4:5], v2, off offset:1280
	v_cvt_pk_bf16_f32 v2, v40, s0
	global_store_short v[4:5], v2, off offset:1536
	v_cvt_pk_bf16_f32 v2, v47, s0
	global_store_short v[4:5], v2, off offset:1792
	v_cvt_pk_bf16_f32 v2, v46, s0
	global_store_short v[4:5], v2, off offset:2048
	v_cvt_pk_bf16_f32 v2, v45, s0
	global_store_short v[4:5], v2, off offset:2304
	v_cvt_pk_bf16_f32 v2, v44, s0
	global_store_short v[4:5], v2, off offset:2560
	v_cvt_pk_bf16_f32 v2, v51, s0
	global_store_short v[4:5], v2, off offset:2816
	v_cvt_pk_bf16_f32 v2, v50, s0
	global_store_short v[4:5], v2, off offset:3072
	v_cvt_pk_bf16_f32 v2, v49, s0
	global_store_short v[4:5], v2, off offset:3328
	v_cvt_pk_bf16_f32 v2, v48, s0
	global_store_short v[4:5], v2, off offset:3584
	v_cvt_pk_bf16_f32 v2, v55, s0
	s_mov_b32 s10, 0xe603000
	global_store_short v[4:5], v2, off offset:3840
	v_add_co_u32_e32 v2, vcc, s10, v26
	v_cvt_pk_bf16_f32 v4, v54, s0
	s_nop 0
	v_addc_co_u32_e32 v3, vcc, 0, v27, vcc
	global_store_short v[2:3], v4, off
	v_cvt_pk_bf16_f32 v4, v53, s0
	global_store_short v[2:3], v4, off offset:256
	v_cvt_pk_bf16_f32 v4, v52, s0
	global_store_short v[2:3], v4, off offset:512
	v_cvt_pk_bf16_f32 v4, v59, s0
	global_store_short v[2:3], v4, off offset:768
	v_cvt_pk_bf16_f32 v4, v58, s0
	global_store_short v[2:3], v4, off offset:1024
	v_cvt_pk_bf16_f32 v4, v57, s0
	global_store_short v[2:3], v4, off offset:1280
	v_cvt_pk_bf16_f32 v4, v56, s0
	global_store_short v[2:3], v4, off offset:1536
	v_cvt_pk_bf16_f32 v4, v63, s0
	global_store_short v[2:3], v4, off offset:1792
	v_cvt_pk_bf16_f32 v4, v62, s0
	global_store_short v[2:3], v4, off offset:2048
	v_cvt_pk_bf16_f32 v4, v61, s0
	global_store_short v[2:3], v4, off offset:2304
	v_cvt_pk_bf16_f32 v4, v60, s0
	global_store_short v[2:3], v4, off offset:2560
	v_cvt_pk_bf16_f32 v4, v66, s0
	global_store_short v[2:3], v4, off offset:2816
	v_cvt_pk_bf16_f32 v4, v65, s0
	global_store_short v[2:3], v4, off offset:3072
	v_cvt_pk_bf16_f32 v4, v64, s0
	v_cvt_pk_bf16_f32 v0, v0, s0
	global_store_short v[2:3], v4, off offset:3328
	global_store_short v[2:3], v0, off offset:3584
